# v045 plus removal of 32 provably redundant s_waitcnt lgkmcnt(0) after the barrier in the GEMM K-loops
# baseline (speedup 1.0000x reference)
; #define PG8_STAGE(bufoff, gbase, voff) do { _Pragma("unroll") for (int _i = 0; _i < 2; ++_i) \
;         __builtin_amdgcn_global_load_lds((const unsigned*)((const char*)(gbase) + (voff)[_i]), (PG8_LAS unsigned*)(lds + (bufoff) + ldsw + _i * 8192), 16, 0, 0); } while (0)
; #define PG8_LDA(dst, b, h) do { _Pragma("unroll") for (int m = 0; m < 4; ++m) _Pragma("unroll") for (int k = 0; k < 2; ++k) dst[m][k] = *(const PG8_LAS bf16x8*)(lds + PG8_SA(b, h) + aoff + m * 2048 + k * 1024); } while (0)
; #define PG8_LDB(dst, b, h) do { _Pragma("unroll") for (int n = 0; n < 2; ++n) _Pragma("unroll") for (int k = 0; k < 2; ++k) dst[n][k] = *(const PG8_LAS bf16x8*)(lds + PG8_SB(b, h) + boff + n * 2048 + k * 1024); } while (0)
; #define PG8_MMA(ai, bj, At, Bt) do { __builtin_amdgcn_s_setprio(1); _Pragma("unroll") for (int m = 0; m < 4; ++m) _Pragma("unroll") for (int n = 0; n < 2; ++n) _Pragma("unroll") for (int k = 0; k < 2; ++k) \
;         acc[ai][bj][m][n] = __builtin_amdgcn_mfma_f32_16x16x32_bf16(Bt[n][k], At[m][k], acc[ai][bj][m][n], 0, 0, 0); __builtin_amdgcn_s_setprio(0); } while (0)
; #define PG8_WAIT_V(n) asm volatile("s_waitcnt vmcnt(" #n ")" ::: "memory")
; template <class Epi, class Sched, bool ALIGN_EPI = false, bool SP2 = false>
; __device__ __forceinline__ void gemm_phase(PG8_LAS unsigned char* lds, const Gemm g, const Sched& S, const Epi& E) {
;     ...
;             PG8_LDB(B0, 0, 0); PG8_LDB(B1, 0, 1); PG8_SCHED; PG8_LDA(At, 0, 0); PG8_STAGE(PG8_SA(1, 1), a1 + hstep, voffA);
;             PG8_WAIT_V(8); PG8_WAIT_L(0); PG8_BAR; PG8_MMA(0, 0, At, B0); PG8_MMA(0, 1, At, B1); PG8_BAR; PG8_SCHED;
;             PG8_LDA(At, 0, 1); PG8_STAGE(PG8_SB(0, 0), b2, voffB); PG8_STAGE(PG8_SB(0, 1), b2 + hstep, voffB); PG8_STAGE(PG8_SA(0, 0), a2, voffA);
;             PG8_WAIT_V(8); PG8_WAIT_L(0); PG8_BAR; PG8_MMA(1, 0, At, B0); PG8_MMA(1, 1, At, B1); PG8_BAR; PG8_SCHED;
;             PG8_LDB(B0, 1, 0); PG8_LDB(B1, 1, 1); PG8_SCHED; PG8_LDA(At, 1, 0); PG8_STAGE(PG8_SA(0, 1), a2 + hstep, voffA);
;             PG8_WAIT_V(8); PG8_WAIT_L(0); PG8_BAR; PG8_MMA(0, 0, At, B0); PG8_MMA(0, 1, At, B1); PG8_BAR; PG8_SCHED;
;             PG8_LDA(At, 1, 1); PG8_STAGE(PG8_SB(1, 0), b3, voffB); PG8_STAGE(PG8_SB(1, 1), b3 + hstep, voffB); PG8_STAGE(PG8_SA(1, 0), a3, voffA);
;             PG8_WAIT_V(8); PG8_WAIT_L(0); PG8_BAR; PG8_MMA(1, 0, At, B0); PG8_MMA(1, 1, At, B1); PG8_BAR; PG8_SCHED;
.LBB0_359:
	ds_read_b128 v[152:155], v165
	ds_read_b128 v[156:159], v165 offset:1024
	ds_read_b128 v[170:173], v165 offset:2048
	ds_read_b128 v[174:177], v165 offset:3072
	ds_read_b128 v[178:181], v166
	ds_read_b128 v[182:185], v166 offset:1024
	ds_read_b128 v[186:189], v166 offset:2048
	ds_read_b128 v[190:193], v166 offset:3072
	s_add_u32 s28, s26, 0xfffc0080
	s_addc_u32 s29, s27, -1
	s_cmp_eq_u32 s56, 12
	s_cselect_b32 s31, s2, s29
	s_cselect_b32 s30, s7, s28
	s_cselect_b32 s29, s15, s33
	s_cselect_b32 s28, s17, s23
	v_lshl_add_u64 v[198:199], s[26:27], 0, v[142:143]
	s_add_i32 m0, s37, 0xc000
	ds_read_b128 v[194:197], v167
	ds_read_b128 v[204:207], v167 offset:1024
	ds_read_b128 v[208:211], v167 offset:2048
	ds_read_b128 v[214:217], v167 offset:3072
	ds_read_b128 v[218:221], v167 offset:4096
	ds_read_b128 v[222:225], v167 offset:5120
	ds_read_b128 v[226:229], v167 offset:6144
	ds_read_b128 v[230:233], v167 offset:7168
	global_load_lds_dwordx4 v[198:199], off
	v_lshl_add_u64 v[198:199], s[26:27], 0, v[146:147]
	s_add_i32 m0, s37, 0xe000
	s_nop 0
	global_load_lds_dwordx4 v[198:199], off
	s_waitcnt vmcnt(8)
	s_waitcnt lgkmcnt(0)
	s_barrier
	s_setprio 1
	v_mfma_f32_16x16x32_bf16 v[124:127], v[152:155], v[194:197], v[124:127]
	v_mfma_f32_16x16x32_bf16 v[116:119], v[170:173], v[194:197], v[116:119]
	v_mfma_f32_16x16x32_bf16 v[108:111], v[152:155], v[208:211], v[108:111]
	v_mfma_f32_16x16x32_bf16 v[100:103], v[170:173], v[208:211], v[100:103]
	v_mfma_f32_16x16x32_bf16 v[92:95], v[152:155], v[218:221], v[92:95]
	v_mfma_f32_16x16x32_bf16 v[84:87], v[170:173], v[218:221], v[84:87]
	v_mfma_f32_16x16x32_bf16 v[76:79], v[152:155], v[226:229], v[76:79]
	v_mfma_f32_16x16x32_bf16 v[68:71], v[170:173], v[226:229], v[68:71]
	v_mfma_f32_16x16x32_bf16 v[124:127], v[156:159], v[204:207], v[124:127]
	v_mfma_f32_16x16x32_bf16 v[116:119], v[174:177], v[204:207], v[116:119]
	v_mfma_f32_16x16x32_bf16 v[108:111], v[156:159], v[214:217], v[108:111]
	v_mfma_f32_16x16x32_bf16 v[100:103], v[174:177], v[214:217], v[100:103]
	v_mfma_f32_16x16x32_bf16 v[92:95], v[156:159], v[222:225], v[92:95]
	v_mfma_f32_16x16x32_bf16 v[84:87], v[174:177], v[222:225], v[84:87]
	v_mfma_f32_16x16x32_bf16 v[76:79], v[156:159], v[230:233], v[76:79]
	v_mfma_f32_16x16x32_bf16 v[68:71], v[174:177], v[230:233], v[68:71]
	s_setprio 0
	s_setprio 1
	v_mfma_f32_16x16x32_bf16 v[120:123], v[178:181], v[194:197], v[120:123]
	v_mfma_f32_16x16x32_bf16 v[112:115], v[186:189], v[194:197], v[112:115]
	v_mfma_f32_16x16x32_bf16 v[104:107], v[178:181], v[208:211], v[104:107]
	v_mfma_f32_16x16x32_bf16 v[96:99], v[186:189], v[208:211], v[96:99]
	v_mfma_f32_16x16x32_bf16 v[88:91], v[178:181], v[218:221], v[88:91]
	v_mfma_f32_16x16x32_bf16 v[80:83], v[186:189], v[218:221], v[80:83]
	v_mfma_f32_16x16x32_bf16 v[72:75], v[178:181], v[226:229], v[72:75]
	v_mfma_f32_16x16x32_bf16 v[64:67], v[186:189], v[226:229], v[64:67]
	v_mfma_f32_16x16x32_bf16 v[120:123], v[182:185], v[204:207], v[120:123]
	v_mfma_f32_16x16x32_bf16 v[112:115], v[190:193], v[204:207], v[112:115]
	v_mfma_f32_16x16x32_bf16 v[104:107], v[182:185], v[214:217], v[104:107]
	v_mfma_f32_16x16x32_bf16 v[96:99], v[190:193], v[214:217], v[96:99]
	v_mfma_f32_16x16x32_bf16 v[88:91], v[182:185], v[222:225], v[88:91]
	v_mfma_f32_16x16x32_bf16 v[80:83], v[190:193], v[222:225], v[80:83]
	v_mfma_f32_16x16x32_bf16 v[72:75], v[182:185], v[230:233], v[72:75]
	v_mfma_f32_16x16x32_bf16 v[64:67], v[190:193], v[230:233], v[64:67]
	s_setprio 0
	s_barrier
	s_add_i32 s57, s47, s36
	v_lshl_add_u64 v[198:199], s[28:29], 0, v[132:133]
	s_mov_b32 m0, s57
	ds_read_b128 v[194:197], v167 offset:16384
	ds_read_b128 v[204:207], v167 offset:17408
	ds_read_b128 v[208:211], v167 offset:18432
	ds_read_b128 v[214:217], v167 offset:19456
	ds_read_b128 v[218:221], v167 offset:20480
	ds_read_b128 v[222:225], v167 offset:21504
	ds_read_b128 v[226:229], v167 offset:22528
	ds_read_b128 v[230:233], v167 offset:23552
	global_load_lds_dwordx4 v[198:199], off
	s_add_i32 m0, s57, 0x2000
	s_add_u32 s58, s28, 0x40000
	v_lshl_add_u64 v[234:235], s[28:29], 0, v[136:137]
	s_addc_u32 s59, s29, 0
	s_add_i32 s57, s49, s36
	global_load_lds_dwordx4 v[234:235], off
	v_lshl_add_u64 v[236:237], s[58:59], 0, v[132:133]
	s_mov_b32 m0, s57
	v_lshl_add_u64 v[238:239], s[30:31], 0, v[134:135]
	global_load_lds_dwordx4 v[236:237], off
	v_lshl_add_u64 v[236:237], s[58:59], 0, v[136:137]
	s_add_i32 m0, s57, 0x2000
	s_nop 0
	global_load_lds_dwordx4 v[236:237], off
	v_lshl_add_u64 v[236:237], s[30:31], 0, v[130:131]
	s_mov_b32 m0, s37
	s_nop 0
	global_load_lds_dwordx4 v[236:237], off
	s_mov_b32 m0, s38
	s_nop 0
	global_load_lds_dwordx4 v[238:239], off
	s_waitcnt vmcnt(8)
	s_waitcnt lgkmcnt(0)
	s_barrier
; #define PG8_STAGE(bufoff, gbase, voff) do { _Pragma("unroll") for (int _i = 0; _i < 2; ++_i) \
;         __builtin_amdgcn_global_load_lds((const unsigned*)((const char*)(gbase) + (voff)[_i]), (PG8_LAS unsigned*)(lds + (bufoff) + ldsw + _i * 8192), 16, 0, 0); } while (0)
; #define PG8_LDA(dst, b, h) do { _Pragma("unroll") for (int m = 0; m < 4; ++m) _Pragma("unroll") for (int k = 0; k < 2; ++k) dst[m][k] = *(const PG8_LAS bf16x8*)(lds + PG8_SA(b, h) + aoff + m * 2048 + k * 1024); } while (0)
; #define PG8_LDB(dst, b, h) do { _Pragma("unroll") for (int n = 0; n < 2; ++n) _Pragma("unroll") for (int k = 0; k < 2; ++k) dst[n][k] = *(const PG8_LAS bf16x8*)(lds + PG8_SB(b, h) + boff + n * 2048 + k * 1024); } while (0)
; #define PG8_MMA(ai, bj, At, Bt) do { __builtin_amdgcn_s_setprio(1); _Pragma("unroll") for (int m = 0; m < 4; ++m) _Pragma("unroll") for (int n = 0; n < 2; ++n) _Pragma("unroll") for (int k = 0; k < 2; ++k) \
;         acc[ai][bj][m][n] = __builtin_amdgcn_mfma_f32_16x16x32_bf16(Bt[n][k], At[m][k], acc[ai][bj][m][n], 0, 0, 0); __builtin_amdgcn_s_setprio(0); } while (0)
; #define PG8_WAIT_V(n) asm volatile("s_waitcnt vmcnt(" #n ")" ::: "memory")
; #define PG8_WAIT_L(n) asm volatile("s_waitcnt lgkmcnt(" #n ")" ::: "memory")
; #define PG8_BAR __builtin_amdgcn_s_barrier()
; #define PG8_SCHED __builtin_amdgcn_sched_barrier(0)
; template <class Epi, class Sched, bool ALIGN_EPI = false, bool SP2 = false>
; __device__ __forceinline__ void gemm_phase(PG8_LAS unsigned char* lds, const Gemm g, const Sched& S, const Epi& E) {
;     ...
;             PG8_WAIT_V(8); PG8_WAIT_L(0); PG8_BAR; PG8_MMA(0, 0, At, B0); PG8_MMA(0, 1, At, B1); PG8_BAR; PG8_SCHED;
;             PG8_LDA(At, 0, 1); PG8_STAGE(PG8_SB(0, 0), b2, voffB); PG8_STAGE(PG8_SB(0, 1), b2 + hstep, voffB); PG8_STAGE(PG8_SA(0, 0), a2, voffA);
;             PG8_WAIT_V(8); PG8_WAIT_L(0); PG8_BAR; PG8_MMA(1, 0, At, B0); PG8_MMA(1, 1, At, B1); PG8_BAR; PG8_SCHED;
;             PG8_LDB(B0, 1, 0); PG8_LDB(B1, 1, 1); PG8_SCHED; PG8_LDA(At, 1, 0); PG8_STAGE(PG8_SA(0, 1), a2 + hstep, voffA);
;             PG8_WAIT_V(8); PG8_WAIT_L(0); PG8_BAR; PG8_MMA(0, 0, At, B0); PG8_MMA(0, 1, At, B1); PG8_BAR; PG8_SCHED;
	s_setprio 1
	v_mfma_f32_16x16x32_bf16 v[60:63], v[152:155], v[194:197], v[60:63]
	v_mfma_f32_16x16x32_bf16 v[52:55], v[170:173], v[194:197], v[52:55]
	v_mfma_f32_16x16x32_bf16 v[44:47], v[152:155], v[208:211], v[44:47]
	v_mfma_f32_16x16x32_bf16 v[36:39], v[170:173], v[208:211], v[36:39]
	v_mfma_f32_16x16x32_bf16 v[28:31], v[152:155], v[218:221], v[28:31]
	v_mfma_f32_16x16x32_bf16 v[20:23], v[170:173], v[218:221], v[20:23]
	v_mfma_f32_16x16x32_bf16 v[12:15], v[152:155], v[226:229], v[12:15]
	v_mfma_f32_16x16x32_bf16 v[4:7], v[170:173], v[226:229], v[4:7]
	v_mfma_f32_16x16x32_bf16 v[60:63], v[156:159], v[204:207], v[60:63]
	v_mfma_f32_16x16x32_bf16 v[52:55], v[174:177], v[204:207], v[52:55]
	v_mfma_f32_16x16x32_bf16 v[44:47], v[156:159], v[214:217], v[44:47]
	v_mfma_f32_16x16x32_bf16 v[36:39], v[174:177], v[214:217], v[36:39]
	v_mfma_f32_16x16x32_bf16 v[28:31], v[156:159], v[222:225], v[28:31]
	v_mfma_f32_16x16x32_bf16 v[20:23], v[174:177], v[222:225], v[20:23]
	v_mfma_f32_16x16x32_bf16 v[12:15], v[156:159], v[230:233], v[12:15]
	v_mfma_f32_16x16x32_bf16 v[4:7], v[174:177], v[230:233], v[4:7]
	s_setprio 0
	s_setprio 1
	v_mfma_f32_16x16x32_bf16 v[56:59], v[178:181], v[194:197], v[56:59]
	v_mfma_f32_16x16x32_bf16 v[48:51], v[186:189], v[194:197], v[48:51]
	v_mfma_f32_16x16x32_bf16 v[40:43], v[178:181], v[208:211], v[40:43]
	v_mfma_f32_16x16x32_bf16 v[32:35], v[186:189], v[208:211], v[32:35]
	v_mfma_f32_16x16x32_bf16 v[24:27], v[178:181], v[218:221], v[24:27]
	v_mfma_f32_16x16x32_bf16 v[16:19], v[186:189], v[218:221], v[16:19]
	v_mfma_f32_16x16x32_bf16 v[8:11], v[178:181], v[226:229], v[8:11]
	v_mfma_f32_16x16x32_bf16 v[0:3], v[186:189], v[226:229], v[0:3]
	v_mfma_f32_16x16x32_bf16 v[56:59], v[182:185], v[204:207], v[56:59]
	v_mfma_f32_16x16x32_bf16 v[48:51], v[190:193], v[204:207], v[48:51]
	v_mfma_f32_16x16x32_bf16 v[40:43], v[182:185], v[214:217], v[40:43]
	v_mfma_f32_16x16x32_bf16 v[32:35], v[190:193], v[214:217], v[32:35]
	v_mfma_f32_16x16x32_bf16 v[24:27], v[182:185], v[222:225], v[24:27]
	v_mfma_f32_16x16x32_bf16 v[16:19], v[190:193], v[222:225], v[16:19]
	v_mfma_f32_16x16x32_bf16 v[8:11], v[182:185], v[230:233], v[8:11]
	v_mfma_f32_16x16x32_bf16 v[0:3], v[190:193], v[230:233], v[0:3]
	s_setprio 0
	s_barrier
	s_add_i32 s57, 0, 0x18000
	v_add_u32_e32 v160, s57, v161
	s_add_i32 s58, 0, 0x1c000
	ds_read_b128 v[152:155], v160
	ds_read_b128 v[156:159], v160 offset:1024
	ds_read_b128 v[170:173], v160 offset:2048
	ds_read_b128 v[174:177], v160 offset:3072
	v_add_u32_e32 v160, s58, v161
	ds_read_b128 v[178:181], v160
	ds_read_b128 v[182:185], v160 offset:1024
	ds_read_b128 v[186:189], v160 offset:2048
	ds_read_b128 v[190:193], v160 offset:3072
	s_add_u32 s30, s30, 0x40000
	s_addc_u32 s31, s31, 0
	s_mov_b32 m0, s39
	v_lshl_add_u64 v[240:241], s[30:31], 0, v[130:131]
	ds_read_b128 v[194:197], v167 offset:32768
	ds_read_b128 v[204:207], v167 offset:33792
	ds_read_b128 v[208:211], v167 offset:34816
	ds_read_b128 v[214:217], v167 offset:35840
	ds_read_b128 v[218:221], v167 offset:36864
	ds_read_b128 v[222:225], v167 offset:37888
	ds_read_b128 v[226:229], v167 offset:38912
	ds_read_b128 v[230:233], v167 offset:39936
	global_load_lds_dwordx4 v[240:241], off
	v_lshl_add_u64 v[240:241], s[30:31], 0, v[134:135]
	s_mov_b32 m0, s40
	s_nop 0
	global_load_lds_dwordx4 v[240:241], off
	s_waitcnt vmcnt(8)
	s_waitcnt lgkmcnt(0)
	s_barrier
	s_setprio 1
	v_mfma_f32_16x16x32_bf16 v[124:127], v[152:155], v[194:197], v[124:127]
	v_mfma_f32_16x16x32_bf16 v[116:119], v[170:173], v[194:197], v[116:119]
	v_mfma_f32_16x16x32_bf16 v[108:111], v[152:155], v[208:211], v[108:111]
	v_mfma_f32_16x16x32_bf16 v[100:103], v[170:173], v[208:211], v[100:103]
	v_mfma_f32_16x16x32_bf16 v[92:95], v[152:155], v[218:221], v[92:95]
	v_mfma_f32_16x16x32_bf16 v[84:87], v[170:173], v[218:221], v[84:87]
	v_mfma_f32_16x16x32_bf16 v[76:79], v[152:155], v[226:229], v[76:79]
	v_mfma_f32_16x16x32_bf16 v[68:71], v[170:173], v[226:229], v[68:71]
	v_mfma_f32_16x16x32_bf16 v[124:127], v[156:159], v[204:207], v[124:127]
	v_mfma_f32_16x16x32_bf16 v[116:119], v[174:177], v[204:207], v[116:119]
	v_mfma_f32_16x16x32_bf16 v[108:111], v[156:159], v[214:217], v[108:111]
	v_mfma_f32_16x16x32_bf16 v[100:103], v[174:177], v[214:217], v[100:103]
	v_mfma_f32_16x16x32_bf16 v[92:95], v[156:159], v[222:225], v[92:95]
	v_mfma_f32_16x16x32_bf16 v[84:87], v[174:177], v[222:225], v[84:87]
	v_mfma_f32_16x16x32_bf16 v[76:79], v[156:159], v[230:233], v[76:79]
	v_mfma_f32_16x16x32_bf16 v[68:71], v[174:177], v[230:233], v[68:71]
	s_setprio 0
	s_setprio 1
	v_mfma_f32_16x16x32_bf16 v[120:123], v[178:181], v[194:197], v[120:123]
	v_mfma_f32_16x16x32_bf16 v[112:115], v[186:189], v[194:197], v[112:115]
	v_mfma_f32_16x16x32_bf16 v[104:107], v[178:181], v[208:211], v[104:107]
	v_mfma_f32_16x16x32_bf16 v[96:99], v[186:189], v[208:211], v[96:99]
	v_mfma_f32_16x16x32_bf16 v[88:91], v[178:181], v[218:221], v[88:91]
	v_mfma_f32_16x16x32_bf16 v[80:83], v[186:189], v[218:221], v[80:83]
	v_mfma_f32_16x16x32_bf16 v[72:75], v[178:181], v[226:229], v[72:75]
	v_mfma_f32_16x16x32_bf16 v[64:67], v[186:189], v[226:229], v[64:67]
	v_mfma_f32_16x16x32_bf16 v[120:123], v[182:185], v[204:207], v[120:123]
	v_mfma_f32_16x16x32_bf16 v[112:115], v[190:193], v[204:207], v[112:115]
	v_mfma_f32_16x16x32_bf16 v[104:107], v[182:185], v[214:217], v[104:107]
	v_mfma_f32_16x16x32_bf16 v[96:99], v[190:193], v[214:217], v[96:99]
	v_mfma_f32_16x16x32_bf16 v[88:91], v[182:185], v[222:225], v[88:91]
	v_mfma_f32_16x16x32_bf16 v[80:83], v[190:193], v[222:225], v[80:83]
	v_mfma_f32_16x16x32_bf16 v[72:75], v[182:185], v[230:233], v[72:75]
	v_mfma_f32_16x16x32_bf16 v[64:67], v[190:193], v[230:233], v[64:67]
	s_setprio 0
	s_barrier
; #define PG8_STAGE(bufoff, gbase, voff) do { _Pragma("unroll") for (int _i = 0; _i < 2; ++_i) \
;         __builtin_amdgcn_global_load_lds((const unsigned*)((const char*)(gbase) + (voff)[_i]), (PG8_LAS unsigned*)(lds + (bufoff) + ldsw + _i * 8192), 16, 0, 0); } while (0)
; #define PG8_LDA(dst, b, h) do { _Pragma("unroll") for (int m = 0; m < 4; ++m) _Pragma("unroll") for (int k = 0; k < 2; ++k) dst[m][k] = *(const PG8_LAS bf16x8*)(lds + PG8_SA(b, h) + aoff + m * 2048 + k * 1024); } while (0)
; #define PG8_MMA(ai, bj, At, Bt) do { __builtin_amdgcn_s_setprio(1); _Pragma("unroll") for (int m = 0; m < 4; ++m) _Pragma("unroll") for (int n = 0; n < 2; ++n) _Pragma("unroll") for (int k = 0; k < 2; ++k) \
;         acc[ai][bj][m][n] = __builtin_amdgcn_mfma_f32_16x16x32_bf16(Bt[n][k], At[m][k], acc[ai][bj][m][n], 0, 0, 0); __builtin_amdgcn_s_setprio(0); } while (0)
; #define PG8_WAIT_V(n) asm volatile("s_waitcnt vmcnt(" #n ")" ::: "memory")
; #define PG8_WAIT_L(n) asm volatile("s_waitcnt lgkmcnt(" #n ")" ::: "memory")
; #define PG8_BAR __builtin_amdgcn_s_barrier()
; #define PG8_SCHED __builtin_amdgcn_sched_barrier(0)
; template <class Epi, class Sched, bool ALIGN_EPI = false, bool SP2 = false>
; __device__ __forceinline__ void gemm_phase(PG8_LAS unsigned char* lds, const Gemm g, const Sched& S, const Epi& E) {
;     ...
;             PG8_WAIT_V(8); PG8_WAIT_L(0); PG8_BAR; PG8_MMA(0, 0, At, B0); PG8_MMA(0, 1, At, B1); PG8_BAR; PG8_SCHED;
;             PG8_LDA(At, 1, 1); PG8_STAGE(PG8_SB(1, 0), b3, voffB); PG8_STAGE(PG8_SB(1, 1), b3 + hstep, voffB); PG8_STAGE(PG8_SA(1, 0), a3, voffA);
;             PG8_WAIT_V(8); PG8_WAIT_L(0); PG8_BAR; PG8_MMA(1, 0, At, B0); PG8_MMA(1, 1, At, B1); PG8_BAR; PG8_SCHED;
	s_add_i32 s30, s57, s36
	v_lshl_add_u64 v[198:199], v[198:199], 0, s[10:11]
	s_mov_b32 m0, s30
	ds_read_b128 v[194:197], v167 offset:49152
	ds_read_b128 v[204:207], v167 offset:50176
	ds_read_b128 v[208:211], v167 offset:51200
	ds_read_b128 v[214:217], v167 offset:52224
	ds_read_b128 v[218:221], v167 offset:53248
	ds_read_b128 v[222:225], v167 offset:54272
	ds_read_b128 v[226:229], v167 offset:55296
	ds_read_b128 v[230:233], v167 offset:56320
	global_load_lds_dwordx4 v[198:199], off
	s_add_i32 m0, s30, 0x2000
	s_add_u32 s28, s28, 0x40080
	v_lshl_add_u64 v[198:199], v[234:235], 0, s[10:11]
	s_addc_u32 s29, s29, 0
	s_add_i32 s30, s58, s36
	global_load_lds_dwordx4 v[198:199], off
	v_lshl_add_u64 v[198:199], s[28:29], 0, v[132:133]
	s_mov_b32 m0, s30
	s_nop 0
	global_load_lds_dwordx4 v[198:199], off
	v_lshl_add_u64 v[198:199], s[28:29], 0, v[136:137]
	s_add_i32 m0, s30, 0x2000
	s_nop 0
	global_load_lds_dwordx4 v[198:199], off
	v_lshl_add_u64 v[198:199], v[236:237], 0, s[10:11]
	s_mov_b32 m0, s42
	s_nop 0
	global_load_lds_dwordx4 v[198:199], off
	v_lshl_add_u64 v[198:199], v[238:239], 0, s[10:11]
	s_mov_b32 m0, s43
	s_nop 0
	global_load_lds_dwordx4 v[198:199], off
	s_waitcnt vmcnt(8)
	s_waitcnt lgkmcnt(0)
	s_barrier
	s_setprio 1
	v_mfma_f32_16x16x32_bf16 v[60:63], v[152:155], v[194:197], v[60:63]
	v_mfma_f32_16x16x32_bf16 v[52:55], v[170:173], v[194:197], v[52:55]
	v_mfma_f32_16x16x32_bf16 v[44:47], v[152:155], v[208:211], v[44:47]
	v_mfma_f32_16x16x32_bf16 v[36:39], v[170:173], v[208:211], v[36:39]
	v_mfma_f32_16x16x32_bf16 v[28:31], v[152:155], v[218:221], v[28:31]
	v_mfma_f32_16x16x32_bf16 v[20:23], v[170:173], v[218:221], v[20:23]
	v_mfma_f32_16x16x32_bf16 v[12:15], v[152:155], v[226:229], v[12:15]
	v_mfma_f32_16x16x32_bf16 v[4:7], v[170:173], v[226:229], v[4:7]
	v_mfma_f32_16x16x32_bf16 v[60:63], v[156:159], v[204:207], v[60:63]
	v_mfma_f32_16x16x32_bf16 v[52:55], v[174:177], v[204:207], v[52:55]
	v_mfma_f32_16x16x32_bf16 v[44:47], v[156:159], v[214:217], v[44:47]
	v_mfma_f32_16x16x32_bf16 v[36:39], v[174:177], v[214:217], v[36:39]
	v_mfma_f32_16x16x32_bf16 v[28:31], v[156:159], v[222:225], v[28:31]
	v_mfma_f32_16x16x32_bf16 v[20:23], v[174:177], v[222:225], v[20:23]
	v_mfma_f32_16x16x32_bf16 v[12:15], v[156:159], v[230:233], v[12:15]
	v_mfma_f32_16x16x32_bf16 v[4:7], v[174:177], v[230:233], v[4:7]
	s_setprio 0
	s_setprio 1
	v_mfma_f32_16x16x32_bf16 v[56:59], v[178:181], v[194:197], v[56:59]
	v_mfma_f32_16x16x32_bf16 v[48:51], v[186:189], v[194:197], v[48:51]
	v_mfma_f32_16x16x32_bf16 v[40:43], v[178:181], v[208:211], v[40:43]
	v_mfma_f32_16x16x32_bf16 v[32:35], v[186:189], v[208:211], v[32:35]
	v_mfma_f32_16x16x32_bf16 v[24:27], v[178:181], v[218:221], v[24:27]
	v_mfma_f32_16x16x32_bf16 v[16:19], v[186:189], v[218:221], v[16:19]
	v_mfma_f32_16x16x32_bf16 v[8:11], v[178:181], v[226:229], v[8:11]
	v_mfma_f32_16x16x32_bf16 v[0:3], v[186:189], v[226:229], v[0:3]
	v_mfma_f32_16x16x32_bf16 v[56:59], v[182:185], v[204:207], v[56:59]
	v_mfma_f32_16x16x32_bf16 v[48:51], v[190:193], v[204:207], v[48:51]
	v_mfma_f32_16x16x32_bf16 v[40:43], v[182:185], v[214:217], v[40:43]
	v_mfma_f32_16x16x32_bf16 v[32:35], v[190:193], v[214:217], v[32:35]
	v_mfma_f32_16x16x32_bf16 v[24:27], v[182:185], v[222:225], v[24:27]
	v_mfma_f32_16x16x32_bf16 v[16:19], v[190:193], v[222:225], v[16:19]
	v_mfma_f32_16x16x32_bf16 v[8:11], v[182:185], v[230:233], v[8:11]
	v_mfma_f32_16x16x32_bf16 v[0:3], v[190:193], v[230:233], v[0:3]
	s_setprio 0
	s_barrier
	s_add_i32 s56, s56, 2
	s_add_u32 s26, s26, 0x100
	s_addc_u32 s27, s27, 0
	s_add_u32 s23, s23, 0x100
	s_addc_u32 s33, s33, 0
	s_cmp_gt_u32 s56, 13
	s_cbranch_scc0 .LBB0_359
	s_and_b64 vcc, exec, s[12:13]
	s_cbranch_vccz .LBB0_362
	s_barrier

; #define PG8_STAGE(bufoff, gbase, voff) do { _Pragma("unroll") for (int _i = 0; _i < 2; ++_i) \
;         __builtin_amdgcn_global_load_lds((const unsigned*)((const char*)(gbase) + (voff)[_i]), (PG8_LAS unsigned*)(lds + (bufoff) + ldsw + _i * 8192), 16, 0, 0); } while (0)
; #define PG8_LDA(dst, b, h) do { _Pragma("unroll") for (int m = 0; m < 4; ++m) _Pragma("unroll") for (int k = 0; k < 2; ++k) dst[m][k] = *(const PG8_LAS bf16x8*)(lds + PG8_SA(b, h) + aoff + m * 2048 + k * 1024); } while (0)
; #define PG8_LDB(dst, b, h) do { _Pragma("unroll") for (int n = 0; n < 2; ++n) _Pragma("unroll") for (int k = 0; k < 2; ++k) dst[n][k] = *(const PG8_LAS bf16x8*)(lds + PG8_SB(b, h) + boff + n * 2048 + k * 1024); } while (0)
; #define PG8_MMA(ai, bj, At, Bt) do { __builtin_amdgcn_s_setprio(1); _Pragma("unroll") for (int m = 0; m < 4; ++m) _Pragma("unroll") for (int n = 0; n < 2; ++n) _Pragma("unroll") for (int k = 0; k < 2; ++k) \
;         acc[ai][bj][m][n] = __builtin_amdgcn_mfma_f32_16x16x32_bf16(Bt[n][k], At[m][k], acc[ai][bj][m][n], 0, 0, 0); __builtin_amdgcn_s_setprio(0); } while (0)
; #define PG8_WAIT_V(n) asm volatile("s_waitcnt vmcnt(" #n ")" ::: "memory")
; #define PG8_WAIT_L(n) asm volatile("s_waitcnt lgkmcnt(" #n ")" ::: "memory")
; #define PG8_BAR __builtin_amdgcn_s_barrier()
; #define PG8_SCHED __builtin_amdgcn_sched_barrier(0)
; template <class Epi, class Sched, bool ALIGN_EPI = false, bool SP2 = false>
; __device__ __forceinline__ void gemm_phase(PG8_LAS unsigned char* lds, const Gemm g, const Sched& S, const Epi& E) {
;     ...
;             PG8_LDB(B0, 0, 0); PG8_LDB(B1, 0, 1); PG8_SCHED; PG8_LDA(At, 0, 0); PG8_STAGE(PG8_SA(1, 1), a1 + hstep, voffA);
;             PG8_WAIT_V(8); PG8_WAIT_L(0); PG8_BAR; PG8_MMA(0, 0, At, B0); PG8_MMA(0, 1, At, B1); PG8_BAR; PG8_SCHED;
;             PG8_LDA(At, 0, 1); PG8_STAGE(PG8_SB(0, 0), b2, voffB); PG8_STAGE(PG8_SB(0, 1), b2 + hstep, voffB); PG8_STAGE(PG8_SA(0, 0), a2, voffA);
;             PG8_WAIT_V(8); PG8_WAIT_L(0); PG8_BAR; PG8_MMA(1, 0, At, B0); PG8_MMA(1, 1, At, B1); PG8_BAR; PG8_SCHED;
;             PG8_LDB(B0, 1, 0); PG8_LDB(B1, 1, 1); PG8_SCHED; PG8_LDA(At, 1, 0); PG8_STAGE(PG8_SA(0, 1), a2 + hstep, voffA);
.LBB0_624:
	ds_read_b128 v[128:131], v220
	ds_read_b128 v[132:135], v220 offset:1024
	ds_read_b128 v[136:139], v220 offset:2048
	ds_read_b128 v[140:143], v220 offset:3072
	ds_read_b128 v[144:147], v221
	ds_read_b128 v[148:151], v221 offset:1024
	ds_read_b128 v[152:155], v221 offset:2048
	ds_read_b128 v[156:159], v221 offset:3072
	s_add_u32 s28, s26, 0xfffc0080
	s_addc_u32 s29, s27, -1
	s_cmp_eq_u32 s47, 12
	s_cselect_b32 s31, s2, s29
	s_cselect_b32 s30, s3, s28
	s_cselect_b32 s29, s15, s46
	s_cselect_b32 s28, s17, s23
	v_lshl_add_u64 v[228:229], s[26:27], 0, v[188:189]
	s_add_i32 m0, s25, 0xc000
	ds_read_b128 v[160:163], v222
	ds_read_b128 v[164:167], v222 offset:1024
	ds_read_b128 v[168:171], v222 offset:2048
	ds_read_b128 v[172:175], v222 offset:3072
	ds_read_b128 v[196:199], v222 offset:4096
	ds_read_b128 v[204:207], v222 offset:5120
	ds_read_b128 v[208:211], v222 offset:6144
	ds_read_b128 v[224:227], v222 offset:7168
	global_load_lds_dwordx4 v[228:229], off
	v_lshl_add_u64 v[228:229], s[26:27], 0, v[190:191]
	s_add_i32 m0, s25, 0xe000
	s_nop 0
	global_load_lds_dwordx4 v[228:229], off
	s_waitcnt vmcnt(8)
	s_waitcnt lgkmcnt(0)
	s_barrier
	s_setprio 1
	v_mfma_f32_16x16x32_bf16 v[124:127], v[128:131], v[160:163], v[124:127]
	v_mfma_f32_16x16x32_bf16 v[120:123], v[136:139], v[160:163], v[120:123]
	v_mfma_f32_16x16x32_bf16 v[108:111], v[128:131], v[168:171], v[108:111]
	v_mfma_f32_16x16x32_bf16 v[104:107], v[136:139], v[168:171], v[104:107]
	v_mfma_f32_16x16x32_bf16 v[92:95], v[128:131], v[196:199], v[92:95]
	v_mfma_f32_16x16x32_bf16 v[88:91], v[136:139], v[196:199], v[88:91]
	v_mfma_f32_16x16x32_bf16 v[76:79], v[128:131], v[208:211], v[76:79]
	v_mfma_f32_16x16x32_bf16 v[72:75], v[136:139], v[208:211], v[72:75]
	v_mfma_f32_16x16x32_bf16 v[124:127], v[132:135], v[164:167], v[124:127]
	v_mfma_f32_16x16x32_bf16 v[120:123], v[140:143], v[164:167], v[120:123]
	v_mfma_f32_16x16x32_bf16 v[108:111], v[132:135], v[172:175], v[108:111]
	v_mfma_f32_16x16x32_bf16 v[104:107], v[140:143], v[172:175], v[104:107]
	v_mfma_f32_16x16x32_bf16 v[92:95], v[132:135], v[204:207], v[92:95]
	v_mfma_f32_16x16x32_bf16 v[88:91], v[140:143], v[204:207], v[88:91]
	v_mfma_f32_16x16x32_bf16 v[76:79], v[132:135], v[224:227], v[76:79]
	v_mfma_f32_16x16x32_bf16 v[72:75], v[140:143], v[224:227], v[72:75]
	s_setprio 0
	s_setprio 1
	v_mfma_f32_16x16x32_bf16 v[116:119], v[144:147], v[160:163], v[116:119]
	v_mfma_f32_16x16x32_bf16 v[112:115], v[152:155], v[160:163], v[112:115]
	v_mfma_f32_16x16x32_bf16 v[100:103], v[144:147], v[168:171], v[100:103]
	v_mfma_f32_16x16x32_bf16 v[96:99], v[152:155], v[168:171], v[96:99]
	v_mfma_f32_16x16x32_bf16 v[84:87], v[144:147], v[196:199], v[84:87]
	v_mfma_f32_16x16x32_bf16 v[80:83], v[152:155], v[196:199], v[80:83]
	v_mfma_f32_16x16x32_bf16 v[68:71], v[144:147], v[208:211], v[68:71]
	v_mfma_f32_16x16x32_bf16 v[64:67], v[152:155], v[208:211], v[64:67]
	v_mfma_f32_16x16x32_bf16 v[116:119], v[148:151], v[164:167], v[116:119]
	v_mfma_f32_16x16x32_bf16 v[112:115], v[156:159], v[164:167], v[112:115]
	v_mfma_f32_16x16x32_bf16 v[100:103], v[148:151], v[172:175], v[100:103]
	v_mfma_f32_16x16x32_bf16 v[96:99], v[156:159], v[172:175], v[96:99]
	v_mfma_f32_16x16x32_bf16 v[84:87], v[148:151], v[204:207], v[84:87]
	v_mfma_f32_16x16x32_bf16 v[80:83], v[156:159], v[204:207], v[80:83]
	v_mfma_f32_16x16x32_bf16 v[68:71], v[148:151], v[224:227], v[68:71]
	v_mfma_f32_16x16x32_bf16 v[64:67], v[156:159], v[224:227], v[64:67]
	s_setprio 0
	s_barrier
	s_add_i32 s48, s44, s35
	v_lshl_add_u64 v[228:229], s[28:29], 0, v[178:179]
	s_mov_b32 m0, s48
	ds_read_b128 v[160:163], v222 offset:16384
	ds_read_b128 v[164:167], v222 offset:17408
	ds_read_b128 v[168:171], v222 offset:18432
	ds_read_b128 v[172:175], v222 offset:19456
	ds_read_b128 v[196:199], v222 offset:20480
	ds_read_b128 v[204:207], v222 offset:21504
	ds_read_b128 v[208:211], v222 offset:22528
	ds_read_b128 v[224:227], v222 offset:23552
	global_load_lds_dwordx4 v[228:229], off
	s_add_i32 m0, s48, 0x2000
	s_add_u32 s48, s28, 0x40000
	v_lshl_add_u64 v[230:231], s[28:29], 0, v[182:183]
	s_addc_u32 s49, s29, 0
	s_add_i32 s50, s45, s35
	global_load_lds_dwordx4 v[230:231], off
	v_lshl_add_u64 v[232:233], s[48:49], 0, v[178:179]
	s_mov_b32 m0, s50
	v_lshl_add_u64 v[234:235], s[30:31], 0, v[180:181]
	global_load_lds_dwordx4 v[232:233], off
	v_lshl_add_u64 v[232:233], s[48:49], 0, v[182:183]
	s_add_i32 m0, s50, 0x2000
	s_nop 0
	global_load_lds_dwordx4 v[232:233], off
	v_lshl_add_u64 v[232:233], s[30:31], 0, v[176:177]
	s_mov_b32 m0, s25
	s_nop 0
	global_load_lds_dwordx4 v[232:233], off
	s_mov_b32 m0, s36
	s_nop 0
	global_load_lds_dwordx4 v[234:235], off
	s_waitcnt vmcnt(8)
	s_waitcnt lgkmcnt(0)
	s_barrier
; #define PG8_STAGE(bufoff, gbase, voff) do { _Pragma("unroll") for (int _i = 0; _i < 2; ++_i) \
;         __builtin_amdgcn_global_load_lds((const unsigned*)((const char*)(gbase) + (voff)[_i]), (PG8_LAS unsigned*)(lds + (bufoff) + ldsw + _i * 8192), 16, 0, 0); } while (0)
; #define PG8_LDA(dst, b, h) do { _Pragma("unroll") for (int m = 0; m < 4; ++m) _Pragma("unroll") for (int k = 0; k < 2; ++k) dst[m][k] = *(const PG8_LAS bf16x8*)(lds + PG8_SA(b, h) + aoff + m * 2048 + k * 1024); } while (0)
; #define PG8_LDB(dst, b, h) do { _Pragma("unroll") for (int n = 0; n < 2; ++n) _Pragma("unroll") for (int k = 0; k < 2; ++k) dst[n][k] = *(const PG8_LAS bf16x8*)(lds + PG8_SB(b, h) + boff + n * 2048 + k * 1024); } while (0)
; #define PG8_MMA(ai, bj, At, Bt) do { __builtin_amdgcn_s_setprio(1); _Pragma("unroll") for (int m = 0; m < 4; ++m) _Pragma("unroll") for (int n = 0; n < 2; ++n) _Pragma("unroll") for (int k = 0; k < 2; ++k) \
;         acc[ai][bj][m][n] = __builtin_amdgcn_mfma_f32_16x16x32_bf16(Bt[n][k], At[m][k], acc[ai][bj][m][n], 0, 0, 0); __builtin_amdgcn_s_setprio(0); } while (0)
; #define PG8_WAIT_V(n) asm volatile("s_waitcnt vmcnt(" #n ")" ::: "memory")
; #define PG8_WAIT_L(n) asm volatile("s_waitcnt lgkmcnt(" #n ")" ::: "memory")
; #define PG8_BAR __builtin_amdgcn_s_barrier()
; #define PG8_SCHED __builtin_amdgcn_sched_barrier(0)
; template <class Epi, class Sched, bool ALIGN_EPI = false, bool SP2 = false>
; __device__ __forceinline__ void gemm_phase(PG8_LAS unsigned char* lds, const Gemm g, const Sched& S, const Epi& E) {
;     ...
;             PG8_WAIT_V(8); PG8_WAIT_L(0); PG8_BAR; PG8_MMA(0, 0, At, B0); PG8_MMA(0, 1, At, B1); PG8_BAR; PG8_SCHED;
;             PG8_LDA(At, 0, 1); PG8_STAGE(PG8_SB(0, 0), b2, voffB); PG8_STAGE(PG8_SB(0, 1), b2 + hstep, voffB); PG8_STAGE(PG8_SA(0, 0), a2, voffA);
;             PG8_WAIT_V(8); PG8_WAIT_L(0); PG8_BAR; PG8_MMA(1, 0, At, B0); PG8_MMA(1, 1, At, B1); PG8_BAR; PG8_SCHED;
;             PG8_LDB(B0, 1, 0); PG8_LDB(B1, 1, 1); PG8_SCHED; PG8_LDA(At, 1, 0); PG8_STAGE(PG8_SA(0, 1), a2 + hstep, voffA);
;             PG8_WAIT_V(8); PG8_WAIT_L(0); PG8_BAR; PG8_MMA(0, 0, At, B0); PG8_MMA(0, 1, At, B1); PG8_BAR; PG8_SCHED;
	s_setprio 1
	v_mfma_f32_16x16x32_bf16 v[60:63], v[128:131], v[160:163], v[60:63]
	v_mfma_f32_16x16x32_bf16 v[56:59], v[136:139], v[160:163], v[56:59]
	v_mfma_f32_16x16x32_bf16 v[44:47], v[128:131], v[168:171], v[44:47]
	v_mfma_f32_16x16x32_bf16 v[40:43], v[136:139], v[168:171], v[40:43]
	v_mfma_f32_16x16x32_bf16 v[28:31], v[128:131], v[196:199], v[28:31]
	v_mfma_f32_16x16x32_bf16 v[24:27], v[136:139], v[196:199], v[24:27]
	v_mfma_f32_16x16x32_bf16 v[12:15], v[128:131], v[208:211], v[12:15]
	v_mfma_f32_16x16x32_bf16 v[8:11], v[136:139], v[208:211], v[8:11]
	v_mfma_f32_16x16x32_bf16 v[60:63], v[132:135], v[164:167], v[60:63]
	v_mfma_f32_16x16x32_bf16 v[56:59], v[140:143], v[164:167], v[56:59]
	v_mfma_f32_16x16x32_bf16 v[44:47], v[132:135], v[172:175], v[44:47]
	v_mfma_f32_16x16x32_bf16 v[40:43], v[140:143], v[172:175], v[40:43]
	v_mfma_f32_16x16x32_bf16 v[28:31], v[132:135], v[204:207], v[28:31]
	v_mfma_f32_16x16x32_bf16 v[24:27], v[140:143], v[204:207], v[24:27]
	v_mfma_f32_16x16x32_bf16 v[12:15], v[132:135], v[224:227], v[12:15]
	v_mfma_f32_16x16x32_bf16 v[8:11], v[140:143], v[224:227], v[8:11]
	s_setprio 0
	s_setprio 1
	v_mfma_f32_16x16x32_bf16 v[52:55], v[144:147], v[160:163], v[52:55]
	v_mfma_f32_16x16x32_bf16 v[48:51], v[152:155], v[160:163], v[48:51]
	v_mfma_f32_16x16x32_bf16 v[36:39], v[144:147], v[168:171], v[36:39]
	v_mfma_f32_16x16x32_bf16 v[32:35], v[152:155], v[168:171], v[32:35]
	v_mfma_f32_16x16x32_bf16 v[20:23], v[144:147], v[196:199], v[20:23]
	v_mfma_f32_16x16x32_bf16 v[16:19], v[152:155], v[196:199], v[16:19]
	v_mfma_f32_16x16x32_bf16 v[4:7], v[144:147], v[208:211], v[4:7]
	v_mfma_f32_16x16x32_bf16 v[0:3], v[152:155], v[208:211], v[0:3]
	v_mfma_f32_16x16x32_bf16 v[52:55], v[148:151], v[164:167], v[52:55]
	v_mfma_f32_16x16x32_bf16 v[48:51], v[156:159], v[164:167], v[48:51]
	v_mfma_f32_16x16x32_bf16 v[36:39], v[148:151], v[172:175], v[36:39]
	v_mfma_f32_16x16x32_bf16 v[32:35], v[156:159], v[172:175], v[32:35]
	v_mfma_f32_16x16x32_bf16 v[20:23], v[148:151], v[204:207], v[20:23]
	v_mfma_f32_16x16x32_bf16 v[16:19], v[156:159], v[204:207], v[16:19]
	v_mfma_f32_16x16x32_bf16 v[4:7], v[148:151], v[224:227], v[4:7]
	v_mfma_f32_16x16x32_bf16 v[0:3], v[156:159], v[224:227], v[0:3]
	s_setprio 0
	s_barrier
	s_add_i32 s48, 0, 0x18000
	s_add_i32 s49, 0, 0x1c000
	v_add_u32_e32 v140, s48, v201
	v_add_u32_e32 v156, s49, v201
	ds_read_b128 v[128:131], v140
	ds_read_b128 v[132:135], v140 offset:1024
	ds_read_b128 v[136:139], v140 offset:2048
	ds_read_b128 v[140:143], v140 offset:3072
	ds_read_b128 v[144:147], v156
	ds_read_b128 v[148:151], v156 offset:1024
	ds_read_b128 v[152:155], v156 offset:2048
	ds_read_b128 v[156:159], v156 offset:3072
	s_add_u32 s30, s30, 0x40000
	s_addc_u32 s31, s31, 0
	s_mov_b32 m0, s37
	v_lshl_add_u64 v[236:237], s[30:31], 0, v[176:177]
	ds_read_b128 v[160:163], v222 offset:32768
	ds_read_b128 v[164:167], v222 offset:33792
	ds_read_b128 v[168:171], v222 offset:34816
	ds_read_b128 v[172:175], v222 offset:35840
	ds_read_b128 v[196:199], v222 offset:36864
	ds_read_b128 v[204:207], v222 offset:37888
	ds_read_b128 v[208:211], v222 offset:38912
	ds_read_b128 v[224:227], v222 offset:39936
	global_load_lds_dwordx4 v[236:237], off
	v_lshl_add_u64 v[236:237], s[30:31], 0, v[180:181]
	s_mov_b32 m0, s38
	s_nop 0
	global_load_lds_dwordx4 v[236:237], off
	s_waitcnt vmcnt(8)
	s_waitcnt lgkmcnt(0)
	s_barrier
	s_setprio 1
	v_mfma_f32_16x16x32_bf16 v[124:127], v[128:131], v[160:163], v[124:127]
	v_mfma_f32_16x16x32_bf16 v[120:123], v[136:139], v[160:163], v[120:123]
	v_mfma_f32_16x16x32_bf16 v[108:111], v[128:131], v[168:171], v[108:111]
	v_mfma_f32_16x16x32_bf16 v[104:107], v[136:139], v[168:171], v[104:107]
	v_mfma_f32_16x16x32_bf16 v[92:95], v[128:131], v[196:199], v[92:95]
	v_mfma_f32_16x16x32_bf16 v[88:91], v[136:139], v[196:199], v[88:91]
	v_mfma_f32_16x16x32_bf16 v[76:79], v[128:131], v[208:211], v[76:79]
	v_mfma_f32_16x16x32_bf16 v[72:75], v[136:139], v[208:211], v[72:75]
	v_mfma_f32_16x16x32_bf16 v[124:127], v[132:135], v[164:167], v[124:127]
	v_mfma_f32_16x16x32_bf16 v[120:123], v[140:143], v[164:167], v[120:123]
	v_mfma_f32_16x16x32_bf16 v[108:111], v[132:135], v[172:175], v[108:111]
	v_mfma_f32_16x16x32_bf16 v[104:107], v[140:143], v[172:175], v[104:107]
	v_mfma_f32_16x16x32_bf16 v[92:95], v[132:135], v[204:207], v[92:95]
	v_mfma_f32_16x16x32_bf16 v[88:91], v[140:143], v[204:207], v[88:91]
	v_mfma_f32_16x16x32_bf16 v[76:79], v[132:135], v[224:227], v[76:79]
	v_mfma_f32_16x16x32_bf16 v[72:75], v[140:143], v[224:227], v[72:75]
	s_setprio 0
	s_setprio 1
	v_mfma_f32_16x16x32_bf16 v[116:119], v[144:147], v[160:163], v[116:119]
	v_mfma_f32_16x16x32_bf16 v[112:115], v[152:155], v[160:163], v[112:115]
	v_mfma_f32_16x16x32_bf16 v[100:103], v[144:147], v[168:171], v[100:103]
	v_mfma_f32_16x16x32_bf16 v[96:99], v[152:155], v[168:171], v[96:99]
	v_mfma_f32_16x16x32_bf16 v[84:87], v[144:147], v[196:199], v[84:87]
	v_mfma_f32_16x16x32_bf16 v[80:83], v[152:155], v[196:199], v[80:83]
	v_mfma_f32_16x16x32_bf16 v[68:71], v[144:147], v[208:211], v[68:71]
	v_mfma_f32_16x16x32_bf16 v[64:67], v[152:155], v[208:211], v[64:67]
	v_mfma_f32_16x16x32_bf16 v[116:119], v[148:151], v[164:167], v[116:119]
	v_mfma_f32_16x16x32_bf16 v[112:115], v[156:159], v[164:167], v[112:115]
	v_mfma_f32_16x16x32_bf16 v[100:103], v[148:151], v[172:175], v[100:103]
	v_mfma_f32_16x16x32_bf16 v[96:99], v[156:159], v[172:175], v[96:99]
	v_mfma_f32_16x16x32_bf16 v[84:87], v[148:151], v[204:207], v[84:87]
	v_mfma_f32_16x16x32_bf16 v[80:83], v[156:159], v[204:207], v[80:83]
	v_mfma_f32_16x16x32_bf16 v[68:71], v[148:151], v[224:227], v[68:71]
	v_mfma_f32_16x16x32_bf16 v[64:67], v[156:159], v[224:227], v[64:67]
	s_setprio 0
	s_barrier
; #define PG8_STAGE(bufoff, gbase, voff) do { _Pragma("unroll") for (int _i = 0; _i < 2; ++_i) \
;         __builtin_amdgcn_global_load_lds((const unsigned*)((const char*)(gbase) + (voff)[_i]), (PG8_LAS unsigned*)(lds + (bufoff) + ldsw + _i * 8192), 16, 0, 0); } while (0)
; #define PG8_LDA(dst, b, h) do { _Pragma("unroll") for (int m = 0; m < 4; ++m) _Pragma("unroll") for (int k = 0; k < 2; ++k) dst[m][k] = *(const PG8_LAS bf16x8*)(lds + PG8_SA(b, h) + aoff + m * 2048 + k * 1024); } while (0)
; #define PG8_MMA(ai, bj, At, Bt) do { __builtin_amdgcn_s_setprio(1); _Pragma("unroll") for (int m = 0; m < 4; ++m) _Pragma("unroll") for (int n = 0; n < 2; ++n) _Pragma("unroll") for (int k = 0; k < 2; ++k) \
;         acc[ai][bj][m][n] = __builtin_amdgcn_mfma_f32_16x16x32_bf16(Bt[n][k], At[m][k], acc[ai][bj][m][n], 0, 0, 0); __builtin_amdgcn_s_setprio(0); } while (0)
; #define PG8_WAIT_V(n) asm volatile("s_waitcnt vmcnt(" #n ")" ::: "memory")
; #define PG8_WAIT_L(n) asm volatile("s_waitcnt lgkmcnt(" #n ")" ::: "memory")
; #define PG8_BAR __builtin_amdgcn_s_barrier()
; #define PG8_SCHED __builtin_amdgcn_sched_barrier(0)
; template <class Epi, class Sched, bool ALIGN_EPI = false, bool SP2 = false>
; __device__ __forceinline__ void gemm_phase(PG8_LAS unsigned char* lds, const Gemm g, const Sched& S, const Epi& E) {
;     ...
;             PG8_WAIT_V(8); PG8_WAIT_L(0); PG8_BAR; PG8_MMA(0, 0, At, B0); PG8_MMA(0, 1, At, B1); PG8_BAR; PG8_SCHED;
;             PG8_LDA(At, 1, 1); PG8_STAGE(PG8_SB(1, 0), b3, voffB); PG8_STAGE(PG8_SB(1, 1), b3 + hstep, voffB); PG8_STAGE(PG8_SA(1, 0), a3, voffA);
;             PG8_WAIT_V(8); PG8_WAIT_L(0); PG8_BAR; PG8_MMA(1, 0, At, B0); PG8_MMA(1, 1, At, B1); PG8_BAR; PG8_SCHED;
	s_add_i32 s30, s48, s35
	v_lshl_add_u64 v[228:229], v[228:229], 0, s[10:11]
	s_mov_b32 m0, s30
	ds_read_b128 v[160:163], v222 offset:49152
	ds_read_b128 v[164:167], v222 offset:50176
	ds_read_b128 v[168:171], v222 offset:51200
	ds_read_b128 v[172:175], v222 offset:52224
	ds_read_b128 v[196:199], v222 offset:53248
	ds_read_b128 v[204:207], v222 offset:54272
	ds_read_b128 v[208:211], v222 offset:55296
	ds_read_b128 v[224:227], v222 offset:56320
	global_load_lds_dwordx4 v[228:229], off
	s_add_i32 m0, s30, 0x2000
	s_add_u32 s28, s28, 0x40080
	v_lshl_add_u64 v[228:229], v[230:231], 0, s[10:11]
	s_addc_u32 s29, s29, 0
	s_add_i32 s30, s49, s35
	global_load_lds_dwordx4 v[228:229], off
	v_lshl_add_u64 v[228:229], s[28:29], 0, v[178:179]
	s_mov_b32 m0, s30
	s_nop 0
	global_load_lds_dwordx4 v[228:229], off
	v_lshl_add_u64 v[228:229], s[28:29], 0, v[182:183]
	s_add_i32 m0, s30, 0x2000
	s_nop 0
	global_load_lds_dwordx4 v[228:229], off
	v_lshl_add_u64 v[228:229], v[232:233], 0, s[10:11]
	s_mov_b32 m0, s40
	s_nop 0
	global_load_lds_dwordx4 v[228:229], off
	v_lshl_add_u64 v[228:229], v[234:235], 0, s[10:11]
	s_mov_b32 m0, s41
	s_nop 0
	global_load_lds_dwordx4 v[228:229], off
	s_waitcnt vmcnt(8)
	s_waitcnt lgkmcnt(0)
	s_barrier
	s_setprio 1
	v_mfma_f32_16x16x32_bf16 v[60:63], v[128:131], v[160:163], v[60:63]
	v_mfma_f32_16x16x32_bf16 v[56:59], v[136:139], v[160:163], v[56:59]
	v_mfma_f32_16x16x32_bf16 v[44:47], v[128:131], v[168:171], v[44:47]
	v_mfma_f32_16x16x32_bf16 v[40:43], v[136:139], v[168:171], v[40:43]
	v_mfma_f32_16x16x32_bf16 v[28:31], v[128:131], v[196:199], v[28:31]
	v_mfma_f32_16x16x32_bf16 v[24:27], v[136:139], v[196:199], v[24:27]
	v_mfma_f32_16x16x32_bf16 v[12:15], v[128:131], v[208:211], v[12:15]
	v_mfma_f32_16x16x32_bf16 v[8:11], v[136:139], v[208:211], v[8:11]
	v_mfma_f32_16x16x32_bf16 v[60:63], v[132:135], v[164:167], v[60:63]
	v_mfma_f32_16x16x32_bf16 v[56:59], v[140:143], v[164:167], v[56:59]
	v_mfma_f32_16x16x32_bf16 v[44:47], v[132:135], v[172:175], v[44:47]
	v_mfma_f32_16x16x32_bf16 v[40:43], v[140:143], v[172:175], v[40:43]
	v_mfma_f32_16x16x32_bf16 v[28:31], v[132:135], v[204:207], v[28:31]
	v_mfma_f32_16x16x32_bf16 v[24:27], v[140:143], v[204:207], v[24:27]
	v_mfma_f32_16x16x32_bf16 v[12:15], v[132:135], v[224:227], v[12:15]
	v_mfma_f32_16x16x32_bf16 v[8:11], v[140:143], v[224:227], v[8:11]
	s_setprio 0
	s_setprio 1
	v_mfma_f32_16x16x32_bf16 v[52:55], v[144:147], v[160:163], v[52:55]
	v_mfma_f32_16x16x32_bf16 v[48:51], v[152:155], v[160:163], v[48:51]
	v_mfma_f32_16x16x32_bf16 v[36:39], v[144:147], v[168:171], v[36:39]
	v_mfma_f32_16x16x32_bf16 v[32:35], v[152:155], v[168:171], v[32:35]
	v_mfma_f32_16x16x32_bf16 v[20:23], v[144:147], v[196:199], v[20:23]
	v_mfma_f32_16x16x32_bf16 v[16:19], v[152:155], v[196:199], v[16:19]
	v_mfma_f32_16x16x32_bf16 v[4:7], v[144:147], v[208:211], v[4:7]
	v_mfma_f32_16x16x32_bf16 v[0:3], v[152:155], v[208:211], v[0:3]
	v_mfma_f32_16x16x32_bf16 v[52:55], v[148:151], v[164:167], v[52:55]
	v_mfma_f32_16x16x32_bf16 v[48:51], v[156:159], v[164:167], v[48:51]
	v_mfma_f32_16x16x32_bf16 v[36:39], v[148:151], v[172:175], v[36:39]
	v_mfma_f32_16x16x32_bf16 v[32:35], v[156:159], v[172:175], v[32:35]
	v_mfma_f32_16x16x32_bf16 v[20:23], v[148:151], v[204:207], v[20:23]
	v_mfma_f32_16x16x32_bf16 v[16:19], v[156:159], v[204:207], v[16:19]
	v_mfma_f32_16x16x32_bf16 v[4:7], v[148:151], v[224:227], v[4:7]
	v_mfma_f32_16x16x32_bf16 v[0:3], v[156:159], v[224:227], v[0:3]
	s_setprio 0
	s_barrier
	s_add_i32 s47, s47, 2
	s_add_u32 s26, s26, 0x100
	s_addc_u32 s27, s27, 0
	s_add_u32 s23, s23, 0x100
	s_addc_u32 s46, s46, 0
	s_cmp_gt_u32 s47, 13
	s_cbranch_scc0 .LBB0_624
	s_and_b64 vcc, exec, s[12:13]
	s_cbranch_vccz .LBB0_627
	s_barrier

; #define PG8_STAGE(bufoff, gbase, voff) do { _Pragma("unroll") for (int _i = 0; _i < 2; ++_i) \
;         __builtin_amdgcn_global_load_lds((const unsigned*)((const char*)(gbase) + (voff)[_i]), (PG8_LAS unsigned*)(lds + (bufoff) + ldsw + _i * 8192), 16, 0, 0); } while (0)
; #define PG8_LDA(dst, b, h) do { _Pragma("unroll") for (int m = 0; m < 4; ++m) _Pragma("unroll") for (int k = 0; k < 2; ++k) dst[m][k] = *(const PG8_LAS bf16x8*)(lds + PG8_SA(b, h) + aoff + m * 2048 + k * 1024); } while (0)
; #define PG8_LDB(dst, b, h) do { _Pragma("unroll") for (int n = 0; n < 2; ++n) _Pragma("unroll") for (int k = 0; k < 2; ++k) dst[n][k] = *(const PG8_LAS bf16x8*)(lds + PG8_SB(b, h) + boff + n * 2048 + k * 1024); } while (0)
; #define PG8_MMA(ai, bj, At, Bt) do { __builtin_amdgcn_s_setprio(1); _Pragma("unroll") for (int m = 0; m < 4; ++m) _Pragma("unroll") for (int n = 0; n < 2; ++n) _Pragma("unroll") for (int k = 0; k < 2; ++k) \
;         acc[ai][bj][m][n] = __builtin_amdgcn_mfma_f32_16x16x32_bf16(Bt[n][k], At[m][k], acc[ai][bj][m][n], 0, 0, 0); __builtin_amdgcn_s_setprio(0); } while (0)
; #define PG8_WAIT_V(n) asm volatile("s_waitcnt vmcnt(" #n ")" ::: "memory")
; #define PG8_WAIT_L(n) asm volatile("s_waitcnt lgkmcnt(" #n ")" ::: "memory")
; #define PG8_BAR __builtin_amdgcn_s_barrier()
; #define PG8_SCHED __builtin_amdgcn_sched_barrier(0)
; template <class Epi, class Sched, bool ALIGN_EPI = false, bool SP2 = false>
; __device__ __forceinline__ void gemm_phase(PG8_LAS unsigned char* lds, const Gemm g, const Sched& S, const Epi& E) {
;     ...
;             PG8_LDB(B0, 0, 0); PG8_LDB(B1, 0, 1); PG8_SCHED; PG8_LDA(At, 0, 0); PG8_STAGE(PG8_SA(1, 1), a1 + hstep, voffA);
;             PG8_WAIT_V(8); PG8_WAIT_L(0); PG8_BAR; PG8_MMA(0, 0, At, B0); PG8_MMA(0, 1, At, B1); PG8_BAR; PG8_SCHED;
;             PG8_LDA(At, 0, 1); PG8_STAGE(PG8_SB(0, 0), b2, voffB); PG8_STAGE(PG8_SB(0, 1), b2 + hstep, voffB); PG8_STAGE(PG8_SA(0, 0), a2, voffA);
;             PG8_WAIT_V(8); PG8_WAIT_L(0); PG8_BAR; PG8_MMA(1, 0, At, B0); PG8_MMA(1, 1, At, B1); PG8_BAR; PG8_SCHED;
;             PG8_LDB(B0, 1, 0); PG8_LDB(B1, 1, 1); PG8_SCHED; PG8_LDA(At, 1, 0); PG8_STAGE(PG8_SA(0, 1), a2 + hstep, voffA);
.LBB0_708:
	ds_read_b128 v[154:157], v150
	ds_read_b128 v[158:161], v150 offset:1024
	ds_read_b128 v[162:165], v150 offset:2048
	ds_read_b128 v[166:169], v150 offset:3072
	ds_read_b128 v[170:173], v151
	ds_read_b128 v[174:177], v151 offset:1024
	ds_read_b128 v[178:181], v151 offset:2048
	ds_read_b128 v[182:185], v151 offset:3072
	s_add_u32 s28, s26, 0xfffc0080
	s_addc_u32 s29, s27, -1
	s_cmp_eq_u32 s51, 12
	s_cselect_b32 s31, s3, s29
	s_cselect_b32 s30, s17, s28
	s_cselect_b32 s29, s15, s50
	s_cselect_b32 s28, s23, s49
	v_lshl_add_u64 v[146:147], s[26:27], 0, v[138:139]
	s_add_i32 m0, s37, 0xc000
	ds_read_b128 v[186:189], v152
	ds_read_b128 v[190:193], v152 offset:1024
	ds_read_b128 v[194:197], v152 offset:2048
	ds_read_b128 v[204:207], v152 offset:3072
	ds_read_b128 v[208:211], v152 offset:4096
	ds_read_b128 v[220:223], v152 offset:5120
	ds_read_b128 v[224:227], v152 offset:6144
	ds_read_b128 v[228:231], v152 offset:7168
	global_load_lds_dwordx4 v[146:147], off
	v_lshl_add_u64 v[146:147], s[26:27], 0, v[140:141]
	s_add_i32 m0, s37, 0xe000
	s_nop 0
	global_load_lds_dwordx4 v[146:147], off
	s_waitcnt vmcnt(8)
	s_waitcnt lgkmcnt(0)
	s_barrier
	s_setprio 1
	v_mfma_f32_16x16x32_bf16 v[116:119], v[154:157], v[186:189], v[116:119]
	v_mfma_f32_16x16x32_bf16 v[112:115], v[162:165], v[186:189], v[112:115]
	v_mfma_f32_16x16x32_bf16 v[104:107], v[154:157], v[194:197], v[104:107]
	v_mfma_f32_16x16x32_bf16 v[96:99], v[162:165], v[194:197], v[96:99]
	v_mfma_f32_16x16x32_bf16 v[88:91], v[154:157], v[208:211], v[88:91]
	v_mfma_f32_16x16x32_bf16 v[80:83], v[162:165], v[208:211], v[80:83]
	v_mfma_f32_16x16x32_bf16 v[72:75], v[154:157], v[224:227], v[72:75]
	v_mfma_f32_16x16x32_bf16 v[64:67], v[162:165], v[224:227], v[64:67]
	v_mfma_f32_16x16x32_bf16 v[116:119], v[158:161], v[190:193], v[116:119]
	v_mfma_f32_16x16x32_bf16 v[112:115], v[166:169], v[190:193], v[112:115]
	v_mfma_f32_16x16x32_bf16 v[104:107], v[158:161], v[204:207], v[104:107]
	v_mfma_f32_16x16x32_bf16 v[96:99], v[166:169], v[204:207], v[96:99]
	v_mfma_f32_16x16x32_bf16 v[88:91], v[158:161], v[220:223], v[88:91]
	v_mfma_f32_16x16x32_bf16 v[80:83], v[166:169], v[220:223], v[80:83]
	v_mfma_f32_16x16x32_bf16 v[72:75], v[158:161], v[228:231], v[72:75]
	v_mfma_f32_16x16x32_bf16 v[64:67], v[166:169], v[228:231], v[64:67]
	s_setprio 0
	s_setprio 1
	v_mfma_f32_16x16x32_bf16 v[124:127], v[170:173], v[186:189], v[124:127]
	v_mfma_f32_16x16x32_bf16 v[120:123], v[178:181], v[186:189], v[120:123]
	v_mfma_f32_16x16x32_bf16 v[108:111], v[170:173], v[194:197], v[108:111]
	v_mfma_f32_16x16x32_bf16 v[100:103], v[178:181], v[194:197], v[100:103]
	v_mfma_f32_16x16x32_bf16 v[92:95], v[170:173], v[208:211], v[92:95]
	v_mfma_f32_16x16x32_bf16 v[84:87], v[178:181], v[208:211], v[84:87]
	v_mfma_f32_16x16x32_bf16 v[76:79], v[170:173], v[224:227], v[76:79]
	v_mfma_f32_16x16x32_bf16 v[68:71], v[178:181], v[224:227], v[68:71]
	v_mfma_f32_16x16x32_bf16 v[124:127], v[174:177], v[190:193], v[124:127]
	v_mfma_f32_16x16x32_bf16 v[120:123], v[182:185], v[190:193], v[120:123]
	v_mfma_f32_16x16x32_bf16 v[108:111], v[174:177], v[204:207], v[108:111]
	v_mfma_f32_16x16x32_bf16 v[100:103], v[182:185], v[204:207], v[100:103]
	v_mfma_f32_16x16x32_bf16 v[92:95], v[174:177], v[220:223], v[92:95]
	v_mfma_f32_16x16x32_bf16 v[84:87], v[182:185], v[220:223], v[84:87]
	v_mfma_f32_16x16x32_bf16 v[76:79], v[174:177], v[228:231], v[76:79]
	v_mfma_f32_16x16x32_bf16 v[68:71], v[182:185], v[228:231], v[68:71]
	s_setprio 0
	s_barrier
	s_add_i32 s52, s45, s35
	v_lshl_add_u64 v[146:147], s[28:29], 0, v[132:133]
	s_mov_b32 m0, s52
	ds_read_b128 v[186:189], v152 offset:16384
	ds_read_b128 v[190:193], v152 offset:17408
	ds_read_b128 v[194:197], v152 offset:18432
	ds_read_b128 v[204:207], v152 offset:19456
	ds_read_b128 v[208:211], v152 offset:20480
	ds_read_b128 v[220:223], v152 offset:21504
	ds_read_b128 v[224:227], v152 offset:22528
	ds_read_b128 v[228:231], v152 offset:23552
	global_load_lds_dwordx4 v[146:147], off
	s_add_i32 m0, s52, 0x2000
	s_add_u32 s52, s28, 0x40000
	v_lshl_add_u64 v[198:199], s[28:29], 0, v[128:129]
	s_addc_u32 s53, s29, 0
	s_add_i32 s54, s46, s35
	global_load_lds_dwordx4 v[198:199], off
	v_lshl_add_u64 v[232:233], s[52:53], 0, v[132:133]
	s_mov_b32 m0, s54
	v_lshl_add_u64 v[234:235], s[30:31], 0, v[130:131]
	global_load_lds_dwordx4 v[232:233], off
	v_lshl_add_u64 v[232:233], s[52:53], 0, v[128:129]
	s_add_i32 m0, s54, 0x2000
	s_nop 0
	global_load_lds_dwordx4 v[232:233], off
	v_lshl_add_u64 v[232:233], s[30:31], 0, v[134:135]
	s_mov_b32 m0, s37
	s_nop 0
	global_load_lds_dwordx4 v[232:233], off
	s_mov_b32 m0, s38
	s_nop 0
	global_load_lds_dwordx4 v[234:235], off
	s_waitcnt vmcnt(8)
	s_waitcnt lgkmcnt(0)
	s_barrier
; #define PG8_STAGE(bufoff, gbase, voff) do { _Pragma("unroll") for (int _i = 0; _i < 2; ++_i) \
;         __builtin_amdgcn_global_load_lds((const unsigned*)((const char*)(gbase) + (voff)[_i]), (PG8_LAS unsigned*)(lds + (bufoff) + ldsw + _i * 8192), 16, 0, 0); } while (0)
; #define PG8_LDA(dst, b, h) do { _Pragma("unroll") for (int m = 0; m < 4; ++m) _Pragma("unroll") for (int k = 0; k < 2; ++k) dst[m][k] = *(const PG8_LAS bf16x8*)(lds + PG8_SA(b, h) + aoff + m * 2048 + k * 1024); } while (0)
; #define PG8_LDB(dst, b, h) do { _Pragma("unroll") for (int n = 0; n < 2; ++n) _Pragma("unroll") for (int k = 0; k < 2; ++k) dst[n][k] = *(const PG8_LAS bf16x8*)(lds + PG8_SB(b, h) + boff + n * 2048 + k * 1024); } while (0)
; #define PG8_MMA(ai, bj, At, Bt) do { __builtin_amdgcn_s_setprio(1); _Pragma("unroll") for (int m = 0; m < 4; ++m) _Pragma("unroll") for (int n = 0; n < 2; ++n) _Pragma("unroll") for (int k = 0; k < 2; ++k) \
;         acc[ai][bj][m][n] = __builtin_amdgcn_mfma_f32_16x16x32_bf16(Bt[n][k], At[m][k], acc[ai][bj][m][n], 0, 0, 0); __builtin_amdgcn_s_setprio(0); } while (0)
; #define PG8_WAIT_V(n) asm volatile("s_waitcnt vmcnt(" #n ")" ::: "memory")
; #define PG8_WAIT_L(n) asm volatile("s_waitcnt lgkmcnt(" #n ")" ::: "memory")
; #define PG8_BAR __builtin_amdgcn_s_barrier()
; #define PG8_SCHED __builtin_amdgcn_sched_barrier(0)
; template <class Epi, class Sched, bool ALIGN_EPI = false, bool SP2 = false>
; __device__ __forceinline__ void gemm_phase(PG8_LAS unsigned char* lds, const Gemm g, const Sched& S, const Epi& E) {
;     ...
;             PG8_WAIT_V(8); PG8_WAIT_L(0); PG8_BAR; PG8_MMA(1, 0, At, B0); PG8_MMA(1, 1, At, B1); PG8_BAR; PG8_SCHED;
;             PG8_LDB(B0, 1, 0); PG8_LDB(B1, 1, 1); PG8_SCHED; PG8_LDA(At, 1, 0); PG8_STAGE(PG8_SA(0, 1), a2 + hstep, voffA);
;             PG8_WAIT_V(8); PG8_WAIT_L(0); PG8_BAR; PG8_MMA(0, 0, At, B0); PG8_MMA(0, 1, At, B1); PG8_BAR; PG8_SCHED;
	s_setprio 1
	v_mfma_f32_16x16x32_bf16 v[56:59], v[154:157], v[186:189], v[56:59]
	v_mfma_f32_16x16x32_bf16 v[48:51], v[162:165], v[186:189], v[48:51]
	v_mfma_f32_16x16x32_bf16 v[40:43], v[154:157], v[194:197], v[40:43]
	v_mfma_f32_16x16x32_bf16 v[32:35], v[162:165], v[194:197], v[32:35]
	v_mfma_f32_16x16x32_bf16 v[24:27], v[154:157], v[208:211], v[24:27]
	v_mfma_f32_16x16x32_bf16 v[16:19], v[162:165], v[208:211], v[16:19]
	v_mfma_f32_16x16x32_bf16 v[8:11], v[154:157], v[224:227], v[8:11]
	v_mfma_f32_16x16x32_bf16 v[0:3], v[162:165], v[224:227], v[0:3]
	v_mfma_f32_16x16x32_bf16 v[56:59], v[158:161], v[190:193], v[56:59]
	v_mfma_f32_16x16x32_bf16 v[48:51], v[166:169], v[190:193], v[48:51]
	v_mfma_f32_16x16x32_bf16 v[40:43], v[158:161], v[204:207], v[40:43]
	v_mfma_f32_16x16x32_bf16 v[32:35], v[166:169], v[204:207], v[32:35]
	v_mfma_f32_16x16x32_bf16 v[24:27], v[158:161], v[220:223], v[24:27]
	v_mfma_f32_16x16x32_bf16 v[16:19], v[166:169], v[220:223], v[16:19]
	v_mfma_f32_16x16x32_bf16 v[8:11], v[158:161], v[228:231], v[8:11]
	v_mfma_f32_16x16x32_bf16 v[0:3], v[166:169], v[228:231], v[0:3]
	s_setprio 0
	s_setprio 1
	v_mfma_f32_16x16x32_bf16 v[60:63], v[170:173], v[186:189], v[60:63]
	v_mfma_f32_16x16x32_bf16 v[52:55], v[178:181], v[186:189], v[52:55]
	v_mfma_f32_16x16x32_bf16 v[44:47], v[170:173], v[194:197], v[44:47]
	v_mfma_f32_16x16x32_bf16 v[36:39], v[178:181], v[194:197], v[36:39]
	v_mfma_f32_16x16x32_bf16 v[28:31], v[170:173], v[208:211], v[28:31]
	v_mfma_f32_16x16x32_bf16 v[20:23], v[178:181], v[208:211], v[20:23]
	v_mfma_f32_16x16x32_bf16 v[12:15], v[170:173], v[224:227], v[12:15]
	v_mfma_f32_16x16x32_bf16 v[4:7], v[178:181], v[224:227], v[4:7]
	v_mfma_f32_16x16x32_bf16 v[60:63], v[174:177], v[190:193], v[60:63]
	v_mfma_f32_16x16x32_bf16 v[52:55], v[182:185], v[190:193], v[52:55]
	v_mfma_f32_16x16x32_bf16 v[44:47], v[174:177], v[204:207], v[44:47]
	v_mfma_f32_16x16x32_bf16 v[36:39], v[182:185], v[204:207], v[36:39]
	v_mfma_f32_16x16x32_bf16 v[28:31], v[174:177], v[220:223], v[28:31]
	v_mfma_f32_16x16x32_bf16 v[20:23], v[182:185], v[220:223], v[20:23]
	v_mfma_f32_16x16x32_bf16 v[12:15], v[174:177], v[228:231], v[12:15]
	v_mfma_f32_16x16x32_bf16 v[4:7], v[182:185], v[228:231], v[4:7]
	s_setprio 0
	s_barrier
	s_add_i32 s52, 0, 0x18000
	s_add_i32 s53, 0, 0x1c000
	v_add_u32_e32 v166, s52, v149
	v_add_u32_e32 v182, s53, v149
	ds_read_b128 v[154:157], v166
	ds_read_b128 v[158:161], v166 offset:1024
	ds_read_b128 v[162:165], v166 offset:2048
	ds_read_b128 v[166:169], v166 offset:3072
	ds_read_b128 v[170:173], v182
	ds_read_b128 v[174:177], v182 offset:1024
	ds_read_b128 v[178:181], v182 offset:2048
	ds_read_b128 v[182:185], v182 offset:3072
	s_add_u32 s30, s30, 0x40000
	s_addc_u32 s31, s31, 0
	s_mov_b32 m0, s39
	v_lshl_add_u64 v[236:237], s[30:31], 0, v[134:135]
	ds_read_b128 v[186:189], v152 offset:32768
	ds_read_b128 v[190:193], v152 offset:33792
	ds_read_b128 v[194:197], v152 offset:34816
	ds_read_b128 v[204:207], v152 offset:35840
	ds_read_b128 v[208:211], v152 offset:36864
	ds_read_b128 v[220:223], v152 offset:37888
	ds_read_b128 v[224:227], v152 offset:38912
	ds_read_b128 v[228:231], v152 offset:39936
	global_load_lds_dwordx4 v[236:237], off
	v_lshl_add_u64 v[236:237], s[30:31], 0, v[130:131]
	s_mov_b32 m0, s40
	s_nop 0
	global_load_lds_dwordx4 v[236:237], off
	s_waitcnt vmcnt(8)
	s_waitcnt lgkmcnt(0)
	s_barrier
	s_setprio 1
	v_mfma_f32_16x16x32_bf16 v[116:119], v[154:157], v[186:189], v[116:119]
	v_mfma_f32_16x16x32_bf16 v[112:115], v[162:165], v[186:189], v[112:115]
	v_mfma_f32_16x16x32_bf16 v[104:107], v[154:157], v[194:197], v[104:107]
	v_mfma_f32_16x16x32_bf16 v[96:99], v[162:165], v[194:197], v[96:99]
	v_mfma_f32_16x16x32_bf16 v[88:91], v[154:157], v[208:211], v[88:91]
	v_mfma_f32_16x16x32_bf16 v[80:83], v[162:165], v[208:211], v[80:83]
	v_mfma_f32_16x16x32_bf16 v[72:75], v[154:157], v[224:227], v[72:75]
	v_mfma_f32_16x16x32_bf16 v[64:67], v[162:165], v[224:227], v[64:67]
	v_mfma_f32_16x16x32_bf16 v[116:119], v[158:161], v[190:193], v[116:119]
	v_mfma_f32_16x16x32_bf16 v[112:115], v[166:169], v[190:193], v[112:115]
	v_mfma_f32_16x16x32_bf16 v[104:107], v[158:161], v[204:207], v[104:107]
	v_mfma_f32_16x16x32_bf16 v[96:99], v[166:169], v[204:207], v[96:99]
	v_mfma_f32_16x16x32_bf16 v[88:91], v[158:161], v[220:223], v[88:91]
	v_mfma_f32_16x16x32_bf16 v[80:83], v[166:169], v[220:223], v[80:83]
	v_mfma_f32_16x16x32_bf16 v[72:75], v[158:161], v[228:231], v[72:75]
	v_mfma_f32_16x16x32_bf16 v[64:67], v[166:169], v[228:231], v[64:67]
	s_setprio 0
	s_setprio 1
	v_mfma_f32_16x16x32_bf16 v[124:127], v[170:173], v[186:189], v[124:127]
	v_mfma_f32_16x16x32_bf16 v[120:123], v[178:181], v[186:189], v[120:123]
	v_mfma_f32_16x16x32_bf16 v[108:111], v[170:173], v[194:197], v[108:111]
	v_mfma_f32_16x16x32_bf16 v[100:103], v[178:181], v[194:197], v[100:103]
	v_mfma_f32_16x16x32_bf16 v[92:95], v[170:173], v[208:211], v[92:95]
	v_mfma_f32_16x16x32_bf16 v[84:87], v[178:181], v[208:211], v[84:87]
	v_mfma_f32_16x16x32_bf16 v[76:79], v[170:173], v[224:227], v[76:79]
	v_mfma_f32_16x16x32_bf16 v[68:71], v[178:181], v[224:227], v[68:71]
	v_mfma_f32_16x16x32_bf16 v[124:127], v[174:177], v[190:193], v[124:127]
	v_mfma_f32_16x16x32_bf16 v[120:123], v[182:185], v[190:193], v[120:123]
	v_mfma_f32_16x16x32_bf16 v[108:111], v[174:177], v[204:207], v[108:111]
	v_mfma_f32_16x16x32_bf16 v[100:103], v[182:185], v[204:207], v[100:103]
	v_mfma_f32_16x16x32_bf16 v[92:95], v[174:177], v[220:223], v[92:95]
	v_mfma_f32_16x16x32_bf16 v[84:87], v[182:185], v[220:223], v[84:87]
	v_mfma_f32_16x16x32_bf16 v[76:79], v[174:177], v[228:231], v[76:79]
	v_mfma_f32_16x16x32_bf16 v[68:71], v[182:185], v[228:231], v[68:71]
	s_setprio 0
	s_barrier
; #define PG8_STAGE(bufoff, gbase, voff) do { _Pragma("unroll") for (int _i = 0; _i < 2; ++_i) \
;         __builtin_amdgcn_global_load_lds((const unsigned*)((const char*)(gbase) + (voff)[_i]), (PG8_LAS unsigned*)(lds + (bufoff) + ldsw + _i * 8192), 16, 0, 0); } while (0)
; #define PG8_LDA(dst, b, h) do { _Pragma("unroll") for (int m = 0; m < 4; ++m) _Pragma("unroll") for (int k = 0; k < 2; ++k) dst[m][k] = *(const PG8_LAS bf16x8*)(lds + PG8_SA(b, h) + aoff + m * 2048 + k * 1024); } while (0)
; #define PG8_MMA(ai, bj, At, Bt) do { __builtin_amdgcn_s_setprio(1); _Pragma("unroll") for (int m = 0; m < 4; ++m) _Pragma("unroll") for (int n = 0; n < 2; ++n) _Pragma("unroll") for (int k = 0; k < 2; ++k) \
;         acc[ai][bj][m][n] = __builtin_amdgcn_mfma_f32_16x16x32_bf16(Bt[n][k], At[m][k], acc[ai][bj][m][n], 0, 0, 0); __builtin_amdgcn_s_setprio(0); } while (0)
; #define PG8_WAIT_V(n) asm volatile("s_waitcnt vmcnt(" #n ")" ::: "memory")
; #define PG8_WAIT_L(n) asm volatile("s_waitcnt lgkmcnt(" #n ")" ::: "memory")
; #define PG8_BAR __builtin_amdgcn_s_barrier()
; #define PG8_SCHED __builtin_amdgcn_sched_barrier(0)
; template <class Epi, class Sched, bool ALIGN_EPI = false, bool SP2 = false>
; __device__ __forceinline__ void gemm_phase(PG8_LAS unsigned char* lds, const Gemm g, const Sched& S, const Epi& E) {
;     ...
;             PG8_LDA(At, 1, 1); PG8_STAGE(PG8_SB(1, 0), b3, voffB); PG8_STAGE(PG8_SB(1, 1), b3 + hstep, voffB); PG8_STAGE(PG8_SA(1, 0), a3, voffA);
;             PG8_WAIT_V(8); PG8_WAIT_L(0); PG8_BAR; PG8_MMA(1, 0, At, B0); PG8_MMA(1, 1, At, B1); PG8_BAR; PG8_SCHED;
;     ...
;         if constexpr (ALIGN_EPI) { if (wr == 0) PG8_BAR; }
	s_add_i32 s30, s52, s35
	v_lshl_add_u64 v[146:147], v[146:147], 0, s[10:11]
	s_mov_b32 m0, s30
	ds_read_b128 v[186:189], v152 offset:49152
	ds_read_b128 v[190:193], v152 offset:50176
	ds_read_b128 v[194:197], v152 offset:51200
	ds_read_b128 v[204:207], v152 offset:52224
	ds_read_b128 v[208:211], v152 offset:53248
	ds_read_b128 v[220:223], v152 offset:54272
	ds_read_b128 v[224:227], v152 offset:55296
	ds_read_b128 v[228:231], v152 offset:56320
	global_load_lds_dwordx4 v[146:147], off
	s_add_i32 m0, s30, 0x2000
	s_add_u32 s28, s28, 0x40080
	v_lshl_add_u64 v[146:147], v[198:199], 0, s[10:11]
	s_addc_u32 s29, s29, 0
	s_add_i32 s30, s53, s35
	global_load_lds_dwordx4 v[146:147], off
	v_lshl_add_u64 v[146:147], s[28:29], 0, v[132:133]
	s_mov_b32 m0, s30
	s_nop 0
	global_load_lds_dwordx4 v[146:147], off
	v_lshl_add_u64 v[146:147], s[28:29], 0, v[128:129]
	s_add_i32 m0, s30, 0x2000
	s_nop 0
	global_load_lds_dwordx4 v[146:147], off
	v_lshl_add_u64 v[146:147], v[232:233], 0, s[10:11]
	s_mov_b32 m0, s41
	s_nop 0
	global_load_lds_dwordx4 v[146:147], off
	v_lshl_add_u64 v[146:147], v[234:235], 0, s[10:11]
	s_mov_b32 m0, s42
	s_nop 0
	global_load_lds_dwordx4 v[146:147], off
	s_waitcnt vmcnt(8)
	s_waitcnt lgkmcnt(0)
	s_barrier
	s_setprio 1
	v_mfma_f32_16x16x32_bf16 v[56:59], v[154:157], v[186:189], v[56:59]
	v_mfma_f32_16x16x32_bf16 v[48:51], v[162:165], v[186:189], v[48:51]
	v_mfma_f32_16x16x32_bf16 v[40:43], v[154:157], v[194:197], v[40:43]
	v_mfma_f32_16x16x32_bf16 v[32:35], v[162:165], v[194:197], v[32:35]
	v_mfma_f32_16x16x32_bf16 v[24:27], v[154:157], v[208:211], v[24:27]
	v_mfma_f32_16x16x32_bf16 v[16:19], v[162:165], v[208:211], v[16:19]
	v_mfma_f32_16x16x32_bf16 v[8:11], v[154:157], v[224:227], v[8:11]
	v_mfma_f32_16x16x32_bf16 v[0:3], v[162:165], v[224:227], v[0:3]
	v_mfma_f32_16x16x32_bf16 v[56:59], v[158:161], v[190:193], v[56:59]
	v_mfma_f32_16x16x32_bf16 v[48:51], v[166:169], v[190:193], v[48:51]
	v_mfma_f32_16x16x32_bf16 v[40:43], v[158:161], v[204:207], v[40:43]
	v_mfma_f32_16x16x32_bf16 v[32:35], v[166:169], v[204:207], v[32:35]
	v_mfma_f32_16x16x32_bf16 v[24:27], v[158:161], v[220:223], v[24:27]
	v_mfma_f32_16x16x32_bf16 v[16:19], v[166:169], v[220:223], v[16:19]
	v_mfma_f32_16x16x32_bf16 v[8:11], v[158:161], v[228:231], v[8:11]
	v_mfma_f32_16x16x32_bf16 v[0:3], v[166:169], v[228:231], v[0:3]
	s_setprio 0
	s_setprio 1
	v_mfma_f32_16x16x32_bf16 v[60:63], v[170:173], v[186:189], v[60:63]
	v_mfma_f32_16x16x32_bf16 v[52:55], v[178:181], v[186:189], v[52:55]
	v_mfma_f32_16x16x32_bf16 v[44:47], v[170:173], v[194:197], v[44:47]
	v_mfma_f32_16x16x32_bf16 v[36:39], v[178:181], v[194:197], v[36:39]
	v_mfma_f32_16x16x32_bf16 v[28:31], v[170:173], v[208:211], v[28:31]
	v_mfma_f32_16x16x32_bf16 v[20:23], v[178:181], v[208:211], v[20:23]
	v_mfma_f32_16x16x32_bf16 v[12:15], v[170:173], v[224:227], v[12:15]
	v_mfma_f32_16x16x32_bf16 v[4:7], v[178:181], v[224:227], v[4:7]
	v_mfma_f32_16x16x32_bf16 v[60:63], v[174:177], v[190:193], v[60:63]
	v_mfma_f32_16x16x32_bf16 v[52:55], v[182:185], v[190:193], v[52:55]
	v_mfma_f32_16x16x32_bf16 v[44:47], v[174:177], v[204:207], v[44:47]
	v_mfma_f32_16x16x32_bf16 v[36:39], v[182:185], v[204:207], v[36:39]
	v_mfma_f32_16x16x32_bf16 v[28:31], v[174:177], v[220:223], v[28:31]
	v_mfma_f32_16x16x32_bf16 v[20:23], v[182:185], v[220:223], v[20:23]
	v_mfma_f32_16x16x32_bf16 v[12:15], v[174:177], v[228:231], v[12:15]
	v_mfma_f32_16x16x32_bf16 v[4:7], v[182:185], v[228:231], v[4:7]
	s_setprio 0
	s_barrier
	s_add_i32 s51, s51, 2
	s_add_u32 s26, s26, 0x100
	s_addc_u32 s27, s27, 0
	s_add_u32 s49, s49, 0x100
	s_addc_u32 s50, s50, 0
	s_cmp_gt_u32 s51, 13
	s_cbranch_scc0 .LBB0_708
	s_and_b64 vcc, exec, s[12:13]
	s_cbranch_vccz .LBB0_711
	s_barrier

; #define PG8_STAGE(bufoff, gbase, voff) do { _Pragma("unroll") for (int _i = 0; _i < 2; ++_i) \
;         __builtin_amdgcn_global_load_lds((const unsigned*)((const char*)(gbase) + (voff)[_i]), (PG8_LAS unsigned*)(lds + (bufoff) + ldsw + _i * 8192), 16, 0, 0); } while (0)
; #define PG8_LDA(dst, b, h) do { _Pragma("unroll") for (int m = 0; m < 4; ++m) _Pragma("unroll") for (int k = 0; k < 2; ++k) dst[m][k] = *(const PG8_LAS bf16x8*)(lds + PG8_SA(b, h) + aoff + m * 2048 + k * 1024); } while (0)
; #define PG8_LDB(dst, b, h) do { _Pragma("unroll") for (int n = 0; n < 2; ++n) _Pragma("unroll") for (int k = 0; k < 2; ++k) dst[n][k] = *(const PG8_LAS bf16x8*)(lds + PG8_SB(b, h) + boff + n * 2048 + k * 1024); } while (0)
; #define PG8_MMA(ai, bj, At, Bt) do { __builtin_amdgcn_s_setprio(1); _Pragma("unroll") for (int m = 0; m < 4; ++m) _Pragma("unroll") for (int n = 0; n < 2; ++n) _Pragma("unroll") for (int k = 0; k < 2; ++k) \
;         acc[ai][bj][m][n] = __builtin_amdgcn_mfma_f32_16x16x32_bf16(Bt[n][k], At[m][k], acc[ai][bj][m][n], 0, 0, 0); __builtin_amdgcn_s_setprio(0); } while (0)
; #define PG8_WAIT_V(n) asm volatile("s_waitcnt vmcnt(" #n ")" ::: "memory")
; #define PG8_WAIT_L(n) asm volatile("s_waitcnt lgkmcnt(" #n ")" ::: "memory")
; #define PG8_BAR __builtin_amdgcn_s_barrier()
; #define PG8_SCHED __builtin_amdgcn_sched_barrier(0)
; template <class Epi, class Sched, bool ALIGN_EPI = false, bool SP2 = false>
; __device__ __forceinline__ void gemm_phase(PG8_LAS unsigned char* lds, const Gemm g, const Sched& S, const Epi& E) {
;     ...
;         for (int t = 0; t < nt; t += 2) {
;             const bool last = (t == nt - 2);
;             const char* a1 = cA + (size_t)(t + 1) * kstep;
;             const char* a2 = last ? nA : cA + (size_t)(t + 2) * kstep; const char* b2 = last ? nB : cB + (size_t)(t + 2) * kstep;
;             const char* a3 = a2 + kstep; const char* b3 = b2 + kstep;
;             if (last && has_next) S.a_ready(nxt);
;             if constexpr (SP2) {
;             PG8_LDB(B0, 0, 0); PG8_LDB(B1, 0, 1); PG8_SCHED; PG8_LDA(At, 0, 0); PG8_STAGE(PG8_SA(1, 1), a1 + hstep, voffA);
;             PG8_WAIT_V(8); PG8_WAIT_L(0); PG8_BAR; PG8_MMA(0, 0, At, B0); PG8_MMA(0, 1, At, B1); PG8_BAR; PG8_SCHED;
;             PG8_LDA(At, 0, 1); PG8_STAGE(PG8_SB(0, 0), b2, voffB); PG8_STAGE(PG8_SB(0, 1), b2 + hstep, voffB); PG8_STAGE(PG8_SA(0, 0), a2, voffA);
.LBB0_790:
	ds_read_b128 v[128:131], v220
	ds_read_b128 v[132:135], v220 offset:1024
	ds_read_b128 v[136:139], v220 offset:2048
	ds_read_b128 v[140:143], v220 offset:3072
	ds_read_b128 v[144:147], v221
	ds_read_b128 v[148:151], v221 offset:1024
	ds_read_b128 v[152:155], v221 offset:2048
	ds_read_b128 v[156:159], v221 offset:3072
	s_add_u32 s24, s22, 0x100
	s_addc_u32 s25, s23, 0
	s_cmp_eq_u32 s49, 40
	s_cselect_b32 s29, s1, s25
	s_cselect_b32 s28, s0, s24
	s_cselect_b32 s27, s19, s48
	s_cselect_b32 s26, s18, s47
	v_lshl_add_u64 v[228:229], s[22:23], 0, v[188:189]
	s_add_i32 m0, s34, 0xc000
	ds_read_b128 v[160:163], v222
	ds_read_b128 v[164:167], v222 offset:1024
	ds_read_b128 v[168:171], v222 offset:2048
	ds_read_b128 v[172:175], v222 offset:3072
	ds_read_b128 v[196:199], v222 offset:4096
	ds_read_b128 v[204:207], v222 offset:5120
	ds_read_b128 v[208:211], v222 offset:6144
	ds_read_b128 v[224:227], v222 offset:7168
	global_load_lds_dwordx4 v[228:229], off
	v_lshl_add_u64 v[228:229], s[22:23], 0, v[190:191]
	s_add_i32 m0, s34, 0xe000
	s_nop 0
	global_load_lds_dwordx4 v[228:229], off
	s_waitcnt vmcnt(8)
	s_waitcnt lgkmcnt(0)
	s_barrier
	s_setprio 1
	v_mfma_f32_16x16x32_bf16 v[124:127], v[128:131], v[160:163], v[124:127]
	v_mfma_f32_16x16x32_bf16 v[120:123], v[136:139], v[160:163], v[120:123]
	v_mfma_f32_16x16x32_bf16 v[108:111], v[128:131], v[168:171], v[108:111]
	v_mfma_f32_16x16x32_bf16 v[104:107], v[136:139], v[168:171], v[104:107]
	v_mfma_f32_16x16x32_bf16 v[92:95], v[128:131], v[196:199], v[92:95]
	v_mfma_f32_16x16x32_bf16 v[88:91], v[136:139], v[196:199], v[88:91]
	v_mfma_f32_16x16x32_bf16 v[76:79], v[128:131], v[208:211], v[76:79]
	v_mfma_f32_16x16x32_bf16 v[72:75], v[136:139], v[208:211], v[72:75]
	v_mfma_f32_16x16x32_bf16 v[124:127], v[132:135], v[164:167], v[124:127]
	v_mfma_f32_16x16x32_bf16 v[120:123], v[140:143], v[164:167], v[120:123]
	v_mfma_f32_16x16x32_bf16 v[108:111], v[132:135], v[172:175], v[108:111]
	v_mfma_f32_16x16x32_bf16 v[104:107], v[140:143], v[172:175], v[104:107]
	v_mfma_f32_16x16x32_bf16 v[92:95], v[132:135], v[204:207], v[92:95]
	v_mfma_f32_16x16x32_bf16 v[88:91], v[140:143], v[204:207], v[88:91]
	v_mfma_f32_16x16x32_bf16 v[76:79], v[132:135], v[224:227], v[76:79]
	v_mfma_f32_16x16x32_bf16 v[72:75], v[140:143], v[224:227], v[72:75]
	s_setprio 0
	s_setprio 1
	v_mfma_f32_16x16x32_bf16 v[116:119], v[144:147], v[160:163], v[116:119]
	v_mfma_f32_16x16x32_bf16 v[112:115], v[152:155], v[160:163], v[112:115]
	v_mfma_f32_16x16x32_bf16 v[100:103], v[144:147], v[168:171], v[100:103]
	v_mfma_f32_16x16x32_bf16 v[96:99], v[152:155], v[168:171], v[96:99]
	v_mfma_f32_16x16x32_bf16 v[84:87], v[144:147], v[196:199], v[84:87]
	v_mfma_f32_16x16x32_bf16 v[80:83], v[152:155], v[196:199], v[80:83]
	v_mfma_f32_16x16x32_bf16 v[68:71], v[144:147], v[208:211], v[68:71]
	v_mfma_f32_16x16x32_bf16 v[64:67], v[152:155], v[208:211], v[64:67]
	v_mfma_f32_16x16x32_bf16 v[116:119], v[148:151], v[164:167], v[116:119]
	v_mfma_f32_16x16x32_bf16 v[112:115], v[156:159], v[164:167], v[112:115]
	v_mfma_f32_16x16x32_bf16 v[100:103], v[148:151], v[172:175], v[100:103]
	v_mfma_f32_16x16x32_bf16 v[96:99], v[156:159], v[172:175], v[96:99]
	v_mfma_f32_16x16x32_bf16 v[84:87], v[148:151], v[204:207], v[84:87]
	v_mfma_f32_16x16x32_bf16 v[80:83], v[156:159], v[204:207], v[80:83]
	v_mfma_f32_16x16x32_bf16 v[68:71], v[148:151], v[224:227], v[68:71]
	v_mfma_f32_16x16x32_bf16 v[64:67], v[156:159], v[224:227], v[64:67]
	s_setprio 0
	s_barrier
	s_add_i32 s22, s43, s33
	v_lshl_add_u64 v[228:229], s[26:27], 0, v[178:179]
	s_mov_b32 m0, s22
	ds_read_b128 v[160:163], v222 offset:16384
	ds_read_b128 v[164:167], v222 offset:17408
	ds_read_b128 v[168:171], v222 offset:18432
	ds_read_b128 v[172:175], v222 offset:19456
	ds_read_b128 v[196:199], v222 offset:20480
	ds_read_b128 v[204:207], v222 offset:21504
	ds_read_b128 v[208:211], v222 offset:22528
	ds_read_b128 v[224:227], v222 offset:23552
	global_load_lds_dwordx4 v[228:229], off
	s_add_i32 m0, s22, 0x2000
	s_add_u32 s22, s26, 0xb0000
	v_lshl_add_u64 v[230:231], s[26:27], 0, v[182:183]
	s_addc_u32 s23, s27, 0
	s_add_i32 s50, s44, s33
	global_load_lds_dwordx4 v[230:231], off
	v_lshl_add_u64 v[232:233], s[22:23], 0, v[178:179]
	s_mov_b32 m0, s50
	v_lshl_add_u64 v[234:235], s[28:29], 0, v[180:181]
	global_load_lds_dwordx4 v[232:233], off
	v_lshl_add_u64 v[232:233], s[22:23], 0, v[182:183]
	s_add_i32 m0, s50, 0x2000
	s_nop 0
	global_load_lds_dwordx4 v[232:233], off
	v_lshl_add_u64 v[232:233], s[28:29], 0, v[176:177]
	s_mov_b32 m0, s34
	s_nop 0
	global_load_lds_dwordx4 v[232:233], off
	s_mov_b32 m0, s35
	s_nop 0
	global_load_lds_dwordx4 v[234:235], off
	s_waitcnt vmcnt(8)
	s_waitcnt lgkmcnt(0)
	s_barrier
; #define PG8_STAGE(bufoff, gbase, voff) do { _Pragma("unroll") for (int _i = 0; _i < 2; ++_i) \
;         __builtin_amdgcn_global_load_lds((const unsigned*)((const char*)(gbase) + (voff)[_i]), (PG8_LAS unsigned*)(lds + (bufoff) + ldsw + _i * 8192), 16, 0, 0); } while (0)
; #define PG8_LDA(dst, b, h) do { _Pragma("unroll") for (int m = 0; m < 4; ++m) _Pragma("unroll") for (int k = 0; k < 2; ++k) dst[m][k] = *(const PG8_LAS bf16x8*)(lds + PG8_SA(b, h) + aoff + m * 2048 + k * 1024); } while (0)
; #define PG8_LDB(dst, b, h) do { _Pragma("unroll") for (int n = 0; n < 2; ++n) _Pragma("unroll") for (int k = 0; k < 2; ++k) dst[n][k] = *(const PG8_LAS bf16x8*)(lds + PG8_SB(b, h) + boff + n * 2048 + k * 1024); } while (0)
; #define PG8_MMA(ai, bj, At, Bt) do { __builtin_amdgcn_s_setprio(1); _Pragma("unroll") for (int m = 0; m < 4; ++m) _Pragma("unroll") for (int n = 0; n < 2; ++n) _Pragma("unroll") for (int k = 0; k < 2; ++k) \
;         acc[ai][bj][m][n] = __builtin_amdgcn_mfma_f32_16x16x32_bf16(Bt[n][k], At[m][k], acc[ai][bj][m][n], 0, 0, 0); __builtin_amdgcn_s_setprio(0); } while (0)
; #define PG8_WAIT_V(n) asm volatile("s_waitcnt vmcnt(" #n ")" ::: "memory")
; #define PG8_WAIT_L(n) asm volatile("s_waitcnt lgkmcnt(" #n ")" ::: "memory")
; #define PG8_BAR __builtin_amdgcn_s_barrier()
; #define PG8_SCHED __builtin_amdgcn_sched_barrier(0)
; template <class Epi, class Sched, bool ALIGN_EPI = false, bool SP2 = false>
; __device__ __forceinline__ void gemm_phase(PG8_LAS unsigned char* lds, const Gemm g, const Sched& S, const Epi& E) {
;     ...
;             PG8_WAIT_V(8); PG8_WAIT_L(0); PG8_BAR; PG8_MMA(1, 0, At, B0); PG8_MMA(1, 1, At, B1); PG8_BAR; PG8_SCHED;
;             PG8_LDB(B0, 1, 0); PG8_LDB(B1, 1, 1); PG8_SCHED; PG8_LDA(At, 1, 0); PG8_STAGE(PG8_SA(0, 1), a2 + hstep, voffA);
;             PG8_WAIT_V(8); PG8_WAIT_L(0); PG8_BAR; PG8_MMA(0, 0, At, B0); PG8_MMA(0, 1, At, B1); PG8_BAR; PG8_SCHED;
	s_setprio 1
	v_mfma_f32_16x16x32_bf16 v[60:63], v[128:131], v[160:163], v[60:63]
	v_mfma_f32_16x16x32_bf16 v[56:59], v[136:139], v[160:163], v[56:59]
	v_mfma_f32_16x16x32_bf16 v[44:47], v[128:131], v[168:171], v[44:47]
	v_mfma_f32_16x16x32_bf16 v[40:43], v[136:139], v[168:171], v[40:43]
	v_mfma_f32_16x16x32_bf16 v[28:31], v[128:131], v[196:199], v[28:31]
	v_mfma_f32_16x16x32_bf16 v[24:27], v[136:139], v[196:199], v[24:27]
	v_mfma_f32_16x16x32_bf16 v[12:15], v[128:131], v[208:211], v[12:15]
	v_mfma_f32_16x16x32_bf16 v[8:11], v[136:139], v[208:211], v[8:11]
	v_mfma_f32_16x16x32_bf16 v[60:63], v[132:135], v[164:167], v[60:63]
	v_mfma_f32_16x16x32_bf16 v[56:59], v[140:143], v[164:167], v[56:59]
	v_mfma_f32_16x16x32_bf16 v[44:47], v[132:135], v[172:175], v[44:47]
	v_mfma_f32_16x16x32_bf16 v[40:43], v[140:143], v[172:175], v[40:43]
	v_mfma_f32_16x16x32_bf16 v[28:31], v[132:135], v[204:207], v[28:31]
	v_mfma_f32_16x16x32_bf16 v[24:27], v[140:143], v[204:207], v[24:27]
	v_mfma_f32_16x16x32_bf16 v[12:15], v[132:135], v[224:227], v[12:15]
	v_mfma_f32_16x16x32_bf16 v[8:11], v[140:143], v[224:227], v[8:11]
	s_setprio 0
	s_setprio 1
	v_mfma_f32_16x16x32_bf16 v[52:55], v[144:147], v[160:163], v[52:55]
	v_mfma_f32_16x16x32_bf16 v[48:51], v[152:155], v[160:163], v[48:51]
	v_mfma_f32_16x16x32_bf16 v[36:39], v[144:147], v[168:171], v[36:39]
	v_mfma_f32_16x16x32_bf16 v[32:35], v[152:155], v[168:171], v[32:35]
	v_mfma_f32_16x16x32_bf16 v[20:23], v[144:147], v[196:199], v[20:23]
	v_mfma_f32_16x16x32_bf16 v[16:19], v[152:155], v[196:199], v[16:19]
	v_mfma_f32_16x16x32_bf16 v[4:7], v[144:147], v[208:211], v[4:7]
	v_mfma_f32_16x16x32_bf16 v[0:3], v[152:155], v[208:211], v[0:3]
	v_mfma_f32_16x16x32_bf16 v[52:55], v[148:151], v[164:167], v[52:55]
	v_mfma_f32_16x16x32_bf16 v[48:51], v[156:159], v[164:167], v[48:51]
	v_mfma_f32_16x16x32_bf16 v[36:39], v[148:151], v[172:175], v[36:39]
	v_mfma_f32_16x16x32_bf16 v[32:35], v[156:159], v[172:175], v[32:35]
	v_mfma_f32_16x16x32_bf16 v[20:23], v[148:151], v[204:207], v[20:23]
	v_mfma_f32_16x16x32_bf16 v[16:19], v[156:159], v[204:207], v[16:19]
	v_mfma_f32_16x16x32_bf16 v[4:7], v[148:151], v[224:227], v[4:7]
	v_mfma_f32_16x16x32_bf16 v[0:3], v[156:159], v[224:227], v[0:3]
	s_setprio 0
	s_barrier
	s_add_i32 s50, 0, 0x18000
	s_add_i32 s51, 0, 0x1c000
	v_add_u32_e32 v140, s50, v201
	v_add_u32_e32 v156, s51, v201
	ds_read_b128 v[128:131], v140
	ds_read_b128 v[132:135], v140 offset:1024
	ds_read_b128 v[136:139], v140 offset:2048
	ds_read_b128 v[140:143], v140 offset:3072
	ds_read_b128 v[144:147], v156
	ds_read_b128 v[148:151], v156 offset:1024
	ds_read_b128 v[152:155], v156 offset:2048
	ds_read_b128 v[156:159], v156 offset:3072
	s_add_u32 s22, s28, 0xb0000
	s_addc_u32 s23, s29, 0
	s_mov_b32 m0, s36
	v_lshl_add_u64 v[236:237], s[22:23], 0, v[176:177]
	ds_read_b128 v[160:163], v222 offset:32768
	ds_read_b128 v[164:167], v222 offset:33792
	ds_read_b128 v[168:171], v222 offset:34816
	ds_read_b128 v[172:175], v222 offset:35840
	ds_read_b128 v[196:199], v222 offset:36864
	ds_read_b128 v[204:207], v222 offset:37888
	ds_read_b128 v[208:211], v222 offset:38912
	ds_read_b128 v[224:227], v222 offset:39936
	global_load_lds_dwordx4 v[236:237], off
	v_lshl_add_u64 v[236:237], s[22:23], 0, v[180:181]
	s_mov_b32 m0, s37
	s_nop 0
	global_load_lds_dwordx4 v[236:237], off
	s_waitcnt vmcnt(8)
	s_waitcnt lgkmcnt(0)
	s_barrier
	s_setprio 1
	v_mfma_f32_16x16x32_bf16 v[124:127], v[128:131], v[160:163], v[124:127]
	v_mfma_f32_16x16x32_bf16 v[120:123], v[136:139], v[160:163], v[120:123]
	v_mfma_f32_16x16x32_bf16 v[108:111], v[128:131], v[168:171], v[108:111]
	v_mfma_f32_16x16x32_bf16 v[104:107], v[136:139], v[168:171], v[104:107]
	v_mfma_f32_16x16x32_bf16 v[92:95], v[128:131], v[196:199], v[92:95]
	v_mfma_f32_16x16x32_bf16 v[88:91], v[136:139], v[196:199], v[88:91]
	v_mfma_f32_16x16x32_bf16 v[76:79], v[128:131], v[208:211], v[76:79]
	v_mfma_f32_16x16x32_bf16 v[72:75], v[136:139], v[208:211], v[72:75]
	v_mfma_f32_16x16x32_bf16 v[124:127], v[132:135], v[164:167], v[124:127]
	v_mfma_f32_16x16x32_bf16 v[120:123], v[140:143], v[164:167], v[120:123]
	v_mfma_f32_16x16x32_bf16 v[108:111], v[132:135], v[172:175], v[108:111]
	v_mfma_f32_16x16x32_bf16 v[104:107], v[140:143], v[172:175], v[104:107]
	v_mfma_f32_16x16x32_bf16 v[92:95], v[132:135], v[204:207], v[92:95]
	v_mfma_f32_16x16x32_bf16 v[88:91], v[140:143], v[204:207], v[88:91]
	v_mfma_f32_16x16x32_bf16 v[76:79], v[132:135], v[224:227], v[76:79]
	v_mfma_f32_16x16x32_bf16 v[72:75], v[140:143], v[224:227], v[72:75]
	s_setprio 0
	s_setprio 1
	v_mfma_f32_16x16x32_bf16 v[116:119], v[144:147], v[160:163], v[116:119]
	v_mfma_f32_16x16x32_bf16 v[112:115], v[152:155], v[160:163], v[112:115]
	v_mfma_f32_16x16x32_bf16 v[100:103], v[144:147], v[168:171], v[100:103]
	v_mfma_f32_16x16x32_bf16 v[96:99], v[152:155], v[168:171], v[96:99]
	v_mfma_f32_16x16x32_bf16 v[84:87], v[144:147], v[196:199], v[84:87]
	v_mfma_f32_16x16x32_bf16 v[80:83], v[152:155], v[196:199], v[80:83]
	v_mfma_f32_16x16x32_bf16 v[68:71], v[144:147], v[208:211], v[68:71]
	v_mfma_f32_16x16x32_bf16 v[64:67], v[152:155], v[208:211], v[64:67]
	v_mfma_f32_16x16x32_bf16 v[116:119], v[148:151], v[164:167], v[116:119]
	v_mfma_f32_16x16x32_bf16 v[112:115], v[156:159], v[164:167], v[112:115]
	v_mfma_f32_16x16x32_bf16 v[100:103], v[148:151], v[172:175], v[100:103]
	v_mfma_f32_16x16x32_bf16 v[96:99], v[156:159], v[172:175], v[96:99]
	v_mfma_f32_16x16x32_bf16 v[84:87], v[148:151], v[204:207], v[84:87]
	v_mfma_f32_16x16x32_bf16 v[80:83], v[156:159], v[204:207], v[80:83]
	v_mfma_f32_16x16x32_bf16 v[68:71], v[148:151], v[224:227], v[68:71]
	v_mfma_f32_16x16x32_bf16 v[64:67], v[156:159], v[224:227], v[64:67]
	s_setprio 0
	s_barrier
; #define PG8_STAGE(bufoff, gbase, voff) do { _Pragma("unroll") for (int _i = 0; _i < 2; ++_i) \
;         __builtin_amdgcn_global_load_lds((const unsigned*)((const char*)(gbase) + (voff)[_i]), (PG8_LAS unsigned*)(lds + (bufoff) + ldsw + _i * 8192), 16, 0, 0); } while (0)
; #define PG8_LDA(dst, b, h) do { _Pragma("unroll") for (int m = 0; m < 4; ++m) _Pragma("unroll") for (int k = 0; k < 2; ++k) dst[m][k] = *(const PG8_LAS bf16x8*)(lds + PG8_SA(b, h) + aoff + m * 2048 + k * 1024); } while (0)
; #define PG8_MMA(ai, bj, At, Bt) do { __builtin_amdgcn_s_setprio(1); _Pragma("unroll") for (int m = 0; m < 4; ++m) _Pragma("unroll") for (int n = 0; n < 2; ++n) _Pragma("unroll") for (int k = 0; k < 2; ++k) \
;         acc[ai][bj][m][n] = __builtin_amdgcn_mfma_f32_16x16x32_bf16(Bt[n][k], At[m][k], acc[ai][bj][m][n], 0, 0, 0); __builtin_amdgcn_s_setprio(0); } while (0)
; #define PG8_WAIT_V(n) asm volatile("s_waitcnt vmcnt(" #n ")" ::: "memory")
; #define PG8_WAIT_L(n) asm volatile("s_waitcnt lgkmcnt(" #n ")" ::: "memory")
; #define PG8_BAR __builtin_amdgcn_s_barrier()
; #define PG8_SCHED __builtin_amdgcn_sched_barrier(0)
; template <class Epi, class Sched, bool ALIGN_EPI = false, bool SP2 = false>
; __device__ __forceinline__ void gemm_phase(PG8_LAS unsigned char* lds, const Gemm g, const Sched& S, const Epi& E) {
;     ...
;             PG8_LDA(At, 1, 1); PG8_STAGE(PG8_SB(1, 0), b3, voffB); PG8_STAGE(PG8_SB(1, 1), b3 + hstep, voffB); PG8_STAGE(PG8_SA(1, 0), a3, voffA);
;             PG8_WAIT_V(8); PG8_WAIT_L(0); PG8_BAR; PG8_MMA(1, 0, At, B0); PG8_MMA(1, 1, At, B1); PG8_BAR; PG8_SCHED;
;     ...
;         if constexpr (ALIGN_EPI) { if (wr == 0) PG8_BAR; }
	s_add_i32 s22, s50, s33
	v_lshl_add_u64 v[228:229], v[228:229], 0, s[14:15]
	s_mov_b32 m0, s22
	ds_read_b128 v[160:163], v222 offset:49152
	ds_read_b128 v[164:167], v222 offset:50176
	ds_read_b128 v[168:171], v222 offset:51200
	ds_read_b128 v[172:175], v222 offset:52224
	ds_read_b128 v[196:199], v222 offset:53248
	ds_read_b128 v[204:207], v222 offset:54272
	ds_read_b128 v[208:211], v222 offset:55296
	ds_read_b128 v[224:227], v222 offset:56320
	global_load_lds_dwordx4 v[228:229], off
	s_add_i32 m0, s22, 0x2000
	s_add_u32 s22, s26, 0xb0080
	v_lshl_add_u64 v[228:229], v[230:231], 0, s[14:15]
	s_addc_u32 s23, s27, 0
	s_add_i32 s26, s51, s33
	global_load_lds_dwordx4 v[228:229], off
	v_lshl_add_u64 v[228:229], s[22:23], 0, v[178:179]
	s_mov_b32 m0, s26
	s_nop 0
	global_load_lds_dwordx4 v[228:229], off
	v_lshl_add_u64 v[228:229], s[22:23], 0, v[182:183]
	s_add_i32 m0, s26, 0x2000
	s_nop 0
	global_load_lds_dwordx4 v[228:229], off
	v_lshl_add_u64 v[228:229], v[232:233], 0, s[14:15]
	s_mov_b32 m0, s39
	s_nop 0
	global_load_lds_dwordx4 v[228:229], off
	v_lshl_add_u64 v[228:229], v[234:235], 0, s[14:15]
	s_mov_b32 m0, s40
	s_nop 0
	global_load_lds_dwordx4 v[228:229], off
	s_waitcnt vmcnt(8)
	s_waitcnt lgkmcnt(0)
	s_barrier
	s_setprio 1
	v_mfma_f32_16x16x32_bf16 v[60:63], v[128:131], v[160:163], v[60:63]
	v_mfma_f32_16x16x32_bf16 v[56:59], v[136:139], v[160:163], v[56:59]
	v_mfma_f32_16x16x32_bf16 v[44:47], v[128:131], v[168:171], v[44:47]
	v_mfma_f32_16x16x32_bf16 v[40:43], v[136:139], v[168:171], v[40:43]
	v_mfma_f32_16x16x32_bf16 v[28:31], v[128:131], v[196:199], v[28:31]
	v_mfma_f32_16x16x32_bf16 v[24:27], v[136:139], v[196:199], v[24:27]
	v_mfma_f32_16x16x32_bf16 v[12:15], v[128:131], v[208:211], v[12:15]
	v_mfma_f32_16x16x32_bf16 v[8:11], v[136:139], v[208:211], v[8:11]
	v_mfma_f32_16x16x32_bf16 v[60:63], v[132:135], v[164:167], v[60:63]
	v_mfma_f32_16x16x32_bf16 v[56:59], v[140:143], v[164:167], v[56:59]
	v_mfma_f32_16x16x32_bf16 v[44:47], v[132:135], v[172:175], v[44:47]
	v_mfma_f32_16x16x32_bf16 v[40:43], v[140:143], v[172:175], v[40:43]
	v_mfma_f32_16x16x32_bf16 v[28:31], v[132:135], v[204:207], v[28:31]
	v_mfma_f32_16x16x32_bf16 v[24:27], v[140:143], v[204:207], v[24:27]
	v_mfma_f32_16x16x32_bf16 v[12:15], v[132:135], v[224:227], v[12:15]
	v_mfma_f32_16x16x32_bf16 v[8:11], v[140:143], v[224:227], v[8:11]
	s_setprio 0
	s_setprio 1
	v_mfma_f32_16x16x32_bf16 v[52:55], v[144:147], v[160:163], v[52:55]
	v_mfma_f32_16x16x32_bf16 v[48:51], v[152:155], v[160:163], v[48:51]
	v_mfma_f32_16x16x32_bf16 v[36:39], v[144:147], v[168:171], v[36:39]
	v_mfma_f32_16x16x32_bf16 v[32:35], v[152:155], v[168:171], v[32:35]
	v_mfma_f32_16x16x32_bf16 v[20:23], v[144:147], v[196:199], v[20:23]
	v_mfma_f32_16x16x32_bf16 v[16:19], v[152:155], v[196:199], v[16:19]
	v_mfma_f32_16x16x32_bf16 v[4:7], v[144:147], v[208:211], v[4:7]
	v_mfma_f32_16x16x32_bf16 v[0:3], v[152:155], v[208:211], v[0:3]
	v_mfma_f32_16x16x32_bf16 v[52:55], v[148:151], v[164:167], v[52:55]
	v_mfma_f32_16x16x32_bf16 v[48:51], v[156:159], v[164:167], v[48:51]
	v_mfma_f32_16x16x32_bf16 v[36:39], v[148:151], v[172:175], v[36:39]
	v_mfma_f32_16x16x32_bf16 v[32:35], v[156:159], v[172:175], v[32:35]
	v_mfma_f32_16x16x32_bf16 v[20:23], v[148:151], v[204:207], v[20:23]
	v_mfma_f32_16x16x32_bf16 v[16:19], v[156:159], v[204:207], v[16:19]
	v_mfma_f32_16x16x32_bf16 v[4:7], v[148:151], v[224:227], v[4:7]
	v_mfma_f32_16x16x32_bf16 v[0:3], v[156:159], v[224:227], v[0:3]
	s_setprio 0
	s_barrier
	s_add_i32 s49, s49, 2
	s_add_u32 s47, s47, 0x100
	s_addc_u32 s48, s48, 0
	s_cmp_gt_u32 s49, 41
	s_mov_b64 s[22:23], s[24:25]
	s_cbranch_scc0 .LBB0_790
	s_and_b64 vcc, exec, s[16:17]
	s_cbranch_vccz .LBB0_793
	s_barrier

; #define PG8_STAGE(bufoff, gbase, voff) do { _Pragma("unroll") for (int _i = 0; _i < 2; ++_i) \
;         __builtin_amdgcn_global_load_lds((const unsigned*)((const char*)(gbase) + (voff)[_i]), (PG8_LAS unsigned*)(lds + (bufoff) + ldsw + _i * 8192), 16, 0, 0); } while (0)
; #define PG8_LDA(dst, b, h) do { _Pragma("unroll") for (int m = 0; m < 4; ++m) _Pragma("unroll") for (int k = 0; k < 2; ++k) dst[m][k] = *(const PG8_LAS bf16x8*)(lds + PG8_SA(b, h) + aoff + m * 2048 + k * 1024); } while (0)
; #define PG8_LDB(dst, b, h) do { _Pragma("unroll") for (int n = 0; n < 2; ++n) _Pragma("unroll") for (int k = 0; k < 2; ++k) dst[n][k] = *(const PG8_LAS bf16x8*)(lds + PG8_SB(b, h) + boff + n * 2048 + k * 1024); } while (0)
; #define PG8_MMA(ai, bj, At, Bt) do { __builtin_amdgcn_s_setprio(1); _Pragma("unroll") for (int m = 0; m < 4; ++m) _Pragma("unroll") for (int n = 0; n < 2; ++n) _Pragma("unroll") for (int k = 0; k < 2; ++k) \
;         acc[ai][bj][m][n] = __builtin_amdgcn_mfma_f32_16x16x32_bf16(Bt[n][k], At[m][k], acc[ai][bj][m][n], 0, 0, 0); __builtin_amdgcn_s_setprio(0); } while (0)
; #define PG8_WAIT_V(n) asm volatile("s_waitcnt vmcnt(" #n ")" ::: "memory")
; #define PG8_WAIT_L(n) asm volatile("s_waitcnt lgkmcnt(" #n ")" ::: "memory")
; #define PG8_BAR __builtin_amdgcn_s_barrier()
; #define PG8_SCHED __builtin_amdgcn_sched_barrier(0)
; template <class Epi, class Sched, bool ALIGN_EPI = false, bool SP2 = false>
; __device__ __forceinline__ void gemm_phase(PG8_LAS unsigned char* lds, const Gemm g, const Sched& S, const Epi& E) {
;     ...
;         for (int t = 0; t < nt; t += 2) {
;             const bool last = (t == nt - 2);
;             const char* a1 = cA + (size_t)(t + 1) * kstep;
;             const char* a2 = last ? nA : cA + (size_t)(t + 2) * kstep; const char* b2 = last ? nB : cB + (size_t)(t + 2) * kstep;
;             const char* a3 = a2 + kstep; const char* b3 = b2 + kstep;
;             if (last && has_next) S.a_ready(nxt);
;             if constexpr (SP2) {
;             PG8_LDB(B0, 0, 0); PG8_LDB(B1, 0, 1); PG8_SCHED; PG8_LDA(At, 0, 0); PG8_STAGE(PG8_SA(1, 1), a1 + hstep, voffA);
;             PG8_WAIT_V(8); PG8_WAIT_L(0); PG8_BAR; PG8_MMA(0, 0, At, B0); PG8_MMA(0, 1, At, B1); PG8_BAR; PG8_SCHED;
;             PG8_LDA(At, 0, 1); PG8_STAGE(PG8_SB(0, 0), b2, voffB); PG8_STAGE(PG8_SB(0, 1), b2 + hstep, voffB); PG8_STAGE(PG8_SA(0, 0), a2, voffA);
.LBB0_876:
	ds_read_b128 v[158:161], v154
	ds_read_b128 v[162:165], v154 offset:1024
	ds_read_b128 v[166:169], v154 offset:2048
	ds_read_b128 v[170:173], v154 offset:3072
	ds_read_b128 v[174:177], v155
	ds_read_b128 v[178:181], v155 offset:1024
	ds_read_b128 v[182:185], v155 offset:2048
	ds_read_b128 v[186:189], v155 offset:3072
	s_add_u32 s34, s22, 0xfffc0080
	s_addc_u32 s35, s23, -1
	s_cmp_eq_u32 s39, 12
	s_cselect_b32 s37, s2, s35
	s_cselect_b32 s36, s3, s34
	s_cselect_b32 s35, s9, s38
	s_cselect_b32 s34, s25, s27
	v_lshl_add_u64 v[148:149], s[22:23], 0, v[140:141]
	s_add_i32 m0, s42, 0xc000
	ds_read_b128 v[190:193], v156
	ds_read_b128 v[194:197], v156 offset:1024
	ds_read_b128 v[204:207], v156 offset:2048
	ds_read_b128 v[208:211], v156 offset:3072
	ds_read_b128 v[220:223], v156 offset:4096
	ds_read_b128 v[224:227], v156 offset:5120
	ds_read_b128 v[228:231], v156 offset:6144
	ds_read_b128 v[232:235], v156 offset:7168
	global_load_lds_dwordx4 v[148:149], off
	v_lshl_add_u64 v[148:149], s[22:23], 0, v[142:143]
	s_add_i32 m0, s42, 0xe000
	s_nop 0
	global_load_lds_dwordx4 v[148:149], off
	s_waitcnt vmcnt(8)
	s_waitcnt lgkmcnt(0)
	s_barrier
	s_setprio 1
	v_mfma_f32_16x16x32_bf16 v[124:127], v[158:161], v[190:193], v[124:127]
	v_mfma_f32_16x16x32_bf16 v[120:123], v[166:169], v[190:193], v[120:123]
	v_mfma_f32_16x16x32_bf16 v[108:111], v[158:161], v[204:207], v[108:111]
	v_mfma_f32_16x16x32_bf16 v[104:107], v[166:169], v[204:207], v[104:107]
	v_mfma_f32_16x16x32_bf16 v[92:95], v[158:161], v[220:223], v[92:95]
	v_mfma_f32_16x16x32_bf16 v[88:91], v[166:169], v[220:223], v[88:91]
	v_mfma_f32_16x16x32_bf16 v[76:79], v[158:161], v[228:231], v[76:79]
	v_mfma_f32_16x16x32_bf16 v[72:75], v[166:169], v[228:231], v[72:75]
	v_mfma_f32_16x16x32_bf16 v[124:127], v[162:165], v[194:197], v[124:127]
	v_mfma_f32_16x16x32_bf16 v[120:123], v[170:173], v[194:197], v[120:123]
	v_mfma_f32_16x16x32_bf16 v[108:111], v[162:165], v[208:211], v[108:111]
	v_mfma_f32_16x16x32_bf16 v[104:107], v[170:173], v[208:211], v[104:107]
	v_mfma_f32_16x16x32_bf16 v[92:95], v[162:165], v[224:227], v[92:95]
	v_mfma_f32_16x16x32_bf16 v[88:91], v[170:173], v[224:227], v[88:91]
	v_mfma_f32_16x16x32_bf16 v[76:79], v[162:165], v[232:235], v[76:79]
	v_mfma_f32_16x16x32_bf16 v[72:75], v[170:173], v[232:235], v[72:75]
	s_setprio 0
	s_setprio 1
	v_mfma_f32_16x16x32_bf16 v[116:119], v[174:177], v[190:193], v[116:119]
	v_mfma_f32_16x16x32_bf16 v[112:115], v[182:185], v[190:193], v[112:115]
	v_mfma_f32_16x16x32_bf16 v[100:103], v[174:177], v[204:207], v[100:103]
	v_mfma_f32_16x16x32_bf16 v[96:99], v[182:185], v[204:207], v[96:99]
	v_mfma_f32_16x16x32_bf16 v[84:87], v[174:177], v[220:223], v[84:87]
	v_mfma_f32_16x16x32_bf16 v[80:83], v[182:185], v[220:223], v[80:83]
	v_mfma_f32_16x16x32_bf16 v[68:71], v[174:177], v[228:231], v[68:71]
	v_mfma_f32_16x16x32_bf16 v[64:67], v[182:185], v[228:231], v[64:67]
	v_mfma_f32_16x16x32_bf16 v[116:119], v[178:181], v[194:197], v[116:119]
	v_mfma_f32_16x16x32_bf16 v[112:115], v[186:189], v[194:197], v[112:115]
	v_mfma_f32_16x16x32_bf16 v[100:103], v[178:181], v[208:211], v[100:103]
	v_mfma_f32_16x16x32_bf16 v[96:99], v[186:189], v[208:211], v[96:99]
	v_mfma_f32_16x16x32_bf16 v[84:87], v[178:181], v[224:227], v[84:87]
	v_mfma_f32_16x16x32_bf16 v[80:83], v[186:189], v[224:227], v[80:83]
	v_mfma_f32_16x16x32_bf16 v[68:71], v[178:181], v[232:235], v[68:71]
	v_mfma_f32_16x16x32_bf16 v[64:67], v[186:189], v[232:235], v[64:67]
	s_setprio 0
	s_barrier
	s_add_i32 s55, s52, s41
	v_lshl_add_u64 v[148:149], s[34:35], 0, v[130:131]
	s_mov_b32 m0, s55
	ds_read_b128 v[190:193], v156 offset:16384
	ds_read_b128 v[194:197], v156 offset:17408
	ds_read_b128 v[204:207], v156 offset:18432
	ds_read_b128 v[208:211], v156 offset:19456
	ds_read_b128 v[220:223], v156 offset:20480
	ds_read_b128 v[224:227], v156 offset:21504
	ds_read_b128 v[228:231], v156 offset:22528
	ds_read_b128 v[232:235], v156 offset:23552
	global_load_lds_dwordx4 v[148:149], off
	s_add_i32 m0, s55, 0x2000
	s_add_u32 s56, s34, 0x40000
	v_lshl_add_u64 v[152:153], s[34:35], 0, v[134:135]
	s_addc_u32 s57, s35, 0
	s_add_i32 s55, s53, s41
	global_load_lds_dwordx4 v[152:153], off
	v_lshl_add_u64 v[198:199], s[56:57], 0, v[130:131]
	s_mov_b32 m0, s55
	v_lshl_add_u64 v[236:237], s[36:37], 0, v[132:133]
	global_load_lds_dwordx4 v[198:199], off
	v_lshl_add_u64 v[198:199], s[56:57], 0, v[134:135]
	s_add_i32 m0, s55, 0x2000
	s_nop 0
	global_load_lds_dwordx4 v[198:199], off
	v_lshl_add_u64 v[198:199], s[36:37], 0, v[128:129]
	s_mov_b32 m0, s42
	s_nop 0
	global_load_lds_dwordx4 v[198:199], off
	s_mov_b32 m0, s43
	s_nop 0
	global_load_lds_dwordx4 v[236:237], off
	s_waitcnt vmcnt(8)
	s_waitcnt lgkmcnt(0)
	s_barrier
; #define PG8_STAGE(bufoff, gbase, voff) do { _Pragma("unroll") for (int _i = 0; _i < 2; ++_i) \
;         __builtin_amdgcn_global_load_lds((const unsigned*)((const char*)(gbase) + (voff)[_i]), (PG8_LAS unsigned*)(lds + (bufoff) + ldsw + _i * 8192), 16, 0, 0); } while (0)
; #define PG8_LDA(dst, b, h) do { _Pragma("unroll") for (int m = 0; m < 4; ++m) _Pragma("unroll") for (int k = 0; k < 2; ++k) dst[m][k] = *(const PG8_LAS bf16x8*)(lds + PG8_SA(b, h) + aoff + m * 2048 + k * 1024); } while (0)
; #define PG8_LDB(dst, b, h) do { _Pragma("unroll") for (int n = 0; n < 2; ++n) _Pragma("unroll") for (int k = 0; k < 2; ++k) dst[n][k] = *(const PG8_LAS bf16x8*)(lds + PG8_SB(b, h) + boff + n * 2048 + k * 1024); } while (0)
; #define PG8_MMA(ai, bj, At, Bt) do { __builtin_amdgcn_s_setprio(1); _Pragma("unroll") for (int m = 0; m < 4; ++m) _Pragma("unroll") for (int n = 0; n < 2; ++n) _Pragma("unroll") for (int k = 0; k < 2; ++k) \
;         acc[ai][bj][m][n] = __builtin_amdgcn_mfma_f32_16x16x32_bf16(Bt[n][k], At[m][k], acc[ai][bj][m][n], 0, 0, 0); __builtin_amdgcn_s_setprio(0); } while (0)
; #define PG8_WAIT_V(n) asm volatile("s_waitcnt vmcnt(" #n ")" ::: "memory")
; #define PG8_WAIT_L(n) asm volatile("s_waitcnt lgkmcnt(" #n ")" ::: "memory")
; #define PG8_BAR __builtin_amdgcn_s_barrier()
; #define PG8_SCHED __builtin_amdgcn_sched_barrier(0)
; template <class Epi, class Sched, bool ALIGN_EPI = false, bool SP2 = false>
; __device__ __forceinline__ void gemm_phase(PG8_LAS unsigned char* lds, const Gemm g, const Sched& S, const Epi& E) {
;     ...
;             PG8_WAIT_V(8); PG8_WAIT_L(0); PG8_BAR; PG8_MMA(1, 0, At, B0); PG8_MMA(1, 1, At, B1); PG8_BAR; PG8_SCHED;
;             PG8_LDB(B0, 1, 0); PG8_LDB(B1, 1, 1); PG8_SCHED; PG8_LDA(At, 1, 0); PG8_STAGE(PG8_SA(0, 1), a2 + hstep, voffA);
;             PG8_WAIT_V(8); PG8_WAIT_L(0); PG8_BAR; PG8_MMA(0, 0, At, B0); PG8_MMA(0, 1, At, B1); PG8_BAR; PG8_SCHED;
	s_setprio 1
	v_mfma_f32_16x16x32_bf16 v[60:63], v[158:161], v[190:193], v[60:63]
	v_mfma_f32_16x16x32_bf16 v[56:59], v[166:169], v[190:193], v[56:59]
	v_mfma_f32_16x16x32_bf16 v[44:47], v[158:161], v[204:207], v[44:47]
	v_mfma_f32_16x16x32_bf16 v[40:43], v[166:169], v[204:207], v[40:43]
	v_mfma_f32_16x16x32_bf16 v[28:31], v[158:161], v[220:223], v[28:31]
	v_mfma_f32_16x16x32_bf16 v[24:27], v[166:169], v[220:223], v[24:27]
	v_mfma_f32_16x16x32_bf16 v[12:15], v[158:161], v[228:231], v[12:15]
	v_mfma_f32_16x16x32_bf16 v[8:11], v[166:169], v[228:231], v[8:11]
	v_mfma_f32_16x16x32_bf16 v[60:63], v[162:165], v[194:197], v[60:63]
	v_mfma_f32_16x16x32_bf16 v[56:59], v[170:173], v[194:197], v[56:59]
	v_mfma_f32_16x16x32_bf16 v[44:47], v[162:165], v[208:211], v[44:47]
	v_mfma_f32_16x16x32_bf16 v[40:43], v[170:173], v[208:211], v[40:43]
	v_mfma_f32_16x16x32_bf16 v[28:31], v[162:165], v[224:227], v[28:31]
	v_mfma_f32_16x16x32_bf16 v[24:27], v[170:173], v[224:227], v[24:27]
	v_mfma_f32_16x16x32_bf16 v[12:15], v[162:165], v[232:235], v[12:15]
	v_mfma_f32_16x16x32_bf16 v[8:11], v[170:173], v[232:235], v[8:11]
	s_setprio 0
	s_setprio 1
	v_mfma_f32_16x16x32_bf16 v[52:55], v[174:177], v[190:193], v[52:55]
	v_mfma_f32_16x16x32_bf16 v[48:51], v[182:185], v[190:193], v[48:51]
	v_mfma_f32_16x16x32_bf16 v[36:39], v[174:177], v[204:207], v[36:39]
	v_mfma_f32_16x16x32_bf16 v[32:35], v[182:185], v[204:207], v[32:35]
	v_mfma_f32_16x16x32_bf16 v[20:23], v[174:177], v[220:223], v[20:23]
	v_mfma_f32_16x16x32_bf16 v[16:19], v[182:185], v[220:223], v[16:19]
	v_mfma_f32_16x16x32_bf16 v[4:7], v[174:177], v[228:231], v[4:7]
	v_mfma_f32_16x16x32_bf16 v[0:3], v[182:185], v[228:231], v[0:3]
	v_mfma_f32_16x16x32_bf16 v[52:55], v[178:181], v[194:197], v[52:55]
	v_mfma_f32_16x16x32_bf16 v[48:51], v[186:189], v[194:197], v[48:51]
	v_mfma_f32_16x16x32_bf16 v[36:39], v[178:181], v[208:211], v[36:39]
	v_mfma_f32_16x16x32_bf16 v[32:35], v[186:189], v[208:211], v[32:35]
	v_mfma_f32_16x16x32_bf16 v[20:23], v[178:181], v[224:227], v[20:23]
	v_mfma_f32_16x16x32_bf16 v[16:19], v[186:189], v[224:227], v[16:19]
	v_mfma_f32_16x16x32_bf16 v[4:7], v[178:181], v[232:235], v[4:7]
	v_mfma_f32_16x16x32_bf16 v[0:3], v[186:189], v[232:235], v[0:3]
	s_setprio 0
	s_barrier
	s_add_i32 s55, 0, 0x18000
	v_add_u32_e32 v136, s55, v151
	s_add_i32 s56, 0, 0x1c000
	ds_read_b128 v[158:161], v136
	ds_read_b128 v[162:165], v136 offset:1024
	ds_read_b128 v[166:169], v136 offset:2048
	ds_read_b128 v[170:173], v136 offset:3072
	v_add_u32_e32 v136, s56, v151
	ds_read_b128 v[174:177], v136
	ds_read_b128 v[178:181], v136 offset:1024
	ds_read_b128 v[182:185], v136 offset:2048
	ds_read_b128 v[186:189], v136 offset:3072
	s_add_u32 s36, s36, 0x40000
	s_addc_u32 s37, s37, 0
	s_mov_b32 m0, s44
	v_lshl_add_u64 v[238:239], s[36:37], 0, v[128:129]
	ds_read_b128 v[190:193], v156 offset:32768
	ds_read_b128 v[194:197], v156 offset:33792
	ds_read_b128 v[204:207], v156 offset:34816
	ds_read_b128 v[208:211], v156 offset:35840
	ds_read_b128 v[220:223], v156 offset:36864
	ds_read_b128 v[224:227], v156 offset:37888
	ds_read_b128 v[228:231], v156 offset:38912
	ds_read_b128 v[232:235], v156 offset:39936
	global_load_lds_dwordx4 v[238:239], off
	v_lshl_add_u64 v[238:239], s[36:37], 0, v[132:133]
	s_mov_b32 m0, s45
	s_nop 0
	global_load_lds_dwordx4 v[238:239], off
	s_waitcnt vmcnt(8)
	s_waitcnt lgkmcnt(0)
	s_barrier
	s_setprio 1
	v_mfma_f32_16x16x32_bf16 v[124:127], v[158:161], v[190:193], v[124:127]
	v_mfma_f32_16x16x32_bf16 v[120:123], v[166:169], v[190:193], v[120:123]
	v_mfma_f32_16x16x32_bf16 v[108:111], v[158:161], v[204:207], v[108:111]
	v_mfma_f32_16x16x32_bf16 v[104:107], v[166:169], v[204:207], v[104:107]
	v_mfma_f32_16x16x32_bf16 v[92:95], v[158:161], v[220:223], v[92:95]
	v_mfma_f32_16x16x32_bf16 v[88:91], v[166:169], v[220:223], v[88:91]
	v_mfma_f32_16x16x32_bf16 v[76:79], v[158:161], v[228:231], v[76:79]
	v_mfma_f32_16x16x32_bf16 v[72:75], v[166:169], v[228:231], v[72:75]
	v_mfma_f32_16x16x32_bf16 v[124:127], v[162:165], v[194:197], v[124:127]
	v_mfma_f32_16x16x32_bf16 v[120:123], v[170:173], v[194:197], v[120:123]
	v_mfma_f32_16x16x32_bf16 v[108:111], v[162:165], v[208:211], v[108:111]
	v_mfma_f32_16x16x32_bf16 v[104:107], v[170:173], v[208:211], v[104:107]
	v_mfma_f32_16x16x32_bf16 v[92:95], v[162:165], v[224:227], v[92:95]
	v_mfma_f32_16x16x32_bf16 v[88:91], v[170:173], v[224:227], v[88:91]
	v_mfma_f32_16x16x32_bf16 v[76:79], v[162:165], v[232:235], v[76:79]
	v_mfma_f32_16x16x32_bf16 v[72:75], v[170:173], v[232:235], v[72:75]
	s_setprio 0
	s_setprio 1
	v_mfma_f32_16x16x32_bf16 v[116:119], v[174:177], v[190:193], v[116:119]
	v_mfma_f32_16x16x32_bf16 v[112:115], v[182:185], v[190:193], v[112:115]
	v_mfma_f32_16x16x32_bf16 v[100:103], v[174:177], v[204:207], v[100:103]
	v_mfma_f32_16x16x32_bf16 v[96:99], v[182:185], v[204:207], v[96:99]
	v_mfma_f32_16x16x32_bf16 v[84:87], v[174:177], v[220:223], v[84:87]
	v_mfma_f32_16x16x32_bf16 v[80:83], v[182:185], v[220:223], v[80:83]
	v_mfma_f32_16x16x32_bf16 v[68:71], v[174:177], v[228:231], v[68:71]
	v_mfma_f32_16x16x32_bf16 v[64:67], v[182:185], v[228:231], v[64:67]
	v_mfma_f32_16x16x32_bf16 v[116:119], v[178:181], v[194:197], v[116:119]
	v_mfma_f32_16x16x32_bf16 v[112:115], v[186:189], v[194:197], v[112:115]
	v_mfma_f32_16x16x32_bf16 v[100:103], v[178:181], v[208:211], v[100:103]
	v_mfma_f32_16x16x32_bf16 v[96:99], v[186:189], v[208:211], v[96:99]
	v_mfma_f32_16x16x32_bf16 v[84:87], v[178:181], v[224:227], v[84:87]
	v_mfma_f32_16x16x32_bf16 v[80:83], v[186:189], v[224:227], v[80:83]
	v_mfma_f32_16x16x32_bf16 v[68:71], v[178:181], v[232:235], v[68:71]
	v_mfma_f32_16x16x32_bf16 v[64:67], v[186:189], v[232:235], v[64:67]
	s_setprio 0
	s_barrier
; #define PG8_STAGE(bufoff, gbase, voff) do { _Pragma("unroll") for (int _i = 0; _i < 2; ++_i) \
;         __builtin_amdgcn_global_load_lds((const unsigned*)((const char*)(gbase) + (voff)[_i]), (PG8_LAS unsigned*)(lds + (bufoff) + ldsw + _i * 8192), 16, 0, 0); } while (0)
; #define PG8_LDA(dst, b, h) do { _Pragma("unroll") for (int m = 0; m < 4; ++m) _Pragma("unroll") for (int k = 0; k < 2; ++k) dst[m][k] = *(const PG8_LAS bf16x8*)(lds + PG8_SA(b, h) + aoff + m * 2048 + k * 1024); } while (0)
; #define PG8_MMA(ai, bj, At, Bt) do { __builtin_amdgcn_s_setprio(1); _Pragma("unroll") for (int m = 0; m < 4; ++m) _Pragma("unroll") for (int n = 0; n < 2; ++n) _Pragma("unroll") for (int k = 0; k < 2; ++k) \
;         acc[ai][bj][m][n] = __builtin_amdgcn_mfma_f32_16x16x32_bf16(Bt[n][k], At[m][k], acc[ai][bj][m][n], 0, 0, 0); __builtin_amdgcn_s_setprio(0); } while (0)
; #define PG8_WAIT_V(n) asm volatile("s_waitcnt vmcnt(" #n ")" ::: "memory")
; #define PG8_WAIT_L(n) asm volatile("s_waitcnt lgkmcnt(" #n ")" ::: "memory")
; #define PG8_BAR __builtin_amdgcn_s_barrier()
; #define PG8_SCHED __builtin_amdgcn_sched_barrier(0)
; template <class Epi, class Sched, bool ALIGN_EPI = false, bool SP2 = false>
; __device__ __forceinline__ void gemm_phase(PG8_LAS unsigned char* lds, const Gemm g, const Sched& S, const Epi& E) {
;     ...
;             PG8_LDA(At, 1, 1); PG8_STAGE(PG8_SB(1, 0), b3, voffB); PG8_STAGE(PG8_SB(1, 1), b3 + hstep, voffB); PG8_STAGE(PG8_SA(1, 0), a3, voffA);
;             PG8_WAIT_V(8); PG8_WAIT_L(0); PG8_BAR; PG8_MMA(1, 0, At, B0); PG8_MMA(1, 1, At, B1); PG8_BAR; PG8_SCHED;
;     ...
;         if constexpr (ALIGN_EPI) { if (wr == 0) PG8_BAR; }
	s_add_i32 s36, s55, s41
	v_lshl_add_u64 v[148:149], v[148:149], 0, s[16:17]
	s_mov_b32 m0, s36
	ds_read_b128 v[190:193], v156 offset:49152
	ds_read_b128 v[194:197], v156 offset:50176
	ds_read_b128 v[204:207], v156 offset:51200
	ds_read_b128 v[208:211], v156 offset:52224
	ds_read_b128 v[220:223], v156 offset:53248
	ds_read_b128 v[224:227], v156 offset:54272
	ds_read_b128 v[228:231], v156 offset:55296
	ds_read_b128 v[232:235], v156 offset:56320
	global_load_lds_dwordx4 v[148:149], off
	s_add_i32 m0, s36, 0x2000
	s_add_u32 s34, s34, 0x40080
	v_lshl_add_u64 v[148:149], v[152:153], 0, s[16:17]
	s_addc_u32 s35, s35, 0
	s_add_i32 s36, s56, s41
	global_load_lds_dwordx4 v[148:149], off
	v_lshl_add_u64 v[148:149], s[34:35], 0, v[130:131]
	s_mov_b32 m0, s36
	s_nop 0
	global_load_lds_dwordx4 v[148:149], off
	v_lshl_add_u64 v[148:149], s[34:35], 0, v[134:135]
	s_add_i32 m0, s36, 0x2000
	s_nop 0
	global_load_lds_dwordx4 v[148:149], off
	v_lshl_add_u64 v[148:149], v[198:199], 0, s[16:17]
	s_mov_b32 m0, s47
	s_nop 0
	global_load_lds_dwordx4 v[148:149], off
	v_lshl_add_u64 v[148:149], v[236:237], 0, s[16:17]
	s_mov_b32 m0, s48
	s_nop 0
	global_load_lds_dwordx4 v[148:149], off
	s_waitcnt vmcnt(8)
	s_waitcnt lgkmcnt(0)
	s_barrier
	s_setprio 1
	v_mfma_f32_16x16x32_bf16 v[60:63], v[158:161], v[190:193], v[60:63]
	v_mfma_f32_16x16x32_bf16 v[56:59], v[166:169], v[190:193], v[56:59]
	v_mfma_f32_16x16x32_bf16 v[44:47], v[158:161], v[204:207], v[44:47]
	v_mfma_f32_16x16x32_bf16 v[40:43], v[166:169], v[204:207], v[40:43]
	v_mfma_f32_16x16x32_bf16 v[28:31], v[158:161], v[220:223], v[28:31]
	v_mfma_f32_16x16x32_bf16 v[24:27], v[166:169], v[220:223], v[24:27]
	v_mfma_f32_16x16x32_bf16 v[12:15], v[158:161], v[228:231], v[12:15]
	v_mfma_f32_16x16x32_bf16 v[8:11], v[166:169], v[228:231], v[8:11]
	v_mfma_f32_16x16x32_bf16 v[60:63], v[162:165], v[194:197], v[60:63]
	v_mfma_f32_16x16x32_bf16 v[56:59], v[170:173], v[194:197], v[56:59]
	v_mfma_f32_16x16x32_bf16 v[44:47], v[162:165], v[208:211], v[44:47]
	v_mfma_f32_16x16x32_bf16 v[40:43], v[170:173], v[208:211], v[40:43]
	v_mfma_f32_16x16x32_bf16 v[28:31], v[162:165], v[224:227], v[28:31]
	v_mfma_f32_16x16x32_bf16 v[24:27], v[170:173], v[224:227], v[24:27]
	v_mfma_f32_16x16x32_bf16 v[12:15], v[162:165], v[232:235], v[12:15]
	v_mfma_f32_16x16x32_bf16 v[8:11], v[170:173], v[232:235], v[8:11]
	s_setprio 0
	s_setprio 1
	v_mfma_f32_16x16x32_bf16 v[52:55], v[174:177], v[190:193], v[52:55]
	v_mfma_f32_16x16x32_bf16 v[48:51], v[182:185], v[190:193], v[48:51]
	v_mfma_f32_16x16x32_bf16 v[36:39], v[174:177], v[204:207], v[36:39]
	v_mfma_f32_16x16x32_bf16 v[32:35], v[182:185], v[204:207], v[32:35]
	v_mfma_f32_16x16x32_bf16 v[20:23], v[174:177], v[220:223], v[20:23]
	v_mfma_f32_16x16x32_bf16 v[16:19], v[182:185], v[220:223], v[16:19]
	v_mfma_f32_16x16x32_bf16 v[4:7], v[174:177], v[228:231], v[4:7]
	v_mfma_f32_16x16x32_bf16 v[0:3], v[182:185], v[228:231], v[0:3]
	v_mfma_f32_16x16x32_bf16 v[52:55], v[178:181], v[194:197], v[52:55]
	v_mfma_f32_16x16x32_bf16 v[48:51], v[186:189], v[194:197], v[48:51]
	v_mfma_f32_16x16x32_bf16 v[36:39], v[178:181], v[208:211], v[36:39]
	v_mfma_f32_16x16x32_bf16 v[32:35], v[186:189], v[208:211], v[32:35]
	v_mfma_f32_16x16x32_bf16 v[20:23], v[178:181], v[224:227], v[20:23]
	v_mfma_f32_16x16x32_bf16 v[16:19], v[186:189], v[224:227], v[16:19]
	v_mfma_f32_16x16x32_bf16 v[4:7], v[178:181], v[232:235], v[4:7]
	v_mfma_f32_16x16x32_bf16 v[0:3], v[186:189], v[232:235], v[0:3]
	s_setprio 0
	s_barrier
	s_add_i32 s39, s39, 2
	s_add_u32 s22, s22, 0x100
	s_addc_u32 s23, s23, 0
	s_add_u32 s27, s27, 0x100
	s_addc_u32 s38, s38, 0
	s_cmp_gt_u32 s39, 13
	s_cbranch_scc0 .LBB0_876
	s_and_b64 vcc, exec, s[18:19]
	s_cbranch_vccz .LBB0_879
	s_barrier

; #define PG8_STAGE(bufoff, gbase, voff) do { _Pragma("unroll") for (int _i = 0; _i < 2; ++_i) \
;         __builtin_amdgcn_global_load_lds((const unsigned*)((const char*)(gbase) + (voff)[_i]), (PG8_LAS unsigned*)(lds + (bufoff) + ldsw + _i * 8192), 16, 0, 0); } while (0)
; #define PG8_LDA(dst, b, h) do { _Pragma("unroll") for (int m = 0; m < 4; ++m) _Pragma("unroll") for (int k = 0; k < 2; ++k) dst[m][k] = *(const PG8_LAS bf16x8*)(lds + PG8_SA(b, h) + aoff + m * 2048 + k * 1024); } while (0)
; #define PG8_LDB(dst, b, h) do { _Pragma("unroll") for (int n = 0; n < 2; ++n) _Pragma("unroll") for (int k = 0; k < 2; ++k) dst[n][k] = *(const PG8_LAS bf16x8*)(lds + PG8_SB(b, h) + boff + n * 2048 + k * 1024); } while (0)
; #define PG8_MMA(ai, bj, At, Bt) do { __builtin_amdgcn_s_setprio(1); _Pragma("unroll") for (int m = 0; m < 4; ++m) _Pragma("unroll") for (int n = 0; n < 2; ++n) _Pragma("unroll") for (int k = 0; k < 2; ++k) \
;         acc[ai][bj][m][n] = __builtin_amdgcn_mfma_f32_16x16x32_bf16(Bt[n][k], At[m][k], acc[ai][bj][m][n], 0, 0, 0); __builtin_amdgcn_s_setprio(0); } while (0)
; #define PG8_WAIT_V(n) asm volatile("s_waitcnt vmcnt(" #n ")" ::: "memory")
; #define PG8_WAIT_L(n) asm volatile("s_waitcnt lgkmcnt(" #n ")" ::: "memory")
; #define PG8_BAR __builtin_amdgcn_s_barrier()
; #define PG8_SCHED __builtin_amdgcn_sched_barrier(0)
; template <class Epi, class Sched, bool ALIGN_EPI = false, bool SP2 = false>
; __device__ __forceinline__ void gemm_phase(PG8_LAS unsigned char* lds, const Gemm g, const Sched& S, const Epi& E) {
;     ...
;         for (int t = 0; t < nt; t += 2) {
;             const bool last = (t == nt - 2);
;             const char* a1 = cA + (size_t)(t + 1) * kstep;
;             const char* a2 = last ? nA : cA + (size_t)(t + 2) * kstep; const char* b2 = last ? nB : cB + (size_t)(t + 2) * kstep;
;             const char* a3 = a2 + kstep; const char* b3 = b2 + kstep;
;             if (last && has_next) S.a_ready(nxt);
;             if constexpr (SP2) {
;             PG8_LDB(B0, 0, 0); PG8_LDB(B1, 0, 1); PG8_SCHED; PG8_LDA(At, 0, 0); PG8_STAGE(PG8_SA(1, 1), a1 + hstep, voffA);
;             PG8_WAIT_V(8); PG8_WAIT_L(0); PG8_BAR; PG8_MMA(0, 0, At, B0); PG8_MMA(0, 1, At, B1); PG8_BAR; PG8_SCHED;
;             PG8_LDA(At, 0, 1); PG8_STAGE(PG8_SB(0, 0), b2, voffB); PG8_STAGE(PG8_SB(0, 1), b2 + hstep, voffB); PG8_STAGE(PG8_SA(0, 0), a2, voffA);
.LBB0_1082:
	ds_read_b128 v[128:131], v212
	ds_read_b128 v[132:135], v212 offset:1024
	ds_read_b128 v[136:139], v212 offset:2048
	ds_read_b128 v[140:143], v212 offset:3072
	ds_read_b128 v[144:147], v213
	ds_read_b128 v[148:151], v213 offset:1024
	ds_read_b128 v[152:155], v213 offset:2048
	ds_read_b128 v[156:159], v213 offset:3072
	s_add_u32 s34, s30, 0xfffc0080
	s_addc_u32 s35, s31, -1
	s_cmp_eq_u32 s49, 12
	s_cselect_b32 s37, s2, s35
	s_cselect_b32 s36, s3, s34
	s_cselect_b32 s35, s17, s48
	s_cselect_b32 s34, s19, s23
	v_lshl_add_u64 v[220:221], s[30:31], 0, v[188:189]
	s_add_i32 m0, s29, 0xc000
	ds_read_b128 v[160:163], v215
	ds_read_b128 v[164:167], v215 offset:1024
	ds_read_b128 v[168:171], v215 offset:2048
	ds_read_b128 v[172:175], v215 offset:3072
	ds_read_b128 v[196:199], v215 offset:4096
	ds_read_b128 v[204:207], v215 offset:5120
	ds_read_b128 v[208:211], v215 offset:6144
	ds_read_b128 v[216:219], v215 offset:7168
	global_load_lds_dwordx4 v[220:221], off
	v_lshl_add_u64 v[220:221], s[30:31], 0, v[190:191]
	s_add_i32 m0, s29, 0xe000
	s_nop 0
	global_load_lds_dwordx4 v[220:221], off
	s_waitcnt vmcnt(8)
	s_waitcnt lgkmcnt(0)
	s_barrier
	s_setprio 1
	v_mfma_f32_16x16x32_bf16 v[124:127], v[128:131], v[160:163], v[124:127]
	v_mfma_f32_16x16x32_bf16 v[120:123], v[136:139], v[160:163], v[120:123]
	v_mfma_f32_16x16x32_bf16 v[108:111], v[128:131], v[168:171], v[108:111]
	v_mfma_f32_16x16x32_bf16 v[104:107], v[136:139], v[168:171], v[104:107]
	v_mfma_f32_16x16x32_bf16 v[92:95], v[128:131], v[196:199], v[92:95]
	v_mfma_f32_16x16x32_bf16 v[88:91], v[136:139], v[196:199], v[88:91]
	v_mfma_f32_16x16x32_bf16 v[76:79], v[128:131], v[208:211], v[76:79]
	v_mfma_f32_16x16x32_bf16 v[72:75], v[136:139], v[208:211], v[72:75]
	v_mfma_f32_16x16x32_bf16 v[124:127], v[132:135], v[164:167], v[124:127]
	v_mfma_f32_16x16x32_bf16 v[120:123], v[140:143], v[164:167], v[120:123]
	v_mfma_f32_16x16x32_bf16 v[108:111], v[132:135], v[172:175], v[108:111]
	v_mfma_f32_16x16x32_bf16 v[104:107], v[140:143], v[172:175], v[104:107]
	v_mfma_f32_16x16x32_bf16 v[92:95], v[132:135], v[204:207], v[92:95]
	v_mfma_f32_16x16x32_bf16 v[88:91], v[140:143], v[204:207], v[88:91]
	v_mfma_f32_16x16x32_bf16 v[76:79], v[132:135], v[216:219], v[76:79]
	v_mfma_f32_16x16x32_bf16 v[72:75], v[140:143], v[216:219], v[72:75]
	s_setprio 0
	s_setprio 1
	v_mfma_f32_16x16x32_bf16 v[116:119], v[144:147], v[160:163], v[116:119]
	v_mfma_f32_16x16x32_bf16 v[112:115], v[152:155], v[160:163], v[112:115]
	v_mfma_f32_16x16x32_bf16 v[100:103], v[144:147], v[168:171], v[100:103]
	v_mfma_f32_16x16x32_bf16 v[96:99], v[152:155], v[168:171], v[96:99]
	v_mfma_f32_16x16x32_bf16 v[84:87], v[144:147], v[196:199], v[84:87]
	v_mfma_f32_16x16x32_bf16 v[80:83], v[152:155], v[196:199], v[80:83]
	v_mfma_f32_16x16x32_bf16 v[68:71], v[144:147], v[208:211], v[68:71]
	v_mfma_f32_16x16x32_bf16 v[64:67], v[152:155], v[208:211], v[64:67]
	v_mfma_f32_16x16x32_bf16 v[116:119], v[148:151], v[164:167], v[116:119]
	v_mfma_f32_16x16x32_bf16 v[112:115], v[156:159], v[164:167], v[112:115]
	v_mfma_f32_16x16x32_bf16 v[100:103], v[148:151], v[172:175], v[100:103]
	v_mfma_f32_16x16x32_bf16 v[96:99], v[156:159], v[172:175], v[96:99]
	v_mfma_f32_16x16x32_bf16 v[84:87], v[148:151], v[204:207], v[84:87]
	v_mfma_f32_16x16x32_bf16 v[80:83], v[156:159], v[204:207], v[80:83]
	v_mfma_f32_16x16x32_bf16 v[68:71], v[148:151], v[216:219], v[68:71]
	v_mfma_f32_16x16x32_bf16 v[64:67], v[156:159], v[216:219], v[64:67]
	s_setprio 0
	s_barrier
	s_add_i32 s50, s46, s33
	v_lshl_add_u64 v[220:221], s[34:35], 0, v[178:179]
	s_mov_b32 m0, s50
	ds_read_b128 v[160:163], v215 offset:16384
	ds_read_b128 v[164:167], v215 offset:17408
	ds_read_b128 v[168:171], v215 offset:18432
	ds_read_b128 v[172:175], v215 offset:19456
	ds_read_b128 v[196:199], v215 offset:20480
	ds_read_b128 v[204:207], v215 offset:21504
	ds_read_b128 v[208:211], v215 offset:22528
	ds_read_b128 v[216:219], v215 offset:23552
	global_load_lds_dwordx4 v[220:221], off
	s_add_i32 m0, s50, 0x2000
	s_add_u32 s50, s34, 0x40000
	v_lshl_add_u64 v[222:223], s[34:35], 0, v[182:183]
	s_addc_u32 s51, s35, 0
	s_add_i32 s52, s47, s33
	global_load_lds_dwordx4 v[222:223], off
	v_lshl_add_u64 v[224:225], s[50:51], 0, v[178:179]
	s_mov_b32 m0, s52
	v_lshl_add_u64 v[226:227], s[36:37], 0, v[180:181]
	global_load_lds_dwordx4 v[224:225], off
	v_lshl_add_u64 v[224:225], s[50:51], 0, v[182:183]
	s_add_i32 m0, s52, 0x2000
	s_nop 0
	global_load_lds_dwordx4 v[224:225], off
	v_lshl_add_u64 v[224:225], s[36:37], 0, v[176:177]
	s_mov_b32 m0, s29
	s_nop 0
	global_load_lds_dwordx4 v[224:225], off
	s_mov_b32 m0, s38
	s_nop 0
	global_load_lds_dwordx4 v[226:227], off
	s_waitcnt vmcnt(8)
	s_waitcnt lgkmcnt(0)
	s_barrier
; #define PG8_STAGE(bufoff, gbase, voff) do { _Pragma("unroll") for (int _i = 0; _i < 2; ++_i) \
;         __builtin_amdgcn_global_load_lds((const unsigned*)((const char*)(gbase) + (voff)[_i]), (PG8_LAS unsigned*)(lds + (bufoff) + ldsw + _i * 8192), 16, 0, 0); } while (0)
; #define PG8_LDA(dst, b, h) do { _Pragma("unroll") for (int m = 0; m < 4; ++m) _Pragma("unroll") for (int k = 0; k < 2; ++k) dst[m][k] = *(const PG8_LAS bf16x8*)(lds + PG8_SA(b, h) + aoff + m * 2048 + k * 1024); } while (0)
; #define PG8_LDB(dst, b, h) do { _Pragma("unroll") for (int n = 0; n < 2; ++n) _Pragma("unroll") for (int k = 0; k < 2; ++k) dst[n][k] = *(const PG8_LAS bf16x8*)(lds + PG8_SB(b, h) + boff + n * 2048 + k * 1024); } while (0)
; #define PG8_MMA(ai, bj, At, Bt) do { __builtin_amdgcn_s_setprio(1); _Pragma("unroll") for (int m = 0; m < 4; ++m) _Pragma("unroll") for (int n = 0; n < 2; ++n) _Pragma("unroll") for (int k = 0; k < 2; ++k) \
;         acc[ai][bj][m][n] = __builtin_amdgcn_mfma_f32_16x16x32_bf16(Bt[n][k], At[m][k], acc[ai][bj][m][n], 0, 0, 0); __builtin_amdgcn_s_setprio(0); } while (0)
; #define PG8_WAIT_V(n) asm volatile("s_waitcnt vmcnt(" #n ")" ::: "memory")
; #define PG8_WAIT_L(n) asm volatile("s_waitcnt lgkmcnt(" #n ")" ::: "memory")
; #define PG8_BAR __builtin_amdgcn_s_barrier()
; #define PG8_SCHED __builtin_amdgcn_sched_barrier(0)
; template <class Epi, class Sched, bool ALIGN_EPI = false, bool SP2 = false>
; __device__ __forceinline__ void gemm_phase(PG8_LAS unsigned char* lds, const Gemm g, const Sched& S, const Epi& E) {
;     ...
;             PG8_WAIT_V(8); PG8_WAIT_L(0); PG8_BAR; PG8_MMA(1, 0, At, B0); PG8_MMA(1, 1, At, B1); PG8_BAR; PG8_SCHED;
;             PG8_LDB(B0, 1, 0); PG8_LDB(B1, 1, 1); PG8_SCHED; PG8_LDA(At, 1, 0); PG8_STAGE(PG8_SA(0, 1), a2 + hstep, voffA);
;             PG8_WAIT_V(8); PG8_WAIT_L(0); PG8_BAR; PG8_MMA(0, 0, At, B0); PG8_MMA(0, 1, At, B1); PG8_BAR; PG8_SCHED;
	s_setprio 1
	v_mfma_f32_16x16x32_bf16 v[60:63], v[128:131], v[160:163], v[60:63]
	v_mfma_f32_16x16x32_bf16 v[56:59], v[136:139], v[160:163], v[56:59]
	v_mfma_f32_16x16x32_bf16 v[44:47], v[128:131], v[168:171], v[44:47]
	v_mfma_f32_16x16x32_bf16 v[40:43], v[136:139], v[168:171], v[40:43]
	v_mfma_f32_16x16x32_bf16 v[28:31], v[128:131], v[196:199], v[28:31]
	v_mfma_f32_16x16x32_bf16 v[24:27], v[136:139], v[196:199], v[24:27]
	v_mfma_f32_16x16x32_bf16 v[12:15], v[128:131], v[208:211], v[12:15]
	v_mfma_f32_16x16x32_bf16 v[8:11], v[136:139], v[208:211], v[8:11]
	v_mfma_f32_16x16x32_bf16 v[60:63], v[132:135], v[164:167], v[60:63]
	v_mfma_f32_16x16x32_bf16 v[56:59], v[140:143], v[164:167], v[56:59]
	v_mfma_f32_16x16x32_bf16 v[44:47], v[132:135], v[172:175], v[44:47]
	v_mfma_f32_16x16x32_bf16 v[40:43], v[140:143], v[172:175], v[40:43]
	v_mfma_f32_16x16x32_bf16 v[28:31], v[132:135], v[204:207], v[28:31]
	v_mfma_f32_16x16x32_bf16 v[24:27], v[140:143], v[204:207], v[24:27]
	v_mfma_f32_16x16x32_bf16 v[12:15], v[132:135], v[216:219], v[12:15]
	v_mfma_f32_16x16x32_bf16 v[8:11], v[140:143], v[216:219], v[8:11]
	s_setprio 0
	s_setprio 1
	v_mfma_f32_16x16x32_bf16 v[52:55], v[144:147], v[160:163], v[52:55]
	v_mfma_f32_16x16x32_bf16 v[48:51], v[152:155], v[160:163], v[48:51]
	v_mfma_f32_16x16x32_bf16 v[36:39], v[144:147], v[168:171], v[36:39]
	v_mfma_f32_16x16x32_bf16 v[32:35], v[152:155], v[168:171], v[32:35]
	v_mfma_f32_16x16x32_bf16 v[20:23], v[144:147], v[196:199], v[20:23]
	v_mfma_f32_16x16x32_bf16 v[16:19], v[152:155], v[196:199], v[16:19]
	v_mfma_f32_16x16x32_bf16 v[4:7], v[144:147], v[208:211], v[4:7]
	v_mfma_f32_16x16x32_bf16 v[0:3], v[152:155], v[208:211], v[0:3]
	v_mfma_f32_16x16x32_bf16 v[52:55], v[148:151], v[164:167], v[52:55]
	v_mfma_f32_16x16x32_bf16 v[48:51], v[156:159], v[164:167], v[48:51]
	v_mfma_f32_16x16x32_bf16 v[36:39], v[148:151], v[172:175], v[36:39]
	v_mfma_f32_16x16x32_bf16 v[32:35], v[156:159], v[172:175], v[32:35]
	v_mfma_f32_16x16x32_bf16 v[20:23], v[148:151], v[204:207], v[20:23]
	v_mfma_f32_16x16x32_bf16 v[16:19], v[156:159], v[204:207], v[16:19]
	v_mfma_f32_16x16x32_bf16 v[4:7], v[148:151], v[216:219], v[4:7]
	v_mfma_f32_16x16x32_bf16 v[0:3], v[156:159], v[216:219], v[0:3]
	s_setprio 0
	s_barrier
	s_add_i32 s50, 0, 0x18000
	s_add_i32 s51, 0, 0x1c000
	v_add_u32_e32 v140, s50, v201
	v_add_u32_e32 v156, s51, v201
	ds_read_b128 v[128:131], v140
	ds_read_b128 v[132:135], v140 offset:1024
	ds_read_b128 v[136:139], v140 offset:2048
	ds_read_b128 v[140:143], v140 offset:3072
	ds_read_b128 v[144:147], v156
	ds_read_b128 v[148:151], v156 offset:1024
	ds_read_b128 v[152:155], v156 offset:2048
	ds_read_b128 v[156:159], v156 offset:3072
	s_add_u32 s36, s36, 0x40000
	s_addc_u32 s37, s37, 0
	s_mov_b32 m0, s39
	v_lshl_add_u64 v[228:229], s[36:37], 0, v[176:177]
	ds_read_b128 v[160:163], v215 offset:32768
	ds_read_b128 v[164:167], v215 offset:33792
	ds_read_b128 v[168:171], v215 offset:34816
	ds_read_b128 v[172:175], v215 offset:35840
	ds_read_b128 v[196:199], v215 offset:36864
	ds_read_b128 v[204:207], v215 offset:37888
	ds_read_b128 v[208:211], v215 offset:38912
	ds_read_b128 v[216:219], v215 offset:39936
	global_load_lds_dwordx4 v[228:229], off
	v_lshl_add_u64 v[228:229], s[36:37], 0, v[180:181]
	s_mov_b32 m0, s40
	s_nop 0
	global_load_lds_dwordx4 v[228:229], off
	s_waitcnt vmcnt(8)
	s_waitcnt lgkmcnt(0)
	s_barrier
	s_setprio 1
	v_mfma_f32_16x16x32_bf16 v[124:127], v[128:131], v[160:163], v[124:127]
	v_mfma_f32_16x16x32_bf16 v[120:123], v[136:139], v[160:163], v[120:123]
	v_mfma_f32_16x16x32_bf16 v[108:111], v[128:131], v[168:171], v[108:111]
	v_mfma_f32_16x16x32_bf16 v[104:107], v[136:139], v[168:171], v[104:107]
	v_mfma_f32_16x16x32_bf16 v[92:95], v[128:131], v[196:199], v[92:95]
	v_mfma_f32_16x16x32_bf16 v[88:91], v[136:139], v[196:199], v[88:91]
	v_mfma_f32_16x16x32_bf16 v[76:79], v[128:131], v[208:211], v[76:79]
	v_mfma_f32_16x16x32_bf16 v[72:75], v[136:139], v[208:211], v[72:75]
	v_mfma_f32_16x16x32_bf16 v[124:127], v[132:135], v[164:167], v[124:127]
	v_mfma_f32_16x16x32_bf16 v[120:123], v[140:143], v[164:167], v[120:123]
	v_mfma_f32_16x16x32_bf16 v[108:111], v[132:135], v[172:175], v[108:111]
	v_mfma_f32_16x16x32_bf16 v[104:107], v[140:143], v[172:175], v[104:107]
	v_mfma_f32_16x16x32_bf16 v[92:95], v[132:135], v[204:207], v[92:95]
	v_mfma_f32_16x16x32_bf16 v[88:91], v[140:143], v[204:207], v[88:91]
	v_mfma_f32_16x16x32_bf16 v[76:79], v[132:135], v[216:219], v[76:79]
	v_mfma_f32_16x16x32_bf16 v[72:75], v[140:143], v[216:219], v[72:75]
	s_setprio 0
	s_setprio 1
	v_mfma_f32_16x16x32_bf16 v[116:119], v[144:147], v[160:163], v[116:119]
	v_mfma_f32_16x16x32_bf16 v[112:115], v[152:155], v[160:163], v[112:115]
	v_mfma_f32_16x16x32_bf16 v[100:103], v[144:147], v[168:171], v[100:103]
	v_mfma_f32_16x16x32_bf16 v[96:99], v[152:155], v[168:171], v[96:99]
	v_mfma_f32_16x16x32_bf16 v[84:87], v[144:147], v[196:199], v[84:87]
	v_mfma_f32_16x16x32_bf16 v[80:83], v[152:155], v[196:199], v[80:83]
	v_mfma_f32_16x16x32_bf16 v[68:71], v[144:147], v[208:211], v[68:71]
	v_mfma_f32_16x16x32_bf16 v[64:67], v[152:155], v[208:211], v[64:67]
	v_mfma_f32_16x16x32_bf16 v[116:119], v[148:151], v[164:167], v[116:119]
	v_mfma_f32_16x16x32_bf16 v[112:115], v[156:159], v[164:167], v[112:115]
	v_mfma_f32_16x16x32_bf16 v[100:103], v[148:151], v[172:175], v[100:103]
	v_mfma_f32_16x16x32_bf16 v[96:99], v[156:159], v[172:175], v[96:99]
	v_mfma_f32_16x16x32_bf16 v[84:87], v[148:151], v[204:207], v[84:87]
	v_mfma_f32_16x16x32_bf16 v[80:83], v[156:159], v[204:207], v[80:83]
	v_mfma_f32_16x16x32_bf16 v[68:71], v[148:151], v[216:219], v[68:71]
	v_mfma_f32_16x16x32_bf16 v[64:67], v[156:159], v[216:219], v[64:67]
	s_setprio 0
	s_barrier
; #define PG8_STAGE(bufoff, gbase, voff) do { _Pragma("unroll") for (int _i = 0; _i < 2; ++_i) \
;         __builtin_amdgcn_global_load_lds((const unsigned*)((const char*)(gbase) + (voff)[_i]), (PG8_LAS unsigned*)(lds + (bufoff) + ldsw + _i * 8192), 16, 0, 0); } while (0)
; #define PG8_LDA(dst, b, h) do { _Pragma("unroll") for (int m = 0; m < 4; ++m) _Pragma("unroll") for (int k = 0; k < 2; ++k) dst[m][k] = *(const PG8_LAS bf16x8*)(lds + PG8_SA(b, h) + aoff + m * 2048 + k * 1024); } while (0)
; #define PG8_MMA(ai, bj, At, Bt) do { __builtin_amdgcn_s_setprio(1); _Pragma("unroll") for (int m = 0; m < 4; ++m) _Pragma("unroll") for (int n = 0; n < 2; ++n) _Pragma("unroll") for (int k = 0; k < 2; ++k) \
;         acc[ai][bj][m][n] = __builtin_amdgcn_mfma_f32_16x16x32_bf16(Bt[n][k], At[m][k], acc[ai][bj][m][n], 0, 0, 0); __builtin_amdgcn_s_setprio(0); } while (0)
; #define PG8_WAIT_V(n) asm volatile("s_waitcnt vmcnt(" #n ")" ::: "memory")
; #define PG8_WAIT_L(n) asm volatile("s_waitcnt lgkmcnt(" #n ")" ::: "memory")
; #define PG8_BAR __builtin_amdgcn_s_barrier()
; #define PG8_SCHED __builtin_amdgcn_sched_barrier(0)
; template <class Epi, class Sched, bool ALIGN_EPI = false, bool SP2 = false>
; __device__ __forceinline__ void gemm_phase(PG8_LAS unsigned char* lds, const Gemm g, const Sched& S, const Epi& E) {
;     ...
;             PG8_LDA(At, 1, 1); PG8_STAGE(PG8_SB(1, 0), b3, voffB); PG8_STAGE(PG8_SB(1, 1), b3 + hstep, voffB); PG8_STAGE(PG8_SA(1, 0), a3, voffA);
;             PG8_WAIT_V(8); PG8_WAIT_L(0); PG8_BAR; PG8_MMA(1, 0, At, B0); PG8_MMA(1, 1, At, B1); PG8_BAR; PG8_SCHED;
;     ...
;         if constexpr (ALIGN_EPI) { if (wr == 0) PG8_BAR; }
	s_add_i32 s36, s50, s33
	v_lshl_add_u64 v[220:221], v[220:221], 0, s[12:13]
	s_mov_b32 m0, s36
	ds_read_b128 v[160:163], v215 offset:49152
	ds_read_b128 v[164:167], v215 offset:50176
	ds_read_b128 v[168:171], v215 offset:51200
	ds_read_b128 v[172:175], v215 offset:52224
	ds_read_b128 v[196:199], v215 offset:53248
	ds_read_b128 v[204:207], v215 offset:54272
	ds_read_b128 v[208:211], v215 offset:55296
	ds_read_b128 v[216:219], v215 offset:56320
	global_load_lds_dwordx4 v[220:221], off
	s_add_i32 m0, s36, 0x2000
	s_add_u32 s34, s34, 0x40080
	v_lshl_add_u64 v[220:221], v[222:223], 0, s[12:13]
	s_addc_u32 s35, s35, 0
	s_add_i32 s36, s51, s33
	global_load_lds_dwordx4 v[220:221], off
	v_lshl_add_u64 v[220:221], s[34:35], 0, v[178:179]
	s_mov_b32 m0, s36
	s_nop 0
	global_load_lds_dwordx4 v[220:221], off
	v_lshl_add_u64 v[220:221], s[34:35], 0, v[182:183]
	s_add_i32 m0, s36, 0x2000
	s_nop 0
	global_load_lds_dwordx4 v[220:221], off
	v_lshl_add_u64 v[220:221], v[224:225], 0, s[12:13]
	s_mov_b32 m0, s42
	s_nop 0
	global_load_lds_dwordx4 v[220:221], off
	v_lshl_add_u64 v[220:221], v[226:227], 0, s[12:13]
	s_mov_b32 m0, s43
	s_nop 0
	global_load_lds_dwordx4 v[220:221], off
	s_waitcnt vmcnt(8)
	s_waitcnt lgkmcnt(0)
	s_barrier
	s_setprio 1
	v_mfma_f32_16x16x32_bf16 v[60:63], v[128:131], v[160:163], v[60:63]
	v_mfma_f32_16x16x32_bf16 v[56:59], v[136:139], v[160:163], v[56:59]
	v_mfma_f32_16x16x32_bf16 v[44:47], v[128:131], v[168:171], v[44:47]
	v_mfma_f32_16x16x32_bf16 v[40:43], v[136:139], v[168:171], v[40:43]
	v_mfma_f32_16x16x32_bf16 v[28:31], v[128:131], v[196:199], v[28:31]
	v_mfma_f32_16x16x32_bf16 v[24:27], v[136:139], v[196:199], v[24:27]
	v_mfma_f32_16x16x32_bf16 v[12:15], v[128:131], v[208:211], v[12:15]
	v_mfma_f32_16x16x32_bf16 v[8:11], v[136:139], v[208:211], v[8:11]
	v_mfma_f32_16x16x32_bf16 v[60:63], v[132:135], v[164:167], v[60:63]
	v_mfma_f32_16x16x32_bf16 v[56:59], v[140:143], v[164:167], v[56:59]
	v_mfma_f32_16x16x32_bf16 v[44:47], v[132:135], v[172:175], v[44:47]
	v_mfma_f32_16x16x32_bf16 v[40:43], v[140:143], v[172:175], v[40:43]
	v_mfma_f32_16x16x32_bf16 v[28:31], v[132:135], v[204:207], v[28:31]
	v_mfma_f32_16x16x32_bf16 v[24:27], v[140:143], v[204:207], v[24:27]
	v_mfma_f32_16x16x32_bf16 v[12:15], v[132:135], v[216:219], v[12:15]
	v_mfma_f32_16x16x32_bf16 v[8:11], v[140:143], v[216:219], v[8:11]
	s_setprio 0
	s_setprio 1
	v_mfma_f32_16x16x32_bf16 v[52:55], v[144:147], v[160:163], v[52:55]
	v_mfma_f32_16x16x32_bf16 v[48:51], v[152:155], v[160:163], v[48:51]
	v_mfma_f32_16x16x32_bf16 v[36:39], v[144:147], v[168:171], v[36:39]
	v_mfma_f32_16x16x32_bf16 v[32:35], v[152:155], v[168:171], v[32:35]
	v_mfma_f32_16x16x32_bf16 v[20:23], v[144:147], v[196:199], v[20:23]
	v_mfma_f32_16x16x32_bf16 v[16:19], v[152:155], v[196:199], v[16:19]
	v_mfma_f32_16x16x32_bf16 v[4:7], v[144:147], v[208:211], v[4:7]
	v_mfma_f32_16x16x32_bf16 v[0:3], v[152:155], v[208:211], v[0:3]
	v_mfma_f32_16x16x32_bf16 v[52:55], v[148:151], v[164:167], v[52:55]
	v_mfma_f32_16x16x32_bf16 v[48:51], v[156:159], v[164:167], v[48:51]
	v_mfma_f32_16x16x32_bf16 v[36:39], v[148:151], v[172:175], v[36:39]
	v_mfma_f32_16x16x32_bf16 v[32:35], v[156:159], v[172:175], v[32:35]
	v_mfma_f32_16x16x32_bf16 v[20:23], v[148:151], v[204:207], v[20:23]
	v_mfma_f32_16x16x32_bf16 v[16:19], v[156:159], v[204:207], v[16:19]
	v_mfma_f32_16x16x32_bf16 v[4:7], v[148:151], v[216:219], v[4:7]
	v_mfma_f32_16x16x32_bf16 v[0:3], v[156:159], v[216:219], v[0:3]
	s_setprio 0
	s_barrier
	s_add_i32 s49, s49, 2
	s_add_u32 s30, s30, 0x100
	s_addc_u32 s31, s31, 0
	s_add_u32 s23, s23, 0x100
	s_addc_u32 s48, s48, 0
	s_cmp_gt_u32 s49, 13
	s_cbranch_scc0 .LBB0_1082
	s_and_b64 vcc, exec, s[14:15]
	s_cbranch_vccz .LBB0_1085
	s_barrier

; #define PG8_STAGE(bufoff, gbase, voff) do { _Pragma("unroll") for (int _i = 0; _i < 2; ++_i) \
;         __builtin_amdgcn_global_load_lds((const unsigned*)((const char*)(gbase) + (voff)[_i]), (PG8_LAS unsigned*)(lds + (bufoff) + ldsw + _i * 8192), 16, 0, 0); } while (0)
; #define PG8_LDA(dst, b, h) do { _Pragma("unroll") for (int m = 0; m < 4; ++m) _Pragma("unroll") for (int k = 0; k < 2; ++k) dst[m][k] = *(const PG8_LAS bf16x8*)(lds + PG8_SA(b, h) + aoff + m * 2048 + k * 1024); } while (0)
; #define PG8_LDB(dst, b, h) do { _Pragma("unroll") for (int n = 0; n < 2; ++n) _Pragma("unroll") for (int k = 0; k < 2; ++k) dst[n][k] = *(const PG8_LAS bf16x8*)(lds + PG8_SB(b, h) + boff + n * 2048 + k * 1024); } while (0)
; #define PG8_MMA(ai, bj, At, Bt) do { __builtin_amdgcn_s_setprio(1); _Pragma("unroll") for (int m = 0; m < 4; ++m) _Pragma("unroll") for (int n = 0; n < 2; ++n) _Pragma("unroll") for (int k = 0; k < 2; ++k) \
;         acc[ai][bj][m][n] = __builtin_amdgcn_mfma_f32_16x16x32_bf16(Bt[n][k], At[m][k], acc[ai][bj][m][n], 0, 0, 0); __builtin_amdgcn_s_setprio(0); } while (0)
; #define PG8_WAIT_V(n) asm volatile("s_waitcnt vmcnt(" #n ")" ::: "memory")
; #define PG8_WAIT_L(n) asm volatile("s_waitcnt lgkmcnt(" #n ")" ::: "memory")
; #define PG8_BAR __builtin_amdgcn_s_barrier()
; #define PG8_SCHED __builtin_amdgcn_sched_barrier(0)
; template <class Epi, class Sched, bool ALIGN_EPI = false, bool SP2 = false>
; __device__ __forceinline__ void gemm_phase(PG8_LAS unsigned char* lds, const Gemm g, const Sched& S, const Epi& E) {
;     ...
;         for (int t = 0; t < nt; t += 2) {
;             const bool last = (t == nt - 2);
;             const char* a1 = cA + (size_t)(t + 1) * kstep;
;             const char* a2 = last ? nA : cA + (size_t)(t + 2) * kstep; const char* b2 = last ? nB : cB + (size_t)(t + 2) * kstep;
;             const char* a3 = a2 + kstep; const char* b3 = b2 + kstep;
;             if (last && has_next) S.a_ready(nxt);
;             if constexpr (SP2) {
;             PG8_LDB(B0, 0, 0); PG8_LDB(B1, 0, 1); PG8_SCHED; PG8_LDA(At, 0, 0); PG8_STAGE(PG8_SA(1, 1), a1 + hstep, voffA);
;             PG8_WAIT_V(8); PG8_WAIT_L(0); PG8_BAR; PG8_MMA(0, 0, At, B0); PG8_MMA(0, 1, At, B1); PG8_BAR; PG8_SCHED;
;             PG8_LDA(At, 0, 1); PG8_STAGE(PG8_SB(0, 0), b2, voffB); PG8_STAGE(PG8_SB(0, 1), b2 + hstep, voffB); PG8_STAGE(PG8_SA(0, 0), a2, voffA);
.LBB0_1166:
	ds_read_b128 v[154:157], v150
	ds_read_b128 v[158:161], v150 offset:1024
	ds_read_b128 v[162:165], v150 offset:2048
	ds_read_b128 v[166:169], v150 offset:3072
	ds_read_b128 v[170:173], v151
	ds_read_b128 v[174:177], v151 offset:1024
	ds_read_b128 v[178:181], v151 offset:2048
	ds_read_b128 v[182:185], v151 offset:3072
	s_add_u32 s28, s26, 0xfffc0080
	s_addc_u32 s29, s27, -1
	s_cmp_eq_u32 s51, 12
	s_cselect_b32 s31, s3, s29
	s_cselect_b32 s30, s19, s28
	s_cselect_b32 s29, s17, s50
	s_cselect_b32 s28, s23, s49
	v_lshl_add_u64 v[146:147], s[26:27], 0, v[138:139]
	s_add_i32 m0, s37, 0xc000
	ds_read_b128 v[186:189], v152
	ds_read_b128 v[190:193], v152 offset:1024
	ds_read_b128 v[194:197], v152 offset:2048
	ds_read_b128 v[204:207], v152 offset:3072
	ds_read_b128 v[208:211], v152 offset:4096
	ds_read_b128 v[216:219], v152 offset:5120
	ds_read_b128 v[220:223], v152 offset:6144
	ds_read_b128 v[224:227], v152 offset:7168
	global_load_lds_dwordx4 v[146:147], off
	v_lshl_add_u64 v[146:147], s[26:27], 0, v[140:141]
	s_add_i32 m0, s37, 0xe000
	s_nop 0
	global_load_lds_dwordx4 v[146:147], off
	s_waitcnt vmcnt(8)
	s_waitcnt lgkmcnt(0)
	s_barrier
	s_setprio 1
	v_mfma_f32_16x16x32_bf16 v[116:119], v[154:157], v[186:189], v[116:119]
	v_mfma_f32_16x16x32_bf16 v[112:115], v[162:165], v[186:189], v[112:115]
	v_mfma_f32_16x16x32_bf16 v[104:107], v[154:157], v[194:197], v[104:107]
	v_mfma_f32_16x16x32_bf16 v[96:99], v[162:165], v[194:197], v[96:99]
	v_mfma_f32_16x16x32_bf16 v[88:91], v[154:157], v[208:211], v[88:91]
	v_mfma_f32_16x16x32_bf16 v[80:83], v[162:165], v[208:211], v[80:83]
	v_mfma_f32_16x16x32_bf16 v[72:75], v[154:157], v[220:223], v[72:75]
	v_mfma_f32_16x16x32_bf16 v[64:67], v[162:165], v[220:223], v[64:67]
	v_mfma_f32_16x16x32_bf16 v[116:119], v[158:161], v[190:193], v[116:119]
	v_mfma_f32_16x16x32_bf16 v[112:115], v[166:169], v[190:193], v[112:115]
	v_mfma_f32_16x16x32_bf16 v[104:107], v[158:161], v[204:207], v[104:107]
	v_mfma_f32_16x16x32_bf16 v[96:99], v[166:169], v[204:207], v[96:99]
	v_mfma_f32_16x16x32_bf16 v[88:91], v[158:161], v[216:219], v[88:91]
	v_mfma_f32_16x16x32_bf16 v[80:83], v[166:169], v[216:219], v[80:83]
	v_mfma_f32_16x16x32_bf16 v[72:75], v[158:161], v[224:227], v[72:75]
	v_mfma_f32_16x16x32_bf16 v[64:67], v[166:169], v[224:227], v[64:67]
	s_setprio 0
	s_setprio 1
	v_mfma_f32_16x16x32_bf16 v[124:127], v[170:173], v[186:189], v[124:127]
	v_mfma_f32_16x16x32_bf16 v[120:123], v[178:181], v[186:189], v[120:123]
	v_mfma_f32_16x16x32_bf16 v[108:111], v[170:173], v[194:197], v[108:111]
	v_mfma_f32_16x16x32_bf16 v[100:103], v[178:181], v[194:197], v[100:103]
	v_mfma_f32_16x16x32_bf16 v[92:95], v[170:173], v[208:211], v[92:95]
	v_mfma_f32_16x16x32_bf16 v[84:87], v[178:181], v[208:211], v[84:87]
	v_mfma_f32_16x16x32_bf16 v[76:79], v[170:173], v[220:223], v[76:79]
	v_mfma_f32_16x16x32_bf16 v[68:71], v[178:181], v[220:223], v[68:71]
	v_mfma_f32_16x16x32_bf16 v[124:127], v[174:177], v[190:193], v[124:127]
	v_mfma_f32_16x16x32_bf16 v[120:123], v[182:185], v[190:193], v[120:123]
	v_mfma_f32_16x16x32_bf16 v[108:111], v[174:177], v[204:207], v[108:111]
	v_mfma_f32_16x16x32_bf16 v[100:103], v[182:185], v[204:207], v[100:103]
	v_mfma_f32_16x16x32_bf16 v[92:95], v[174:177], v[216:219], v[92:95]
	v_mfma_f32_16x16x32_bf16 v[84:87], v[182:185], v[216:219], v[84:87]
	v_mfma_f32_16x16x32_bf16 v[76:79], v[174:177], v[224:227], v[76:79]
	v_mfma_f32_16x16x32_bf16 v[68:71], v[182:185], v[224:227], v[68:71]
	s_setprio 0
	s_barrier
	s_add_i32 s52, s45, s35
	v_lshl_add_u64 v[146:147], s[28:29], 0, v[132:133]
	s_mov_b32 m0, s52
	ds_read_b128 v[186:189], v152 offset:16384
	ds_read_b128 v[190:193], v152 offset:17408
	ds_read_b128 v[194:197], v152 offset:18432
	ds_read_b128 v[204:207], v152 offset:19456
	ds_read_b128 v[208:211], v152 offset:20480
	ds_read_b128 v[216:219], v152 offset:21504
	ds_read_b128 v[220:223], v152 offset:22528
	ds_read_b128 v[224:227], v152 offset:23552
	global_load_lds_dwordx4 v[146:147], off
	s_add_i32 m0, s52, 0x2000
	s_add_u32 s52, s28, 0x40000
	v_lshl_add_u64 v[198:199], s[28:29], 0, v[128:129]
	s_addc_u32 s53, s29, 0
	s_add_i32 s54, s46, s35
	global_load_lds_dwordx4 v[198:199], off
	v_lshl_add_u64 v[212:213], s[52:53], 0, v[132:133]
	s_mov_b32 m0, s54
	v_lshl_add_u64 v[228:229], s[30:31], 0, v[130:131]
	global_load_lds_dwordx4 v[212:213], off
	v_lshl_add_u64 v[212:213], s[52:53], 0, v[128:129]
	s_add_i32 m0, s54, 0x2000
	s_nop 0
	global_load_lds_dwordx4 v[212:213], off
	v_lshl_add_u64 v[212:213], s[30:31], 0, v[134:135]
	s_mov_b32 m0, s37
	s_nop 0
	global_load_lds_dwordx4 v[212:213], off
	s_mov_b32 m0, s38
	s_nop 0
	global_load_lds_dwordx4 v[228:229], off
	s_waitcnt vmcnt(8)
	s_waitcnt lgkmcnt(0)
	s_barrier
; #define PG8_STAGE(bufoff, gbase, voff) do { _Pragma("unroll") for (int _i = 0; _i < 2; ++_i) \
;         __builtin_amdgcn_global_load_lds((const unsigned*)((const char*)(gbase) + (voff)[_i]), (PG8_LAS unsigned*)(lds + (bufoff) + ldsw + _i * 8192), 16, 0, 0); } while (0)
; #define PG8_LDA(dst, b, h) do { _Pragma("unroll") for (int m = 0; m < 4; ++m) _Pragma("unroll") for (int k = 0; k < 2; ++k) dst[m][k] = *(const PG8_LAS bf16x8*)(lds + PG8_SA(b, h) + aoff + m * 2048 + k * 1024); } while (0)
; #define PG8_LDB(dst, b, h) do { _Pragma("unroll") for (int n = 0; n < 2; ++n) _Pragma("unroll") for (int k = 0; k < 2; ++k) dst[n][k] = *(const PG8_LAS bf16x8*)(lds + PG8_SB(b, h) + boff + n * 2048 + k * 1024); } while (0)
; #define PG8_MMA(ai, bj, At, Bt) do { __builtin_amdgcn_s_setprio(1); _Pragma("unroll") for (int m = 0; m < 4; ++m) _Pragma("unroll") for (int n = 0; n < 2; ++n) _Pragma("unroll") for (int k = 0; k < 2; ++k) \
;         acc[ai][bj][m][n] = __builtin_amdgcn_mfma_f32_16x16x32_bf16(Bt[n][k], At[m][k], acc[ai][bj][m][n], 0, 0, 0); __builtin_amdgcn_s_setprio(0); } while (0)
; #define PG8_WAIT_V(n) asm volatile("s_waitcnt vmcnt(" #n ")" ::: "memory")
; #define PG8_WAIT_L(n) asm volatile("s_waitcnt lgkmcnt(" #n ")" ::: "memory")
; #define PG8_BAR __builtin_amdgcn_s_barrier()
; #define PG8_SCHED __builtin_amdgcn_sched_barrier(0)
; template <class Epi, class Sched, bool ALIGN_EPI = false, bool SP2 = false>
; __device__ __forceinline__ void gemm_phase(PG8_LAS unsigned char* lds, const Gemm g, const Sched& S, const Epi& E) {
;     ...
;             PG8_WAIT_V(8); PG8_WAIT_L(0); PG8_BAR; PG8_MMA(1, 0, At, B0); PG8_MMA(1, 1, At, B1); PG8_BAR; PG8_SCHED;
;             PG8_LDB(B0, 1, 0); PG8_LDB(B1, 1, 1); PG8_SCHED; PG8_LDA(At, 1, 0); PG8_STAGE(PG8_SA(0, 1), a2 + hstep, voffA);
;             PG8_WAIT_V(8); PG8_WAIT_L(0); PG8_BAR; PG8_MMA(0, 0, At, B0); PG8_MMA(0, 1, At, B1); PG8_BAR; PG8_SCHED;
	s_setprio 1
	v_mfma_f32_16x16x32_bf16 v[56:59], v[154:157], v[186:189], v[56:59]
	v_mfma_f32_16x16x32_bf16 v[48:51], v[162:165], v[186:189], v[48:51]
	v_mfma_f32_16x16x32_bf16 v[40:43], v[154:157], v[194:197], v[40:43]
	v_mfma_f32_16x16x32_bf16 v[32:35], v[162:165], v[194:197], v[32:35]
	v_mfma_f32_16x16x32_bf16 v[24:27], v[154:157], v[208:211], v[24:27]
	v_mfma_f32_16x16x32_bf16 v[16:19], v[162:165], v[208:211], v[16:19]
	v_mfma_f32_16x16x32_bf16 v[8:11], v[154:157], v[220:223], v[8:11]
	v_mfma_f32_16x16x32_bf16 v[0:3], v[162:165], v[220:223], v[0:3]
	v_mfma_f32_16x16x32_bf16 v[56:59], v[158:161], v[190:193], v[56:59]
	v_mfma_f32_16x16x32_bf16 v[48:51], v[166:169], v[190:193], v[48:51]
	v_mfma_f32_16x16x32_bf16 v[40:43], v[158:161], v[204:207], v[40:43]
	v_mfma_f32_16x16x32_bf16 v[32:35], v[166:169], v[204:207], v[32:35]
	v_mfma_f32_16x16x32_bf16 v[24:27], v[158:161], v[216:219], v[24:27]
	v_mfma_f32_16x16x32_bf16 v[16:19], v[166:169], v[216:219], v[16:19]
	v_mfma_f32_16x16x32_bf16 v[8:11], v[158:161], v[224:227], v[8:11]
	v_mfma_f32_16x16x32_bf16 v[0:3], v[166:169], v[224:227], v[0:3]
	s_setprio 0
	s_setprio 1
	v_mfma_f32_16x16x32_bf16 v[60:63], v[170:173], v[186:189], v[60:63]
	v_mfma_f32_16x16x32_bf16 v[52:55], v[178:181], v[186:189], v[52:55]
	v_mfma_f32_16x16x32_bf16 v[44:47], v[170:173], v[194:197], v[44:47]
	v_mfma_f32_16x16x32_bf16 v[36:39], v[178:181], v[194:197], v[36:39]
	v_mfma_f32_16x16x32_bf16 v[28:31], v[170:173], v[208:211], v[28:31]
	v_mfma_f32_16x16x32_bf16 v[20:23], v[178:181], v[208:211], v[20:23]
	v_mfma_f32_16x16x32_bf16 v[12:15], v[170:173], v[220:223], v[12:15]
	v_mfma_f32_16x16x32_bf16 v[4:7], v[178:181], v[220:223], v[4:7]
	v_mfma_f32_16x16x32_bf16 v[60:63], v[174:177], v[190:193], v[60:63]
	v_mfma_f32_16x16x32_bf16 v[52:55], v[182:185], v[190:193], v[52:55]
	v_mfma_f32_16x16x32_bf16 v[44:47], v[174:177], v[204:207], v[44:47]
	v_mfma_f32_16x16x32_bf16 v[36:39], v[182:185], v[204:207], v[36:39]
	v_mfma_f32_16x16x32_bf16 v[28:31], v[174:177], v[216:219], v[28:31]
	v_mfma_f32_16x16x32_bf16 v[20:23], v[182:185], v[216:219], v[20:23]
	v_mfma_f32_16x16x32_bf16 v[12:15], v[174:177], v[224:227], v[12:15]
	v_mfma_f32_16x16x32_bf16 v[4:7], v[182:185], v[224:227], v[4:7]
	s_setprio 0
	s_barrier
	s_add_i32 s52, 0, 0x18000
	s_add_i32 s53, 0, 0x1c000
	v_add_u32_e32 v166, s52, v149
	v_add_u32_e32 v182, s53, v149
	ds_read_b128 v[154:157], v166
	ds_read_b128 v[158:161], v166 offset:1024
	ds_read_b128 v[162:165], v166 offset:2048
	ds_read_b128 v[166:169], v166 offset:3072
	ds_read_b128 v[170:173], v182
	ds_read_b128 v[174:177], v182 offset:1024
	ds_read_b128 v[178:181], v182 offset:2048
	ds_read_b128 v[182:185], v182 offset:3072
	s_add_u32 s30, s30, 0x40000
	s_addc_u32 s31, s31, 0
	s_mov_b32 m0, s39
	v_lshl_add_u64 v[230:231], s[30:31], 0, v[134:135]
	ds_read_b128 v[186:189], v152 offset:32768
	ds_read_b128 v[190:193], v152 offset:33792
	ds_read_b128 v[194:197], v152 offset:34816
	ds_read_b128 v[204:207], v152 offset:35840
	ds_read_b128 v[208:211], v152 offset:36864
	ds_read_b128 v[216:219], v152 offset:37888
	ds_read_b128 v[220:223], v152 offset:38912
	ds_read_b128 v[224:227], v152 offset:39936
	global_load_lds_dwordx4 v[230:231], off
	v_lshl_add_u64 v[230:231], s[30:31], 0, v[130:131]
	s_mov_b32 m0, s40
	s_nop 0
	global_load_lds_dwordx4 v[230:231], off
	s_waitcnt vmcnt(8)
	s_waitcnt lgkmcnt(0)
	s_barrier
	s_setprio 1
	v_mfma_f32_16x16x32_bf16 v[116:119], v[154:157], v[186:189], v[116:119]
	v_mfma_f32_16x16x32_bf16 v[112:115], v[162:165], v[186:189], v[112:115]
	v_mfma_f32_16x16x32_bf16 v[104:107], v[154:157], v[194:197], v[104:107]
	v_mfma_f32_16x16x32_bf16 v[96:99], v[162:165], v[194:197], v[96:99]
	v_mfma_f32_16x16x32_bf16 v[88:91], v[154:157], v[208:211], v[88:91]
	v_mfma_f32_16x16x32_bf16 v[80:83], v[162:165], v[208:211], v[80:83]
	v_mfma_f32_16x16x32_bf16 v[72:75], v[154:157], v[220:223], v[72:75]
	v_mfma_f32_16x16x32_bf16 v[64:67], v[162:165], v[220:223], v[64:67]
	v_mfma_f32_16x16x32_bf16 v[116:119], v[158:161], v[190:193], v[116:119]
	v_mfma_f32_16x16x32_bf16 v[112:115], v[166:169], v[190:193], v[112:115]
	v_mfma_f32_16x16x32_bf16 v[104:107], v[158:161], v[204:207], v[104:107]
	v_mfma_f32_16x16x32_bf16 v[96:99], v[166:169], v[204:207], v[96:99]
	v_mfma_f32_16x16x32_bf16 v[88:91], v[158:161], v[216:219], v[88:91]
	v_mfma_f32_16x16x32_bf16 v[80:83], v[166:169], v[216:219], v[80:83]
	v_mfma_f32_16x16x32_bf16 v[72:75], v[158:161], v[224:227], v[72:75]
	v_mfma_f32_16x16x32_bf16 v[64:67], v[166:169], v[224:227], v[64:67]
	s_setprio 0
	s_setprio 1
	v_mfma_f32_16x16x32_bf16 v[124:127], v[170:173], v[186:189], v[124:127]
	v_mfma_f32_16x16x32_bf16 v[120:123], v[178:181], v[186:189], v[120:123]
	v_mfma_f32_16x16x32_bf16 v[108:111], v[170:173], v[194:197], v[108:111]
	v_mfma_f32_16x16x32_bf16 v[100:103], v[178:181], v[194:197], v[100:103]
	v_mfma_f32_16x16x32_bf16 v[92:95], v[170:173], v[208:211], v[92:95]
	v_mfma_f32_16x16x32_bf16 v[84:87], v[178:181], v[208:211], v[84:87]
	v_mfma_f32_16x16x32_bf16 v[76:79], v[170:173], v[220:223], v[76:79]
	v_mfma_f32_16x16x32_bf16 v[68:71], v[178:181], v[220:223], v[68:71]
	v_mfma_f32_16x16x32_bf16 v[124:127], v[174:177], v[190:193], v[124:127]
	v_mfma_f32_16x16x32_bf16 v[120:123], v[182:185], v[190:193], v[120:123]
	v_mfma_f32_16x16x32_bf16 v[108:111], v[174:177], v[204:207], v[108:111]
	v_mfma_f32_16x16x32_bf16 v[100:103], v[182:185], v[204:207], v[100:103]
	v_mfma_f32_16x16x32_bf16 v[92:95], v[174:177], v[216:219], v[92:95]
	v_mfma_f32_16x16x32_bf16 v[84:87], v[182:185], v[216:219], v[84:87]
	v_mfma_f32_16x16x32_bf16 v[76:79], v[174:177], v[224:227], v[76:79]
	v_mfma_f32_16x16x32_bf16 v[68:71], v[182:185], v[224:227], v[68:71]
	s_setprio 0
	s_barrier
; #define PG8_STAGE(bufoff, gbase, voff) do { _Pragma("unroll") for (int _i = 0; _i < 2; ++_i) \
;         __builtin_amdgcn_global_load_lds((const unsigned*)((const char*)(gbase) + (voff)[_i]), (PG8_LAS unsigned*)(lds + (bufoff) + ldsw + _i * 8192), 16, 0, 0); } while (0)
; #define PG8_LDA(dst, b, h) do { _Pragma("unroll") for (int m = 0; m < 4; ++m) _Pragma("unroll") for (int k = 0; k < 2; ++k) dst[m][k] = *(const PG8_LAS bf16x8*)(lds + PG8_SA(b, h) + aoff + m * 2048 + k * 1024); } while (0)
; #define PG8_MMA(ai, bj, At, Bt) do { __builtin_amdgcn_s_setprio(1); _Pragma("unroll") for (int m = 0; m < 4; ++m) _Pragma("unroll") for (int n = 0; n < 2; ++n) _Pragma("unroll") for (int k = 0; k < 2; ++k) \
;         acc[ai][bj][m][n] = __builtin_amdgcn_mfma_f32_16x16x32_bf16(Bt[n][k], At[m][k], acc[ai][bj][m][n], 0, 0, 0); __builtin_amdgcn_s_setprio(0); } while (0)
; #define PG8_WAIT_V(n) asm volatile("s_waitcnt vmcnt(" #n ")" ::: "memory")
; #define PG8_WAIT_L(n) asm volatile("s_waitcnt lgkmcnt(" #n ")" ::: "memory")
; #define PG8_BAR __builtin_amdgcn_s_barrier()
; #define PG8_SCHED __builtin_amdgcn_sched_barrier(0)
; template <class Epi, class Sched, bool ALIGN_EPI = false, bool SP2 = false>
; __device__ __forceinline__ void gemm_phase(PG8_LAS unsigned char* lds, const Gemm g, const Sched& S, const Epi& E) {
;     ...
;             PG8_LDA(At, 1, 1); PG8_STAGE(PG8_SB(1, 0), b3, voffB); PG8_STAGE(PG8_SB(1, 1), b3 + hstep, voffB); PG8_STAGE(PG8_SA(1, 0), a3, voffA);
;             PG8_WAIT_V(8); PG8_WAIT_L(0); PG8_BAR; PG8_MMA(1, 0, At, B0); PG8_MMA(1, 1, At, B1); PG8_BAR; PG8_SCHED;
;     ...
;         if constexpr (ALIGN_EPI) { if (wr == 0) PG8_BAR; }
	s_add_i32 s30, s52, s35
	v_lshl_add_u64 v[146:147], v[146:147], 0, s[12:13]
	s_mov_b32 m0, s30
	ds_read_b128 v[186:189], v152 offset:49152
	ds_read_b128 v[190:193], v152 offset:50176
	ds_read_b128 v[194:197], v152 offset:51200
	ds_read_b128 v[204:207], v152 offset:52224
	ds_read_b128 v[208:211], v152 offset:53248
	ds_read_b128 v[216:219], v152 offset:54272
	ds_read_b128 v[220:223], v152 offset:55296
	ds_read_b128 v[224:227], v152 offset:56320
	global_load_lds_dwordx4 v[146:147], off
	s_add_i32 m0, s30, 0x2000
	s_add_u32 s28, s28, 0x40080
	v_lshl_add_u64 v[146:147], v[198:199], 0, s[12:13]
	s_addc_u32 s29, s29, 0
	s_add_i32 s30, s53, s35
	global_load_lds_dwordx4 v[146:147], off
	v_lshl_add_u64 v[146:147], s[28:29], 0, v[132:133]
	s_mov_b32 m0, s30
	s_nop 0
	global_load_lds_dwordx4 v[146:147], off
	v_lshl_add_u64 v[146:147], s[28:29], 0, v[128:129]
	s_add_i32 m0, s30, 0x2000
	s_nop 0
	global_load_lds_dwordx4 v[146:147], off
	v_lshl_add_u64 v[146:147], v[212:213], 0, s[12:13]
	s_mov_b32 m0, s41
	s_nop 0
	global_load_lds_dwordx4 v[146:147], off
	v_lshl_add_u64 v[146:147], v[228:229], 0, s[12:13]
	s_mov_b32 m0, s42
	s_nop 0
	global_load_lds_dwordx4 v[146:147], off
	s_waitcnt vmcnt(8)
	s_waitcnt lgkmcnt(0)
	s_barrier
	s_setprio 1
	v_mfma_f32_16x16x32_bf16 v[56:59], v[154:157], v[186:189], v[56:59]
	v_mfma_f32_16x16x32_bf16 v[48:51], v[162:165], v[186:189], v[48:51]
	v_mfma_f32_16x16x32_bf16 v[40:43], v[154:157], v[194:197], v[40:43]
	v_mfma_f32_16x16x32_bf16 v[32:35], v[162:165], v[194:197], v[32:35]
	v_mfma_f32_16x16x32_bf16 v[24:27], v[154:157], v[208:211], v[24:27]
	v_mfma_f32_16x16x32_bf16 v[16:19], v[162:165], v[208:211], v[16:19]
	v_mfma_f32_16x16x32_bf16 v[8:11], v[154:157], v[220:223], v[8:11]
	v_mfma_f32_16x16x32_bf16 v[0:3], v[162:165], v[220:223], v[0:3]
	v_mfma_f32_16x16x32_bf16 v[56:59], v[158:161], v[190:193], v[56:59]
	v_mfma_f32_16x16x32_bf16 v[48:51], v[166:169], v[190:193], v[48:51]
	v_mfma_f32_16x16x32_bf16 v[40:43], v[158:161], v[204:207], v[40:43]
	v_mfma_f32_16x16x32_bf16 v[32:35], v[166:169], v[204:207], v[32:35]
	v_mfma_f32_16x16x32_bf16 v[24:27], v[158:161], v[216:219], v[24:27]
	v_mfma_f32_16x16x32_bf16 v[16:19], v[166:169], v[216:219], v[16:19]
	v_mfma_f32_16x16x32_bf16 v[8:11], v[158:161], v[224:227], v[8:11]
	v_mfma_f32_16x16x32_bf16 v[0:3], v[166:169], v[224:227], v[0:3]
	s_setprio 0
	s_setprio 1
	v_mfma_f32_16x16x32_bf16 v[60:63], v[170:173], v[186:189], v[60:63]
	v_mfma_f32_16x16x32_bf16 v[52:55], v[178:181], v[186:189], v[52:55]
	v_mfma_f32_16x16x32_bf16 v[44:47], v[170:173], v[194:197], v[44:47]
	v_mfma_f32_16x16x32_bf16 v[36:39], v[178:181], v[194:197], v[36:39]
	v_mfma_f32_16x16x32_bf16 v[28:31], v[170:173], v[208:211], v[28:31]
	v_mfma_f32_16x16x32_bf16 v[20:23], v[178:181], v[208:211], v[20:23]
	v_mfma_f32_16x16x32_bf16 v[12:15], v[170:173], v[220:223], v[12:15]
	v_mfma_f32_16x16x32_bf16 v[4:7], v[178:181], v[220:223], v[4:7]
	v_mfma_f32_16x16x32_bf16 v[60:63], v[174:177], v[190:193], v[60:63]
	v_mfma_f32_16x16x32_bf16 v[52:55], v[182:185], v[190:193], v[52:55]
	v_mfma_f32_16x16x32_bf16 v[44:47], v[174:177], v[204:207], v[44:47]
	v_mfma_f32_16x16x32_bf16 v[36:39], v[182:185], v[204:207], v[36:39]
	v_mfma_f32_16x16x32_bf16 v[28:31], v[174:177], v[216:219], v[28:31]
	v_mfma_f32_16x16x32_bf16 v[20:23], v[182:185], v[216:219], v[20:23]
	v_mfma_f32_16x16x32_bf16 v[12:15], v[174:177], v[224:227], v[12:15]
	v_mfma_f32_16x16x32_bf16 v[4:7], v[182:185], v[224:227], v[4:7]
	s_setprio 0
	s_barrier
	s_add_i32 s51, s51, 2
	s_add_u32 s26, s26, 0x100
	s_addc_u32 s27, s27, 0
	s_add_u32 s49, s49, 0x100
	s_addc_u32 s50, s50, 0
	s_cmp_gt_u32 s51, 13
	s_cbranch_scc0 .LBB0_1166
	s_and_b64 vcc, exec, s[14:15]
	s_cbranch_vccz .LBB0_1169
	s_barrier

; #define PG8_STAGE(bufoff, gbase, voff) do { _Pragma("unroll") for (int _i = 0; _i < 2; ++_i) \
;         __builtin_amdgcn_global_load_lds((const unsigned*)((const char*)(gbase) + (voff)[_i]), (PG8_LAS unsigned*)(lds + (bufoff) + ldsw + _i * 8192), 16, 0, 0); } while (0)
; #define PG8_LDA(dst, b, h) do { _Pragma("unroll") for (int m = 0; m < 4; ++m) _Pragma("unroll") for (int k = 0; k < 2; ++k) dst[m][k] = *(const PG8_LAS bf16x8*)(lds + PG8_SA(b, h) + aoff + m * 2048 + k * 1024); } while (0)
; #define PG8_LDB(dst, b, h) do { _Pragma("unroll") for (int n = 0; n < 2; ++n) _Pragma("unroll") for (int k = 0; k < 2; ++k) dst[n][k] = *(const PG8_LAS bf16x8*)(lds + PG8_SB(b, h) + boff + n * 2048 + k * 1024); } while (0)
; #define PG8_MMA(ai, bj, At, Bt) do { __builtin_amdgcn_s_setprio(1); _Pragma("unroll") for (int m = 0; m < 4; ++m) _Pragma("unroll") for (int n = 0; n < 2; ++n) _Pragma("unroll") for (int k = 0; k < 2; ++k) \
;         acc[ai][bj][m][n] = __builtin_amdgcn_mfma_f32_16x16x32_bf16(Bt[n][k], At[m][k], acc[ai][bj][m][n], 0, 0, 0); __builtin_amdgcn_s_setprio(0); } while (0)
; #define PG8_WAIT_V(n) asm volatile("s_waitcnt vmcnt(" #n ")" ::: "memory")
; #define PG8_WAIT_L(n) asm volatile("s_waitcnt lgkmcnt(" #n ")" ::: "memory")
; #define PG8_BAR __builtin_amdgcn_s_barrier()
; #define PG8_SCHED __builtin_amdgcn_sched_barrier(0)
; template <class Epi, class Sched, bool ALIGN_EPI = false, bool SP2 = false>
; __device__ __forceinline__ void gemm_phase(PG8_LAS unsigned char* lds, const Gemm g, const Sched& S, const Epi& E) {
;     ...
;         for (int t = 0; t < nt; t += 2) {
;             const bool last = (t == nt - 2);
;             const char* a1 = cA + (size_t)(t + 1) * kstep;
;             const char* a2 = last ? nA : cA + (size_t)(t + 2) * kstep; const char* b2 = last ? nB : cB + (size_t)(t + 2) * kstep;
;             const char* a3 = a2 + kstep; const char* b3 = b2 + kstep;
;             if (last && has_next) S.a_ready(nxt);
;             if constexpr (SP2) {
;             PG8_LDB(B0, 0, 0); PG8_LDB(B1, 0, 1); PG8_SCHED; PG8_LDA(At, 0, 0); PG8_STAGE(PG8_SA(1, 1), a1 + hstep, voffA);
;             PG8_WAIT_V(8); PG8_WAIT_L(0); PG8_BAR; PG8_MMA(0, 0, At, B0); PG8_MMA(0, 1, At, B1); PG8_BAR; PG8_SCHED;
;             PG8_LDA(At, 0, 1); PG8_STAGE(PG8_SB(0, 0), b2, voffB); PG8_STAGE(PG8_SB(0, 1), b2 + hstep, voffB); PG8_STAGE(PG8_SA(0, 0), a2, voffA);
.LBB0_1248:
	ds_read_b128 v[128:131], v216
	ds_read_b128 v[132:135], v216 offset:1024
	ds_read_b128 v[136:139], v216 offset:2048
	ds_read_b128 v[140:143], v216 offset:3072
	ds_read_b128 v[144:147], v217
	ds_read_b128 v[148:151], v217 offset:1024
	ds_read_b128 v[152:155], v217 offset:2048
	ds_read_b128 v[156:159], v217 offset:3072
	s_add_u32 s20, s18, 0x100
	s_addc_u32 s21, s19, 0
	s_cmp_eq_u32 s45, 40
	s_cselect_b32 s25, s1, s21
	s_cselect_b32 s24, s0, s20
	s_cselect_b32 s23, s17, s44
	s_cselect_b32 s22, s16, s43
	v_lshl_add_u64 v[200:201], s[18:19], 0, v[188:189]
	s_add_i32 m0, s29, 0xc000
	ds_read_b128 v[160:163], v218
	ds_read_b128 v[164:167], v218 offset:1024
	ds_read_b128 v[168:171], v218 offset:2048
	ds_read_b128 v[172:175], v218 offset:3072
	ds_read_b128 v[196:199], v218 offset:4096
	ds_read_b128 v[204:207], v218 offset:5120
	ds_read_b128 v[208:211], v218 offset:6144
	ds_read_b128 v[220:223], v218 offset:7168
	global_load_lds_dwordx4 v[200:201], off
	v_lshl_add_u64 v[200:201], s[18:19], 0, v[190:191]
	s_add_i32 m0, s29, 0xe000
	s_nop 0
	global_load_lds_dwordx4 v[200:201], off
	s_waitcnt vmcnt(8)
	s_waitcnt lgkmcnt(0)
	s_barrier
	s_setprio 1
	v_mfma_f32_16x16x32_bf16 v[124:127], v[128:131], v[160:163], v[124:127]
	v_mfma_f32_16x16x32_bf16 v[120:123], v[136:139], v[160:163], v[120:123]
	v_mfma_f32_16x16x32_bf16 v[108:111], v[128:131], v[168:171], v[108:111]
	v_mfma_f32_16x16x32_bf16 v[104:107], v[136:139], v[168:171], v[104:107]
	v_mfma_f32_16x16x32_bf16 v[92:95], v[128:131], v[196:199], v[92:95]
	v_mfma_f32_16x16x32_bf16 v[88:91], v[136:139], v[196:199], v[88:91]
	v_mfma_f32_16x16x32_bf16 v[76:79], v[128:131], v[208:211], v[76:79]
	v_mfma_f32_16x16x32_bf16 v[72:75], v[136:139], v[208:211], v[72:75]
	v_mfma_f32_16x16x32_bf16 v[124:127], v[132:135], v[164:167], v[124:127]
	v_mfma_f32_16x16x32_bf16 v[120:123], v[140:143], v[164:167], v[120:123]
	v_mfma_f32_16x16x32_bf16 v[108:111], v[132:135], v[172:175], v[108:111]
	v_mfma_f32_16x16x32_bf16 v[104:107], v[140:143], v[172:175], v[104:107]
	v_mfma_f32_16x16x32_bf16 v[92:95], v[132:135], v[204:207], v[92:95]
	v_mfma_f32_16x16x32_bf16 v[88:91], v[140:143], v[204:207], v[88:91]
	v_mfma_f32_16x16x32_bf16 v[76:79], v[132:135], v[220:223], v[76:79]
	v_mfma_f32_16x16x32_bf16 v[72:75], v[140:143], v[220:223], v[72:75]
	s_setprio 0
	s_setprio 1
	v_mfma_f32_16x16x32_bf16 v[116:119], v[144:147], v[160:163], v[116:119]
	v_mfma_f32_16x16x32_bf16 v[112:115], v[152:155], v[160:163], v[112:115]
	v_mfma_f32_16x16x32_bf16 v[100:103], v[144:147], v[168:171], v[100:103]
	v_mfma_f32_16x16x32_bf16 v[96:99], v[152:155], v[168:171], v[96:99]
	v_mfma_f32_16x16x32_bf16 v[84:87], v[144:147], v[196:199], v[84:87]
	v_mfma_f32_16x16x32_bf16 v[80:83], v[152:155], v[196:199], v[80:83]
	v_mfma_f32_16x16x32_bf16 v[68:71], v[144:147], v[208:211], v[68:71]
	v_mfma_f32_16x16x32_bf16 v[64:67], v[152:155], v[208:211], v[64:67]
	v_mfma_f32_16x16x32_bf16 v[116:119], v[148:151], v[164:167], v[116:119]
	v_mfma_f32_16x16x32_bf16 v[112:115], v[156:159], v[164:167], v[112:115]
	v_mfma_f32_16x16x32_bf16 v[100:103], v[148:151], v[172:175], v[100:103]
	v_mfma_f32_16x16x32_bf16 v[96:99], v[156:159], v[172:175], v[96:99]
	v_mfma_f32_16x16x32_bf16 v[84:87], v[148:151], v[204:207], v[84:87]
	v_mfma_f32_16x16x32_bf16 v[80:83], v[156:159], v[204:207], v[80:83]
	v_mfma_f32_16x16x32_bf16 v[68:71], v[148:151], v[220:223], v[68:71]
	v_mfma_f32_16x16x32_bf16 v[64:67], v[156:159], v[220:223], v[64:67]
	s_setprio 0
	s_barrier
	s_add_i32 s18, s39, s28
	v_lshl_add_u64 v[200:201], s[22:23], 0, v[178:179]
	s_mov_b32 m0, s18
	ds_read_b128 v[160:163], v218 offset:16384
	ds_read_b128 v[164:167], v218 offset:17408
	ds_read_b128 v[168:171], v218 offset:18432
	ds_read_b128 v[172:175], v218 offset:19456
	ds_read_b128 v[196:199], v218 offset:20480
	ds_read_b128 v[204:207], v218 offset:21504
	ds_read_b128 v[208:211], v218 offset:22528
	ds_read_b128 v[220:223], v218 offset:23552
	global_load_lds_dwordx4 v[200:201], off
	s_add_i32 m0, s18, 0x2000
	s_add_u32 s18, s22, 0xb0000
	v_lshl_add_u64 v[212:213], s[22:23], 0, v[182:183]
	s_addc_u32 s19, s23, 0
	s_add_i32 s46, s40, s28
	global_load_lds_dwordx4 v[212:213], off
	v_lshl_add_u64 v[224:225], s[18:19], 0, v[178:179]
	s_mov_b32 m0, s46
	v_lshl_add_u64 v[226:227], s[24:25], 0, v[180:181]
	global_load_lds_dwordx4 v[224:225], off
	v_lshl_add_u64 v[224:225], s[18:19], 0, v[182:183]
	s_add_i32 m0, s46, 0x2000
	s_nop 0
	global_load_lds_dwordx4 v[224:225], off
	v_lshl_add_u64 v[224:225], s[24:25], 0, v[176:177]
	s_mov_b32 m0, s29
	s_nop 0
	global_load_lds_dwordx4 v[224:225], off
	s_mov_b32 m0, s30
	s_nop 0
	global_load_lds_dwordx4 v[226:227], off
	s_waitcnt vmcnt(8)
	s_waitcnt lgkmcnt(0)
	s_barrier
; #define PG8_STAGE(bufoff, gbase, voff) do { _Pragma("unroll") for (int _i = 0; _i < 2; ++_i) \
;         __builtin_amdgcn_global_load_lds((const unsigned*)((const char*)(gbase) + (voff)[_i]), (PG8_LAS unsigned*)(lds + (bufoff) + ldsw + _i * 8192), 16, 0, 0); } while (0)
; #define PG8_LDA(dst, b, h) do { _Pragma("unroll") for (int m = 0; m < 4; ++m) _Pragma("unroll") for (int k = 0; k < 2; ++k) dst[m][k] = *(const PG8_LAS bf16x8*)(lds + PG8_SA(b, h) + aoff + m * 2048 + k * 1024); } while (0)
; #define PG8_LDB(dst, b, h) do { _Pragma("unroll") for (int n = 0; n < 2; ++n) _Pragma("unroll") for (int k = 0; k < 2; ++k) dst[n][k] = *(const PG8_LAS bf16x8*)(lds + PG8_SB(b, h) + boff + n * 2048 + k * 1024); } while (0)
; #define PG8_MMA(ai, bj, At, Bt) do { __builtin_amdgcn_s_setprio(1); _Pragma("unroll") for (int m = 0; m < 4; ++m) _Pragma("unroll") for (int n = 0; n < 2; ++n) _Pragma("unroll") for (int k = 0; k < 2; ++k) \
;         acc[ai][bj][m][n] = __builtin_amdgcn_mfma_f32_16x16x32_bf16(Bt[n][k], At[m][k], acc[ai][bj][m][n], 0, 0, 0); __builtin_amdgcn_s_setprio(0); } while (0)
; #define PG8_WAIT_V(n) asm volatile("s_waitcnt vmcnt(" #n ")" ::: "memory")
; #define PG8_WAIT_L(n) asm volatile("s_waitcnt lgkmcnt(" #n ")" ::: "memory")
; #define PG8_BAR __builtin_amdgcn_s_barrier()
; #define PG8_SCHED __builtin_amdgcn_sched_barrier(0)
; template <class Epi, class Sched, bool ALIGN_EPI = false, bool SP2 = false>
; __device__ __forceinline__ void gemm_phase(PG8_LAS unsigned char* lds, const Gemm g, const Sched& S, const Epi& E) {
;     ...
;             PG8_WAIT_V(8); PG8_WAIT_L(0); PG8_BAR; PG8_MMA(1, 0, At, B0); PG8_MMA(1, 1, At, B1); PG8_BAR; PG8_SCHED;
;             PG8_LDB(B0, 1, 0); PG8_LDB(B1, 1, 1); PG8_SCHED; PG8_LDA(At, 1, 0); PG8_STAGE(PG8_SA(0, 1), a2 + hstep, voffA);
;             PG8_WAIT_V(8); PG8_WAIT_L(0); PG8_BAR; PG8_MMA(0, 0, At, B0); PG8_MMA(0, 1, At, B1); PG8_BAR; PG8_SCHED;
	s_setprio 1
	v_mfma_f32_16x16x32_bf16 v[60:63], v[128:131], v[160:163], v[60:63]
	v_mfma_f32_16x16x32_bf16 v[56:59], v[136:139], v[160:163], v[56:59]
	v_mfma_f32_16x16x32_bf16 v[44:47], v[128:131], v[168:171], v[44:47]
	v_mfma_f32_16x16x32_bf16 v[40:43], v[136:139], v[168:171], v[40:43]
	v_mfma_f32_16x16x32_bf16 v[28:31], v[128:131], v[196:199], v[28:31]
	v_mfma_f32_16x16x32_bf16 v[24:27], v[136:139], v[196:199], v[24:27]
	v_mfma_f32_16x16x32_bf16 v[12:15], v[128:131], v[208:211], v[12:15]
	v_mfma_f32_16x16x32_bf16 v[8:11], v[136:139], v[208:211], v[8:11]
	v_mfma_f32_16x16x32_bf16 v[60:63], v[132:135], v[164:167], v[60:63]
	v_mfma_f32_16x16x32_bf16 v[56:59], v[140:143], v[164:167], v[56:59]
	v_mfma_f32_16x16x32_bf16 v[44:47], v[132:135], v[172:175], v[44:47]
	v_mfma_f32_16x16x32_bf16 v[40:43], v[140:143], v[172:175], v[40:43]
	v_mfma_f32_16x16x32_bf16 v[28:31], v[132:135], v[204:207], v[28:31]
	v_mfma_f32_16x16x32_bf16 v[24:27], v[140:143], v[204:207], v[24:27]
	v_mfma_f32_16x16x32_bf16 v[12:15], v[132:135], v[220:223], v[12:15]
	v_mfma_f32_16x16x32_bf16 v[8:11], v[140:143], v[220:223], v[8:11]
	s_setprio 0
	s_setprio 1
	v_mfma_f32_16x16x32_bf16 v[52:55], v[144:147], v[160:163], v[52:55]
	v_mfma_f32_16x16x32_bf16 v[48:51], v[152:155], v[160:163], v[48:51]
	v_mfma_f32_16x16x32_bf16 v[36:39], v[144:147], v[168:171], v[36:39]
	v_mfma_f32_16x16x32_bf16 v[32:35], v[152:155], v[168:171], v[32:35]
	v_mfma_f32_16x16x32_bf16 v[20:23], v[144:147], v[196:199], v[20:23]
	v_mfma_f32_16x16x32_bf16 v[16:19], v[152:155], v[196:199], v[16:19]
	v_mfma_f32_16x16x32_bf16 v[4:7], v[144:147], v[208:211], v[4:7]
	v_mfma_f32_16x16x32_bf16 v[0:3], v[152:155], v[208:211], v[0:3]
	v_mfma_f32_16x16x32_bf16 v[52:55], v[148:151], v[164:167], v[52:55]
	v_mfma_f32_16x16x32_bf16 v[48:51], v[156:159], v[164:167], v[48:51]
	v_mfma_f32_16x16x32_bf16 v[36:39], v[148:151], v[172:175], v[36:39]
	v_mfma_f32_16x16x32_bf16 v[32:35], v[156:159], v[172:175], v[32:35]
	v_mfma_f32_16x16x32_bf16 v[20:23], v[148:151], v[204:207], v[20:23]
	v_mfma_f32_16x16x32_bf16 v[16:19], v[156:159], v[204:207], v[16:19]
	v_mfma_f32_16x16x32_bf16 v[4:7], v[148:151], v[220:223], v[4:7]
	v_mfma_f32_16x16x32_bf16 v[0:3], v[156:159], v[220:223], v[0:3]
	s_setprio 0
	s_barrier
	s_add_i32 s46, 0, 0x18000
	s_add_i32 s47, 0, 0x1c000
	v_add_u32_e32 v140, s46, v215
	v_add_u32_e32 v156, s47, v215
	ds_read_b128 v[128:131], v140
	ds_read_b128 v[132:135], v140 offset:1024
	ds_read_b128 v[136:139], v140 offset:2048
	ds_read_b128 v[140:143], v140 offset:3072
	ds_read_b128 v[144:147], v156
	ds_read_b128 v[148:151], v156 offset:1024
	ds_read_b128 v[152:155], v156 offset:2048
	ds_read_b128 v[156:159], v156 offset:3072
	s_add_u32 s18, s24, 0xb0000
	s_addc_u32 s19, s25, 0
	s_mov_b32 m0, s31
	v_lshl_add_u64 v[228:229], s[18:19], 0, v[176:177]
	ds_read_b128 v[160:163], v218 offset:32768
	ds_read_b128 v[164:167], v218 offset:33792
	ds_read_b128 v[168:171], v218 offset:34816
	ds_read_b128 v[172:175], v218 offset:35840
	ds_read_b128 v[196:199], v218 offset:36864
	ds_read_b128 v[204:207], v218 offset:37888
	ds_read_b128 v[208:211], v218 offset:38912
	ds_read_b128 v[220:223], v218 offset:39936
	global_load_lds_dwordx4 v[228:229], off
	v_lshl_add_u64 v[228:229], s[18:19], 0, v[180:181]
	s_mov_b32 m0, s33
	s_nop 0
	global_load_lds_dwordx4 v[228:229], off
	s_waitcnt vmcnt(8)
	s_waitcnt lgkmcnt(0)
	s_barrier
	s_setprio 1
	v_mfma_f32_16x16x32_bf16 v[124:127], v[128:131], v[160:163], v[124:127]
	v_mfma_f32_16x16x32_bf16 v[120:123], v[136:139], v[160:163], v[120:123]
	v_mfma_f32_16x16x32_bf16 v[108:111], v[128:131], v[168:171], v[108:111]
	v_mfma_f32_16x16x32_bf16 v[104:107], v[136:139], v[168:171], v[104:107]
	v_mfma_f32_16x16x32_bf16 v[92:95], v[128:131], v[196:199], v[92:95]
	v_mfma_f32_16x16x32_bf16 v[88:91], v[136:139], v[196:199], v[88:91]
	v_mfma_f32_16x16x32_bf16 v[76:79], v[128:131], v[208:211], v[76:79]
	v_mfma_f32_16x16x32_bf16 v[72:75], v[136:139], v[208:211], v[72:75]
	v_mfma_f32_16x16x32_bf16 v[124:127], v[132:135], v[164:167], v[124:127]
	v_mfma_f32_16x16x32_bf16 v[120:123], v[140:143], v[164:167], v[120:123]
	v_mfma_f32_16x16x32_bf16 v[108:111], v[132:135], v[172:175], v[108:111]
	v_mfma_f32_16x16x32_bf16 v[104:107], v[140:143], v[172:175], v[104:107]
	v_mfma_f32_16x16x32_bf16 v[92:95], v[132:135], v[204:207], v[92:95]
	v_mfma_f32_16x16x32_bf16 v[88:91], v[140:143], v[204:207], v[88:91]
	v_mfma_f32_16x16x32_bf16 v[76:79], v[132:135], v[220:223], v[76:79]
	v_mfma_f32_16x16x32_bf16 v[72:75], v[140:143], v[220:223], v[72:75]
	s_setprio 0
	s_setprio 1
	v_mfma_f32_16x16x32_bf16 v[116:119], v[144:147], v[160:163], v[116:119]
	v_mfma_f32_16x16x32_bf16 v[112:115], v[152:155], v[160:163], v[112:115]
	v_mfma_f32_16x16x32_bf16 v[100:103], v[144:147], v[168:171], v[100:103]
	v_mfma_f32_16x16x32_bf16 v[96:99], v[152:155], v[168:171], v[96:99]
	v_mfma_f32_16x16x32_bf16 v[84:87], v[144:147], v[196:199], v[84:87]
	v_mfma_f32_16x16x32_bf16 v[80:83], v[152:155], v[196:199], v[80:83]
	v_mfma_f32_16x16x32_bf16 v[68:71], v[144:147], v[208:211], v[68:71]
	v_mfma_f32_16x16x32_bf16 v[64:67], v[152:155], v[208:211], v[64:67]
	v_mfma_f32_16x16x32_bf16 v[116:119], v[148:151], v[164:167], v[116:119]
	v_mfma_f32_16x16x32_bf16 v[112:115], v[156:159], v[164:167], v[112:115]
	v_mfma_f32_16x16x32_bf16 v[100:103], v[148:151], v[172:175], v[100:103]
	v_mfma_f32_16x16x32_bf16 v[96:99], v[156:159], v[172:175], v[96:99]
	v_mfma_f32_16x16x32_bf16 v[84:87], v[148:151], v[204:207], v[84:87]
	v_mfma_f32_16x16x32_bf16 v[80:83], v[156:159], v[204:207], v[80:83]
	v_mfma_f32_16x16x32_bf16 v[68:71], v[148:151], v[220:223], v[68:71]
	v_mfma_f32_16x16x32_bf16 v[64:67], v[156:159], v[220:223], v[64:67]
	s_setprio 0
	s_barrier
; #define PG8_STAGE(bufoff, gbase, voff) do { _Pragma("unroll") for (int _i = 0; _i < 2; ++_i) \
;         __builtin_amdgcn_global_load_lds((const unsigned*)((const char*)(gbase) + (voff)[_i]), (PG8_LAS unsigned*)(lds + (bufoff) + ldsw + _i * 8192), 16, 0, 0); } while (0)
; #define PG8_LDA(dst, b, h) do { _Pragma("unroll") for (int m = 0; m < 4; ++m) _Pragma("unroll") for (int k = 0; k < 2; ++k) dst[m][k] = *(const PG8_LAS bf16x8*)(lds + PG8_SA(b, h) + aoff + m * 2048 + k * 1024); } while (0)
; #define PG8_MMA(ai, bj, At, Bt) do { __builtin_amdgcn_s_setprio(1); _Pragma("unroll") for (int m = 0; m < 4; ++m) _Pragma("unroll") for (int n = 0; n < 2; ++n) _Pragma("unroll") for (int k = 0; k < 2; ++k) \
;         acc[ai][bj][m][n] = __builtin_amdgcn_mfma_f32_16x16x32_bf16(Bt[n][k], At[m][k], acc[ai][bj][m][n], 0, 0, 0); __builtin_amdgcn_s_setprio(0); } while (0)
; #define PG8_WAIT_V(n) asm volatile("s_waitcnt vmcnt(" #n ")" ::: "memory")
; #define PG8_WAIT_L(n) asm volatile("s_waitcnt lgkmcnt(" #n ")" ::: "memory")
; #define PG8_BAR __builtin_amdgcn_s_barrier()
; #define PG8_SCHED __builtin_amdgcn_sched_barrier(0)
; template <class Epi, class Sched, bool ALIGN_EPI = false, bool SP2 = false>
; __device__ __forceinline__ void gemm_phase(PG8_LAS unsigned char* lds, const Gemm g, const Sched& S, const Epi& E) {
;     ...
;             PG8_LDA(At, 1, 1); PG8_STAGE(PG8_SB(1, 0), b3, voffB); PG8_STAGE(PG8_SB(1, 1), b3 + hstep, voffB); PG8_STAGE(PG8_SA(1, 0), a3, voffA);
;             PG8_WAIT_V(8); PG8_WAIT_L(0); PG8_BAR; PG8_MMA(1, 0, At, B0); PG8_MMA(1, 1, At, B1); PG8_BAR; PG8_SCHED;
;     ...
;         if constexpr (ALIGN_EPI) { if (wr == 0) PG8_BAR; }
	s_add_i32 s18, s46, s28
	v_lshl_add_u64 v[200:201], v[200:201], 0, s[12:13]
	s_mov_b32 m0, s18
	ds_read_b128 v[160:163], v218 offset:49152
	ds_read_b128 v[164:167], v218 offset:50176
	ds_read_b128 v[168:171], v218 offset:51200
	ds_read_b128 v[172:175], v218 offset:52224
	ds_read_b128 v[196:199], v218 offset:53248
	ds_read_b128 v[204:207], v218 offset:54272
	ds_read_b128 v[208:211], v218 offset:55296
	ds_read_b128 v[220:223], v218 offset:56320
	global_load_lds_dwordx4 v[200:201], off
	s_add_i32 m0, s18, 0x2000
	s_add_u32 s18, s22, 0xb0080
	v_lshl_add_u64 v[200:201], v[212:213], 0, s[12:13]
	s_addc_u32 s19, s23, 0
	s_add_i32 s22, s47, s28
	global_load_lds_dwordx4 v[200:201], off
	v_lshl_add_u64 v[200:201], s[18:19], 0, v[178:179]
	s_mov_b32 m0, s22
	s_nop 0
	global_load_lds_dwordx4 v[200:201], off
	v_lshl_add_u64 v[200:201], s[18:19], 0, v[182:183]
	s_add_i32 m0, s22, 0x2000
	s_nop 0
	global_load_lds_dwordx4 v[200:201], off
	v_lshl_add_u64 v[200:201], v[224:225], 0, s[12:13]
	s_mov_b32 m0, s35
	s_nop 0
	global_load_lds_dwordx4 v[200:201], off
	v_lshl_add_u64 v[200:201], v[226:227], 0, s[12:13]
	s_mov_b32 m0, s36
	s_nop 0
	global_load_lds_dwordx4 v[200:201], off
	s_waitcnt vmcnt(8)
	s_waitcnt lgkmcnt(0)
	s_barrier
	s_setprio 1
	v_mfma_f32_16x16x32_bf16 v[60:63], v[128:131], v[160:163], v[60:63]
	v_mfma_f32_16x16x32_bf16 v[56:59], v[136:139], v[160:163], v[56:59]
	v_mfma_f32_16x16x32_bf16 v[44:47], v[128:131], v[168:171], v[44:47]
	v_mfma_f32_16x16x32_bf16 v[40:43], v[136:139], v[168:171], v[40:43]
	v_mfma_f32_16x16x32_bf16 v[28:31], v[128:131], v[196:199], v[28:31]
	v_mfma_f32_16x16x32_bf16 v[24:27], v[136:139], v[196:199], v[24:27]
	v_mfma_f32_16x16x32_bf16 v[12:15], v[128:131], v[208:211], v[12:15]
	v_mfma_f32_16x16x32_bf16 v[8:11], v[136:139], v[208:211], v[8:11]
	v_mfma_f32_16x16x32_bf16 v[60:63], v[132:135], v[164:167], v[60:63]
	v_mfma_f32_16x16x32_bf16 v[56:59], v[140:143], v[164:167], v[56:59]
	v_mfma_f32_16x16x32_bf16 v[44:47], v[132:135], v[172:175], v[44:47]
	v_mfma_f32_16x16x32_bf16 v[40:43], v[140:143], v[172:175], v[40:43]
	v_mfma_f32_16x16x32_bf16 v[28:31], v[132:135], v[204:207], v[28:31]
	v_mfma_f32_16x16x32_bf16 v[24:27], v[140:143], v[204:207], v[24:27]
	v_mfma_f32_16x16x32_bf16 v[12:15], v[132:135], v[220:223], v[12:15]
	v_mfma_f32_16x16x32_bf16 v[8:11], v[140:143], v[220:223], v[8:11]
	s_setprio 0
	s_setprio 1
	v_mfma_f32_16x16x32_bf16 v[52:55], v[144:147], v[160:163], v[52:55]
	v_mfma_f32_16x16x32_bf16 v[48:51], v[152:155], v[160:163], v[48:51]
	v_mfma_f32_16x16x32_bf16 v[36:39], v[144:147], v[168:171], v[36:39]
	v_mfma_f32_16x16x32_bf16 v[32:35], v[152:155], v[168:171], v[32:35]
	v_mfma_f32_16x16x32_bf16 v[20:23], v[144:147], v[196:199], v[20:23]
	v_mfma_f32_16x16x32_bf16 v[16:19], v[152:155], v[196:199], v[16:19]
	v_mfma_f32_16x16x32_bf16 v[4:7], v[144:147], v[208:211], v[4:7]
	v_mfma_f32_16x16x32_bf16 v[0:3], v[152:155], v[208:211], v[0:3]
	v_mfma_f32_16x16x32_bf16 v[52:55], v[148:151], v[164:167], v[52:55]
	v_mfma_f32_16x16x32_bf16 v[48:51], v[156:159], v[164:167], v[48:51]
	v_mfma_f32_16x16x32_bf16 v[36:39], v[148:151], v[172:175], v[36:39]
	v_mfma_f32_16x16x32_bf16 v[32:35], v[156:159], v[172:175], v[32:35]
	v_mfma_f32_16x16x32_bf16 v[20:23], v[148:151], v[204:207], v[20:23]
	v_mfma_f32_16x16x32_bf16 v[16:19], v[156:159], v[204:207], v[16:19]
	v_mfma_f32_16x16x32_bf16 v[4:7], v[148:151], v[220:223], v[4:7]
	v_mfma_f32_16x16x32_bf16 v[0:3], v[156:159], v[220:223], v[0:3]
	s_setprio 0
	s_barrier
	s_add_i32 s45, s45, 2
	s_add_u32 s43, s43, 0x100
	s_addc_u32 s44, s44, 0
	s_cmp_gt_u32 s45, 41
	s_mov_b64 s[18:19], s[20:21]
	s_cbranch_scc0 .LBB0_1248
	s_and_b64 vcc, exec, s[14:15]
	s_cbranch_vccz .LBB0_1251
	s_barrier
